# early L1 invalidate + write-through (sc1) epilogue stores in the four residual-output phases
# speedup vs baseline: 1.0056x; 1.0041x over previous
; #define PG8_STAGE(bufoff, gbase, voff) do { _Pragma("unroll") for (int _i = 0; _i < 2; ++_i) \
;         __builtin_amdgcn_global_load_lds((const unsigned*)((const char*)(gbase) + (voff)[_i]), (LAS unsigned*)(lds + (bufoff) + ldsw + _i * 8192), 16, 0, 0); } while (0)
; #define PG8_LDA(dst, b, h) do { _Pragma("unroll") for (int m = 0; m < 4; ++m) _Pragma("unroll") for (int k = 0; k < 2; ++k) dst[m][k] = *(const LAS bf16x8*)(lds + PG8_SA(b, h) + aoff + m * 2048 + k * 1024); } while (0)
; #define PG8_LDB(dst, b, h) do { _Pragma("unroll") for (int n = 0; n < 2; ++n) _Pragma("unroll") for (int k = 0; k < 2; ++k) dst[n][k] = *(const LAS bf16x8*)(lds + PG8_SB(b, h) + boff + n * 2048 + k * 1024); } while (0)
; #define PG8_MMA(ai, bj, At, Bt) do { __builtin_amdgcn_s_setprio(1); _Pragma("unroll") for (int m = 0; m < 4; ++m) _Pragma("unroll") for (int n = 0; n < 2; ++n) _Pragma("unroll") for (int k = 0; k < 2; ++k) \
;         acc[ai][bj][m][n] = __builtin_amdgcn_mfma_f32_16x16x32_bf16(Bt[n][k], At[m][k], acc[ai][bj][m][n], 0, 0, 0); __builtin_amdgcn_s_setprio(0); } while (0)
; #define PG8_WAIT_V(n) asm volatile("s_waitcnt vmcnt(" #n ")" ::: "memory")
; #define PG8_WAIT_L(n) asm volatile("s_waitcnt lgkmcnt(" #n ")" ::: "memory")
; #define PG8_BAR __builtin_amdgcn_s_barrier()
; #define PG8_SCHED __builtin_amdgcn_sched_barrier(0)
; template <class Epi>
; DI void gemm_phase(LAS unsigned char* lds, int wid, int K, int lda, int ldb, bool bperm, const Sched3& S, const Epi& E) {
;     ...
;             PG8_LDB(B0, 0, 0); PG8_SCHED; PG8_LDA(At, 0, 0); PG8_STAGE(PG8_SA(1, 1), a1 + hA, voffA);
;             PG8_WAIT_L(8); PG8_BAR; PG8_WAIT_L(0); PG8_MMA(0, 0, At, B0); PG8_BAR; PG8_SCHED;
;             PG8_LDB(B1, 0, 1); PG8_STAGE(PG8_SB(0, 0), b2, voffB);
;             PG8_BAR; PG8_WAIT_L(0); PG8_MMA(0, 1, At, B1); PG8_BAR;
;             PG8_LDA(At, 0, 1); PG8_STAGE(PG8_SA(0, 0), a2, voffA);
;             PG8_BAR; PG8_WAIT_L(0); if (full) PG8_MMA(1, 0, At, B0); PG8_BAR; PG8_SCHED;
;             PG8_STAGE(PG8_SB(0, 1), b2 + hstepB, voffB);
;             PG8_WAIT_V(6); PG8_BAR; if (full) PG8_MMA(1, 1, At, B1); PG8_BAR;
.LBB0_621:
	ds_read_b128 v[128:131], v203
	ds_read_b128 v[132:135], v203 offset:1024
	ds_read_b128 v[136:139], v203 offset:2048
	ds_read_b128 v[140:143], v203 offset:3072
	s_add_u32 s40, s38, 0xfff80080
	s_addc_u32 s41, s39, -1
	s_cmp_eq_u32 s29, 28
	s_cselect_b32 s43, s31, s41
	s_cselect_b32 s42, s30, s40
	s_cselect_b32 s41, s37, s23
	s_cselect_b32 s40, s36, s21
	v_lshl_add_u64 v[186:187], s[38:39], 0, v[180:181]
	s_add_i32 m0, s50, 0xc000
	ds_read_b128 v[144:147], v204
	ds_read_b128 v[148:151], v204 offset:1024
	ds_read_b128 v[152:155], v204 offset:2048
	ds_read_b128 v[156:159], v204 offset:3072
	ds_read_b128 v[160:163], v204 offset:4096
	ds_read_b128 v[164:167], v204 offset:5120
	ds_read_b128 v[168:171], v204 offset:6144
	ds_read_b128 v[172:175], v204 offset:7168
	global_load_lds_dwordx4 v[186:187], off
	v_lshl_add_u64 v[186:187], s[38:39], 0, v[182:183]
	s_add_i32 m0, s50, 0xe000
	s_nop 0
	global_load_lds_dwordx4 v[186:187], off
	s_waitcnt lgkmcnt(8)
	s_barrier
	s_waitcnt lgkmcnt(0)
	s_setprio 1
	s_waitcnt lgkmcnt(0)
	v_mfma_f32_16x16x32_bf16 v[124:127], v[128:131], v[144:147], v[124:127]
	v_mfma_f32_16x16x32_bf16 v[120:123], v[136:139], v[144:147], v[120:123]
	v_mfma_f32_16x16x32_bf16 v[108:111], v[128:131], v[152:155], v[108:111]
	v_mfma_f32_16x16x32_bf16 v[104:107], v[136:139], v[152:155], v[104:107]
	v_mfma_f32_16x16x32_bf16 v[92:95], v[128:131], v[160:163], v[92:95]
	v_mfma_f32_16x16x32_bf16 v[88:91], v[136:139], v[160:163], v[88:91]
	v_mfma_f32_16x16x32_bf16 v[76:79], v[128:131], v[168:171], v[76:79]
	v_mfma_f32_16x16x32_bf16 v[72:75], v[136:139], v[168:171], v[72:75]
	v_mfma_f32_16x16x32_bf16 v[124:127], v[132:135], v[148:151], v[124:127]
	v_mfma_f32_16x16x32_bf16 v[120:123], v[140:143], v[148:151], v[120:123]
	v_mfma_f32_16x16x32_bf16 v[108:111], v[132:135], v[156:159], v[108:111]
	v_mfma_f32_16x16x32_bf16 v[104:107], v[140:143], v[156:159], v[104:107]
	v_mfma_f32_16x16x32_bf16 v[92:95], v[132:135], v[164:167], v[92:95]
	v_mfma_f32_16x16x32_bf16 v[88:91], v[140:143], v[164:167], v[88:91]
	v_mfma_f32_16x16x32_bf16 v[76:79], v[132:135], v[172:175], v[76:79]
	v_mfma_f32_16x16x32_bf16 v[72:75], v[140:143], v[172:175], v[72:75]
	s_setprio 0
	s_barrier
	s_add_i32 s63, s59, s49
	v_lshl_add_u64 v[210:211], s[40:41], 0, v[176:177]
	s_mov_b32 m0, s63
	ds_read_b128 v[186:189], v205
	ds_read_b128 v[190:193], v205 offset:1024
	ds_read_b128 v[194:197], v205 offset:2048
	ds_read_b128 v[206:209], v205 offset:3072
	global_load_lds_dwordx4 v[210:211], off
	v_lshl_add_u64 v[212:213], s[40:41], 0, v[178:179]
	s_add_i32 m0, s63, 0x2000
	s_nop 0
	global_load_lds_dwordx4 v[212:213], off
	s_barrier
	s_waitcnt lgkmcnt(0)
	s_setprio 1
	s_waitcnt lgkmcnt(0)
	v_mfma_f32_16x16x32_bf16 v[116:119], v[186:189], v[144:147], v[116:119]
	v_mfma_f32_16x16x32_bf16 v[112:115], v[194:197], v[144:147], v[112:115]
	v_mfma_f32_16x16x32_bf16 v[100:103], v[186:189], v[152:155], v[100:103]
	v_mfma_f32_16x16x32_bf16 v[96:99], v[194:197], v[152:155], v[96:99]
	v_mfma_f32_16x16x32_bf16 v[84:87], v[186:189], v[160:163], v[84:87]
	v_mfma_f32_16x16x32_bf16 v[80:83], v[194:197], v[160:163], v[80:83]
	v_mfma_f32_16x16x32_bf16 v[68:71], v[186:189], v[168:171], v[68:71]
	v_mfma_f32_16x16x32_bf16 v[64:67], v[194:197], v[168:171], v[64:67]
	v_mfma_f32_16x16x32_bf16 v[116:119], v[190:193], v[148:151], v[116:119]
	v_mfma_f32_16x16x32_bf16 v[112:115], v[206:209], v[148:151], v[112:115]
	v_mfma_f32_16x16x32_bf16 v[100:103], v[190:193], v[156:159], v[100:103]
	v_mfma_f32_16x16x32_bf16 v[96:99], v[206:209], v[156:159], v[96:99]
	v_mfma_f32_16x16x32_bf16 v[84:87], v[190:193], v[164:167], v[84:87]
	v_mfma_f32_16x16x32_bf16 v[80:83], v[206:209], v[164:167], v[80:83]
	v_mfma_f32_16x16x32_bf16 v[68:71], v[190:193], v[172:175], v[68:71]
	v_mfma_f32_16x16x32_bf16 v[64:67], v[206:209], v[172:175], v[64:67]
	s_setprio 0
	s_mov_b32 m0, s50
	v_lshl_add_u64 v[214:215], s[42:43], 0, v[176:177]
	s_barrier
	ds_read_b128 v[144:147], v204 offset:16384
	ds_read_b128 v[148:151], v204 offset:17408
	ds_read_b128 v[152:155], v204 offset:18432
	ds_read_b128 v[156:159], v204 offset:19456
	ds_read_b128 v[160:163], v204 offset:20480
	ds_read_b128 v[164:167], v204 offset:21504
	ds_read_b128 v[168:171], v204 offset:22528
	ds_read_b128 v[172:175], v204 offset:23552
	global_load_lds_dwordx4 v[214:215], off
	v_lshl_add_u64 v[216:217], s[42:43], 0, v[178:179]
	s_mov_b32 m0, s51
	s_nop 0
	global_load_lds_dwordx4 v[216:217], off
	s_barrier
	s_waitcnt lgkmcnt(0)
	s_setprio 1
	s_waitcnt lgkmcnt(0)
	v_mfma_f32_16x16x32_bf16 v[60:63], v[128:131], v[144:147], v[60:63]
	v_mfma_f32_16x16x32_bf16 v[56:59], v[136:139], v[144:147], v[56:59]
	v_mfma_f32_16x16x32_bf16 v[44:47], v[128:131], v[152:155], v[44:47]
	v_mfma_f32_16x16x32_bf16 v[40:43], v[136:139], v[152:155], v[40:43]
	v_mfma_f32_16x16x32_bf16 v[28:31], v[128:131], v[160:163], v[28:31]
	v_mfma_f32_16x16x32_bf16 v[24:27], v[136:139], v[160:163], v[24:27]
	v_mfma_f32_16x16x32_bf16 v[12:15], v[128:131], v[168:171], v[12:15]
	v_mfma_f32_16x16x32_bf16 v[8:11], v[136:139], v[168:171], v[8:11]
	v_mfma_f32_16x16x32_bf16 v[60:63], v[132:135], v[148:151], v[60:63]
	v_mfma_f32_16x16x32_bf16 v[56:59], v[140:143], v[148:151], v[56:59]
	v_mfma_f32_16x16x32_bf16 v[44:47], v[132:135], v[156:159], v[44:47]
	v_mfma_f32_16x16x32_bf16 v[40:43], v[140:143], v[156:159], v[40:43]
	v_mfma_f32_16x16x32_bf16 v[28:31], v[132:135], v[164:167], v[28:31]
	v_mfma_f32_16x16x32_bf16 v[24:27], v[140:143], v[164:167], v[24:27]
	v_mfma_f32_16x16x32_bf16 v[12:15], v[132:135], v[172:175], v[12:15]
	v_mfma_f32_16x16x32_bf16 v[8:11], v[140:143], v[172:175], v[8:11]
	s_setprio 0
	s_barrier
; #define PG8_STAGE(bufoff, gbase, voff) do { _Pragma("unroll") for (int _i = 0; _i < 2; ++_i) \
;         __builtin_amdgcn_global_load_lds((const unsigned*)((const char*)(gbase) + (voff)[_i]), (LAS unsigned*)(lds + (bufoff) + ldsw + _i * 8192), 16, 0, 0); } while (0)
; #define PG8_LDA(dst, b, h) do { _Pragma("unroll") for (int m = 0; m < 4; ++m) _Pragma("unroll") for (int k = 0; k < 2; ++k) dst[m][k] = *(const LAS bf16x8*)(lds + PG8_SA(b, h) + aoff + m * 2048 + k * 1024); } while (0)
; #define PG8_LDB(dst, b, h) do { _Pragma("unroll") for (int n = 0; n < 2; ++n) _Pragma("unroll") for (int k = 0; k < 2; ++k) dst[n][k] = *(const LAS bf16x8*)(lds + PG8_SB(b, h) + boff + n * 2048 + k * 1024); } while (0)
; #define PG8_MMA(ai, bj, At, Bt) do { __builtin_amdgcn_s_setprio(1); _Pragma("unroll") for (int m = 0; m < 4; ++m) _Pragma("unroll") for (int n = 0; n < 2; ++n) _Pragma("unroll") for (int k = 0; k < 2; ++k) \
;         acc[ai][bj][m][n] = __builtin_amdgcn_mfma_f32_16x16x32_bf16(Bt[n][k], At[m][k], acc[ai][bj][m][n], 0, 0, 0); __builtin_amdgcn_s_setprio(0); } while (0)
; #define PG8_WAIT_V(n) asm volatile("s_waitcnt vmcnt(" #n ")" ::: "memory")
; #define PG8_WAIT_L(n) asm volatile("s_waitcnt lgkmcnt(" #n ")" ::: "memory")
; #define PG8_BAR __builtin_amdgcn_s_barrier()
; #define PG8_SCHED __builtin_amdgcn_sched_barrier(0)
; template <class Epi>
; DI void gemm_phase(LAS unsigned char* lds, int wid, int K, int lda, int ldb, bool bperm, const Sched3& S, const Epi& E) {
;     ...
;             PG8_STAGE(PG8_SB(0, 1), b2 + hstepB, voffB);
;             PG8_WAIT_V(6); PG8_BAR; if (full) PG8_MMA(1, 1, At, B1); PG8_BAR;
;             PG8_LDB(B0, 1, 0); PG8_SCHED; PG8_LDA(At, 1, 0); PG8_STAGE(PG8_SA(0, 1), a2 + h2, voffA);
;             PG8_WAIT_L(8); PG8_BAR; PG8_WAIT_L(0); PG8_MMA(0, 0, At, B0); PG8_BAR; PG8_SCHED;
;             PG8_LDB(B1, 1, 1); PG8_STAGE(PG8_SB(1, 0), b3, voffB);
;             PG8_BAR; PG8_WAIT_L(0); PG8_MMA(0, 1, At, B1); PG8_BAR;
;             PG8_LDA(At, 1, 1); PG8_STAGE(PG8_SA(1, 0), a3, voffA);
;             PG8_BAR; PG8_WAIT_L(0); if (full) PG8_MMA(1, 0, At, B0); PG8_BAR; PG8_SCHED;
	s_add_u32 s64, s40, 0x80000
	s_addc_u32 s65, s41, 0
	s_add_i32 s63, s60, s49
	v_lshl_add_u64 v[128:129], s[64:65], 0, v[176:177]
	s_mov_b32 m0, s63
	s_nop 0
	global_load_lds_dwordx4 v[128:129], off
	v_lshl_add_u64 v[128:129], s[64:65], 0, v[178:179]
	s_add_i32 m0, s63, 0x2000
	s_nop 0
	global_load_lds_dwordx4 v[128:129], off
	s_waitcnt vmcnt(6)
	s_barrier
	s_setprio 1
	v_mfma_f32_16x16x32_bf16 v[52:55], v[186:189], v[144:147], v[52:55]
	v_mfma_f32_16x16x32_bf16 v[48:51], v[194:197], v[144:147], v[48:51]
	v_mfma_f32_16x16x32_bf16 v[36:39], v[186:189], v[152:155], v[36:39]
	v_mfma_f32_16x16x32_bf16 v[32:35], v[194:197], v[152:155], v[32:35]
	v_mfma_f32_16x16x32_bf16 v[20:23], v[186:189], v[160:163], v[20:23]
	v_mfma_f32_16x16x32_bf16 v[16:19], v[194:197], v[160:163], v[16:19]
	v_mfma_f32_16x16x32_bf16 v[4:7], v[186:189], v[168:171], v[4:7]
	v_mfma_f32_16x16x32_bf16 v[0:3], v[194:197], v[168:171], v[0:3]
	v_mfma_f32_16x16x32_bf16 v[52:55], v[190:193], v[148:151], v[52:55]
	v_mfma_f32_16x16x32_bf16 v[48:51], v[206:209], v[148:151], v[48:51]
	v_mfma_f32_16x16x32_bf16 v[36:39], v[190:193], v[156:159], v[36:39]
	v_mfma_f32_16x16x32_bf16 v[32:35], v[206:209], v[156:159], v[32:35]
	v_mfma_f32_16x16x32_bf16 v[20:23], v[190:193], v[164:167], v[20:23]
	v_mfma_f32_16x16x32_bf16 v[16:19], v[206:209], v[164:167], v[16:19]
	v_mfma_f32_16x16x32_bf16 v[4:7], v[190:193], v[172:175], v[4:7]
	v_mfma_f32_16x16x32_bf16 v[0:3], v[206:209], v[172:175], v[0:3]
	s_setprio 0
	s_add_i32 s63, 0, 0x18000
	v_add_u32_e32 v140, s63, v199
	s_barrier
	ds_read_b128 v[128:131], v140
	ds_read_b128 v[132:135], v140 offset:1024
	ds_read_b128 v[136:139], v140 offset:2048
	ds_read_b128 v[140:143], v140 offset:3072
	s_add_u32 s42, s42, 0x80000
	s_addc_u32 s43, s43, 0
	s_mov_b32 m0, s52
	v_lshl_add_u64 v[186:187], s[42:43], 0, v[176:177]
	ds_read_b128 v[144:147], v204 offset:32768
	ds_read_b128 v[148:151], v204 offset:33792
	ds_read_b128 v[152:155], v204 offset:34816
	ds_read_b128 v[156:159], v204 offset:35840
	ds_read_b128 v[160:163], v204 offset:36864
	ds_read_b128 v[164:167], v204 offset:37888
	ds_read_b128 v[168:171], v204 offset:38912
	ds_read_b128 v[172:175], v204 offset:39936
	global_load_lds_dwordx4 v[186:187], off
	v_lshl_add_u64 v[186:187], s[42:43], 0, v[178:179]
	s_mov_b32 m0, s53
	s_nop 0
	global_load_lds_dwordx4 v[186:187], off
	s_waitcnt lgkmcnt(8)
	s_barrier
	s_waitcnt lgkmcnt(0)
	s_setprio 1
	s_waitcnt lgkmcnt(0)
	v_mfma_f32_16x16x32_bf16 v[124:127], v[128:131], v[144:147], v[124:127]
	v_mfma_f32_16x16x32_bf16 v[120:123], v[136:139], v[144:147], v[120:123]
	v_mfma_f32_16x16x32_bf16 v[108:111], v[128:131], v[152:155], v[108:111]
	v_mfma_f32_16x16x32_bf16 v[104:107], v[136:139], v[152:155], v[104:107]
	v_mfma_f32_16x16x32_bf16 v[92:95], v[128:131], v[160:163], v[92:95]
	v_mfma_f32_16x16x32_bf16 v[88:91], v[136:139], v[160:163], v[88:91]
	v_mfma_f32_16x16x32_bf16 v[76:79], v[128:131], v[168:171], v[76:79]
	v_mfma_f32_16x16x32_bf16 v[72:75], v[136:139], v[168:171], v[72:75]
	v_mfma_f32_16x16x32_bf16 v[124:127], v[132:135], v[148:151], v[124:127]
	v_mfma_f32_16x16x32_bf16 v[120:123], v[140:143], v[148:151], v[120:123]
	v_mfma_f32_16x16x32_bf16 v[108:111], v[132:135], v[156:159], v[108:111]
	v_mfma_f32_16x16x32_bf16 v[104:107], v[140:143], v[156:159], v[104:107]
	v_mfma_f32_16x16x32_bf16 v[92:95], v[132:135], v[164:167], v[92:95]
	v_mfma_f32_16x16x32_bf16 v[88:91], v[140:143], v[164:167], v[88:91]
	v_mfma_f32_16x16x32_bf16 v[76:79], v[132:135], v[172:175], v[76:79]
	v_mfma_f32_16x16x32_bf16 v[72:75], v[140:143], v[172:175], v[72:75]
	s_setprio 0
	s_barrier
	s_add_i32 s42, 0, 0x1c000
	s_add_i32 s43, s63, s49
	v_add_u32_e32 v206, s42, v199
	v_lshl_add_u64 v[210:211], v[210:211], 0, s[12:13]
	s_mov_b32 m0, s43
	ds_read_b128 v[186:189], v206
	ds_read_b128 v[190:193], v206 offset:1024
	ds_read_b128 v[194:197], v206 offset:2048
	ds_read_b128 v[206:209], v206 offset:3072
	global_load_lds_dwordx4 v[210:211], off
	v_lshl_add_u64 v[210:211], v[212:213], 0, s[12:13]
	s_add_i32 m0, s43, 0x2000
	s_nop 0
	global_load_lds_dwordx4 v[210:211], off
	s_barrier
	s_waitcnt lgkmcnt(0)
	s_setprio 1
	s_waitcnt lgkmcnt(0)
	v_mfma_f32_16x16x32_bf16 v[116:119], v[186:189], v[144:147], v[116:119]
	v_mfma_f32_16x16x32_bf16 v[112:115], v[194:197], v[144:147], v[112:115]
	v_mfma_f32_16x16x32_bf16 v[100:103], v[186:189], v[152:155], v[100:103]
	v_mfma_f32_16x16x32_bf16 v[96:99], v[194:197], v[152:155], v[96:99]
	v_mfma_f32_16x16x32_bf16 v[84:87], v[186:189], v[160:163], v[84:87]
	v_mfma_f32_16x16x32_bf16 v[80:83], v[194:197], v[160:163], v[80:83]
	v_mfma_f32_16x16x32_bf16 v[68:71], v[186:189], v[168:171], v[68:71]
	v_mfma_f32_16x16x32_bf16 v[64:67], v[194:197], v[168:171], v[64:67]
	v_mfma_f32_16x16x32_bf16 v[116:119], v[190:193], v[148:151], v[116:119]
	v_mfma_f32_16x16x32_bf16 v[112:115], v[206:209], v[148:151], v[112:115]
	v_mfma_f32_16x16x32_bf16 v[100:103], v[190:193], v[156:159], v[100:103]
	v_mfma_f32_16x16x32_bf16 v[96:99], v[206:209], v[156:159], v[96:99]
	v_mfma_f32_16x16x32_bf16 v[84:87], v[190:193], v[164:167], v[84:87]
	v_mfma_f32_16x16x32_bf16 v[80:83], v[206:209], v[164:167], v[80:83]
	v_mfma_f32_16x16x32_bf16 v[68:71], v[190:193], v[172:175], v[68:71]
	v_mfma_f32_16x16x32_bf16 v[64:67], v[206:209], v[172:175], v[64:67]
	s_setprio 0
	s_mov_b32 m0, s55
	v_lshl_add_u64 v[210:211], v[214:215], 0, s[12:13]
	s_barrier
	ds_read_b128 v[144:147], v204 offset:49152
	ds_read_b128 v[148:151], v204 offset:50176
	ds_read_b128 v[152:155], v204 offset:51200
	ds_read_b128 v[156:159], v204 offset:52224
	ds_read_b128 v[160:163], v204 offset:53248
	ds_read_b128 v[164:167], v204 offset:54272
	ds_read_b128 v[168:171], v204 offset:55296
	ds_read_b128 v[172:175], v204 offset:56320
	global_load_lds_dwordx4 v[210:211], off
	v_lshl_add_u64 v[210:211], v[216:217], 0, s[12:13]
	s_mov_b32 m0, s56
	s_nop 0
	global_load_lds_dwordx4 v[210:211], off
	s_barrier
; DI u32x2 pk4(f32x4 v) { u32x2 r; r.x = pk2(v[0], v[1]); r.y = pk2(v[2], v[3]); return r; }
; DI float bf_lo(unsigned w) { return __uint_as_float(w << 16); }
; DI float bf_hi(unsigned w) { return __uint_as_float(w & 0xffff0000u); }
; #define PG8_STAGE(bufoff, gbase, voff) do { _Pragma("unroll") for (int _i = 0; _i < 2; ++_i) \
;         __builtin_amdgcn_global_load_lds((const unsigned*)((const char*)(gbase) + (voff)[_i]), (LAS unsigned*)(lds + (bufoff) + ldsw + _i * 8192), 16, 0, 0); } while (0)
; template <class Epi>
; DI void gemm_phase(LAS unsigned char* lds, int wid, int K, int lda, int ldb, bool bperm, const Sched3& S, const Epi& E) {
;     ...
;             PG8_BAR; PG8_WAIT_L(0); if (full) PG8_MMA(1, 0, At, B0); PG8_BAR; PG8_SCHED;
;             PG8_STAGE(PG8_SB(1, 1), b3 + hstepB, voffB);
;             PG8_WAIT_V(6); PG8_BAR; if (full) PG8_MMA(1, 1, At, B1); PG8_BAR;
;         }
;     DI void operator()(const Acc& acc, const Unit& u, int wr, int wc, int fr, int fq) const {
;     ...
;                 for (int m = 0; m < 4; ++m) { const size_t o = (size_t)(row0 + ai * HALF + m * 16) * 2048 + colp;
;                     if (PH == 4) { COLS4 xo[m][bj][n] = *(const f32x4*)(p.x + o + bj * HALF + n * 4); }
;                     else {
; #pragma unroll
;                         for (int bj = 0; bj < 2; ++bj) { const u32x4 w = *(const u32x4*)(WSB(OFF_XB) + o + bj * HALF);
;                             xo[m][bj][0] = (f32x4){bf_lo(w.x), bf_hi(w.x), bf_lo(w.y), bf_hi(w.y)}; xo[m][bj][1] = (f32x4){bf_lo(w.z), bf_hi(w.z), bf_lo(w.w), bf_hi(w.w)}; } } }
; #pragma unroll
;                 for (int m = 0; m < 4; ++m) { const int r = row0 + ai * HALF + m * 16; const size_t o = (size_t)r * 2048 + colp; float part = 0.f;
; #pragma unroll
;                     for (int bj = 0; bj < 2; ++bj) { const f32x4 x0 = xo[m][bj][0] + acc[ai][bj][m][0], x1 = xo[m][bj][1] + acc[ai][bj][m][1];
;                         const u32x2 h0 = pk4(x0), h1 = pk4(x1);
;                         *(u32x4*)(WSB(OFF_XB) + o + bj * HALF) = (u32x4){h0.x, h0.y, h1.x, h1.y};
;                         part += x0[0] * x0[0] + x0[1] * x0[1] + x0[2] * x0[2] + x0[3] * x0[3] + x1[0] * x1[0] + x1[1] * x1[1] + x1[2] * x1[2] + x1[3] * x1[3]; }
;                     part += __shfl_xor(part, 16); part += __shfl_xor(part, 32);
;                     if (fq == 0) unsafeAtomicAdd(ssq + r, part);
	s_waitcnt lgkmcnt(0)
	s_setprio 1
	s_waitcnt lgkmcnt(0)
	v_mfma_f32_16x16x32_bf16 v[60:63], v[128:131], v[144:147], v[60:63]
	v_mfma_f32_16x16x32_bf16 v[56:59], v[136:139], v[144:147], v[56:59]
	v_mfma_f32_16x16x32_bf16 v[44:47], v[128:131], v[152:155], v[44:47]
	v_mfma_f32_16x16x32_bf16 v[40:43], v[136:139], v[152:155], v[40:43]
	v_mfma_f32_16x16x32_bf16 v[28:31], v[128:131], v[160:163], v[28:31]
	v_mfma_f32_16x16x32_bf16 v[24:27], v[136:139], v[160:163], v[24:27]
	v_mfma_f32_16x16x32_bf16 v[12:15], v[128:131], v[168:171], v[12:15]
	v_mfma_f32_16x16x32_bf16 v[8:11], v[136:139], v[168:171], v[8:11]
	v_mfma_f32_16x16x32_bf16 v[60:63], v[132:135], v[148:151], v[60:63]
	v_mfma_f32_16x16x32_bf16 v[56:59], v[140:143], v[148:151], v[56:59]
	v_mfma_f32_16x16x32_bf16 v[44:47], v[132:135], v[156:159], v[44:47]
	v_mfma_f32_16x16x32_bf16 v[40:43], v[140:143], v[156:159], v[40:43]
	v_mfma_f32_16x16x32_bf16 v[28:31], v[132:135], v[164:167], v[28:31]
	v_mfma_f32_16x16x32_bf16 v[24:27], v[140:143], v[164:167], v[24:27]
	v_mfma_f32_16x16x32_bf16 v[12:15], v[132:135], v[172:175], v[12:15]
	v_mfma_f32_16x16x32_bf16 v[8:11], v[140:143], v[172:175], v[8:11]
	s_setprio 0
	s_barrier
	s_add_u32 s40, s40, 0x80080
	s_addc_u32 s41, s41, 0
	s_add_i32 s42, s42, s49
	v_lshl_add_u64 v[128:129], s[40:41], 0, v[176:177]
	s_mov_b32 m0, s42
	s_nop 0
	global_load_lds_dwordx4 v[128:129], off
	v_lshl_add_u64 v[128:129], s[40:41], 0, v[178:179]
	s_add_i32 m0, s42, 0x2000
	s_nop 0
	global_load_lds_dwordx4 v[128:129], off
	s_waitcnt vmcnt(6)
	s_barrier
	s_setprio 1
	v_mfma_f32_16x16x32_bf16 v[52:55], v[186:189], v[144:147], v[52:55]
	v_mfma_f32_16x16x32_bf16 v[48:51], v[194:197], v[144:147], v[48:51]
	v_mfma_f32_16x16x32_bf16 v[36:39], v[186:189], v[152:155], v[36:39]
	v_mfma_f32_16x16x32_bf16 v[32:35], v[194:197], v[152:155], v[32:35]
	v_mfma_f32_16x16x32_bf16 v[20:23], v[186:189], v[160:163], v[20:23]
	v_mfma_f32_16x16x32_bf16 v[16:19], v[194:197], v[160:163], v[16:19]
	v_mfma_f32_16x16x32_bf16 v[4:7], v[186:189], v[168:171], v[4:7]
	v_mfma_f32_16x16x32_bf16 v[0:3], v[194:197], v[168:171], v[0:3]
	v_mfma_f32_16x16x32_bf16 v[52:55], v[190:193], v[148:151], v[52:55]
	v_mfma_f32_16x16x32_bf16 v[48:51], v[206:209], v[148:151], v[48:51]
	v_mfma_f32_16x16x32_bf16 v[36:39], v[190:193], v[156:159], v[36:39]
	v_mfma_f32_16x16x32_bf16 v[32:35], v[206:209], v[156:159], v[32:35]
	v_mfma_f32_16x16x32_bf16 v[20:23], v[190:193], v[164:167], v[20:23]
	v_mfma_f32_16x16x32_bf16 v[16:19], v[206:209], v[164:167], v[16:19]
	v_mfma_f32_16x16x32_bf16 v[4:7], v[190:193], v[172:175], v[4:7]
	v_mfma_f32_16x16x32_bf16 v[0:3], v[206:209], v[172:175], v[0:3]
	s_setprio 0
	s_add_i32 s29, s29, 2
	s_add_u32 s38, s38, 0x100
	s_addc_u32 s39, s39, 0
	s_add_u32 s21, s21, 0x100
	s_addc_u32 s23, s23, 0
	s_cmp_gt_u32 s29, 29
	s_barrier
	s_cbranch_scc0 .LBB0_621
	v_lshl_add_u32 v190, s28, 8, v198
	v_lshl_add_u32 v186, s62, 8, v200
	v_ashrrev_i32_e32 v187, 31, v186
	v_ashrrev_i32_e32 v191, 31, v190
	v_lshl_add_u64 v[188:189], v[186:187], 2, s[16:17]
	v_lshlrev_b64 v[128:129], 13, v[190:191]
	v_lshl_add_u64 v[128:129], v[188:189], 0, v[128:129]
	global_load_dwordx4 v[206:209], v[128:129], off
	global_load_dwordx4 v[210:213], v[128:129], off offset:16
	global_load_dwordx4 v[214:217], v[128:129], off offset:512
	global_load_dwordx4 v[218:221], v[128:129], off offset:528
	v_or_b32_e32 v196, 16, v190
	v_or_b32_e32 v194, 32, v190
	v_or_b32_e32 v192, 48, v190
	v_ashrrev_i32_e32 v197, 31, v196
	v_ashrrev_i32_e32 v195, 31, v194
	v_ashrrev_i32_e32 v193, 31, v192
	v_lshlrev_b64 v[128:129], 13, v[196:197]
	v_lshlrev_b64 v[130:131], 13, v[194:195]
	v_lshlrev_b64 v[132:133], 13, v[192:193]
	v_lshl_add_u64 v[128:129], v[188:189], 0, v[128:129]
	v_lshl_add_u64 v[130:131], v[188:189], 0, v[130:131]
	v_lshl_add_u64 v[132:133], v[188:189], 0, v[132:133]
	global_load_dwordx4 v[168:171], v[128:129], off offset:16
	global_load_dwordx4 v[172:175], v[128:129], off
	global_load_dwordx4 v[160:163], v[128:129], off offset:528
	global_load_dwordx4 v[164:167], v[128:129], off offset:512
	global_load_dwordx4 v[152:155], v[130:131], off offset:16
	global_load_dwordx4 v[156:159], v[130:131], off
	global_load_dwordx4 v[144:147], v[130:131], off offset:528
	global_load_dwordx4 v[148:151], v[130:131], off offset:512
	global_load_dwordx4 v[136:139], v[132:133], off offset:16
	global_load_dwordx4 v[140:143], v[132:133], off
	s_nop 0
	global_load_dwordx4 v[128:131], v[132:133], off offset:528
	s_nop 0
	global_load_dwordx4 v[132:135], v[132:133], off offset:512
	v_lshlrev_b64 v[222:223], 12, v[190:191]
	v_lshlrev_b64 v[186:187], 1, v[186:187]
	v_lshl_add_u64 v[224:225], s[18:19], 0, v[222:223]
	v_lshl_add_u64 v[224:225], v[224:225], 0, v[186:187]
	v_lshl_add_u64 v[222:223], s[10:11], 0, v[222:223]
	v_lshl_add_u64 v[222:223], v[222:223], 0, v[186:187]
	s_waitcnt vmcnt(0)
	v_pk_add_f32 v[124:125], v[124:125], v[206:207]
	v_pk_add_f32 v[120:121], v[120:121], v[210:211]
	v_pk_add_f32 v[206:207], v[116:117], v[214:215]
	v_pk_add_f32 v[210:211], v[112:113], v[218:219]
	v_cvt_pk_bf16_f32 v112, v124, v125
	v_mul_f32_e32 v117, v125, v125
	v_mul_f32_e32 v125, v207, v207
	v_pk_add_f32 v[126:127], v[126:127], v[208:209]
	v_pk_add_f32 v[118:119], v[118:119], v[216:217]
	v_fmac_f32_e32 v117, v124, v124
	v_fmac_f32_e32 v125, v206, v206
	v_fmac_f32_e32 v117, v126, v126
	v_fmac_f32_e32 v125, v118, v118
	v_fmac_f32_e32 v117, v127, v127
	v_fmac_f32_e32 v125, v119, v119
	v_fmac_f32_e32 v117, v120, v120
	v_fmac_f32_e32 v125, v210, v210
	v_pk_add_f32 v[122:123], v[122:123], v[212:213]
	v_pk_add_f32 v[208:209], v[114:115], v[220:221]
	v_fmac_f32_e32 v117, v121, v121
	v_fmac_f32_e32 v125, v211, v211
	v_fmac_f32_e32 v117, v122, v122
	v_fmac_f32_e32 v125, v208, v208
	v_fmac_f32_e32 v117, v123, v123
	v_fmac_f32_e32 v125, v209, v209
	v_cvt_pk_bf16_f32 v114, v120, v121
	v_add_f32_e32 v120, v117, v125
	ds_bpermute_b32 v121, v201, v120
	v_cvt_pk_bf16_f32 v113, v126, v127
	v_cvt_pk_bf16_f32 v115, v122, v123
	global_store_dwordx4 v[224:225], v[112:115], off sc1
	v_cvt_pk_bf16_f32 v116, v206, v207
	v_cvt_pk_bf16_f32 v117, v118, v119
	s_waitcnt lgkmcnt(0)
	v_add_f32_e32 v112, v120, v121
	ds_bpermute_b32 v113, v202, v112
	v_add_co_u32_e32 v114, vcc, s61, v222
	v_cvt_pk_bf16_f32 v118, v210, v211
	v_cvt_pk_bf16_f32 v119, v208, v209
	v_addc_co_u32_e32 v115, vcc, 0, v223, vcc
	global_store_dwordx4 v[114:115], v[116:119], off offset:256 sc1
	s_and_saveexec_b64 s[28:29], s[2:3]
	s_cbranch_execz .LBB0_624
	s_waitcnt lgkmcnt(0)
	v_add_f32_e32 v114, v112, v113
	v_lshl_add_u64 v[112:113], v[190:191], 2, s[14:15]
	global_atomic_add_f32 v[112:113], v114, off
; DI u32x2 pk4(f32x4 v) { u32x2 r; r.x = pk2(v[0], v[1]); r.y = pk2(v[2], v[3]); return r; }
;     DI void operator()(const Acc& acc, const Unit& u, int wr, int wc, int fr, int fq) const {
;     ...
;                 for (int m = 0; m < 4; ++m) { const int r = row0 + ai * HALF + m * 16; const size_t o = (size_t)r * 2048 + colp; float part = 0.f;
; #pragma unroll
;                     for (int bj = 0; bj < 2; ++bj) { const f32x4 x0 = xo[m][bj][0] + acc[ai][bj][m][0], x1 = xo[m][bj][1] + acc[ai][bj][m][1];
;                         const u32x2 h0 = pk4(x0), h1 = pk4(x1);
;                         *(u32x4*)(WSB(OFF_XB) + o + bj * HALF) = (u32x4){h0.x, h0.y, h1.x, h1.y};
;                         part += x0[0] * x0[0] + x0[1] * x0[1] + x0[2] * x0[2] + x0[3] * x0[3] + x1[0] * x1[0] + x1[1] * x1[1] + x1[2] * x1[2] + x1[3] * x1[3]; }
;                     part += __shfl_xor(part, 16); part += __shfl_xor(part, 32);
;                     if (fq == 0) unsafeAtomicAdd(ssq + r, part);
.LBB0_624:
	s_or_b64 exec, exec, s[28:29]
	s_waitcnt lgkmcnt(0)
	v_lshlrev_b64 v[112:113], 12, v[196:197]
	v_pk_add_f32 v[110:111], v[110:111], v[174:175]
	v_pk_add_f32 v[108:109], v[108:109], v[172:173]
	v_pk_add_f32 v[114:115], v[106:107], v[170:171]
	v_pk_add_f32 v[116:117], v[104:105], v[168:169]
	v_lshl_add_u64 v[118:119], s[18:19], 0, v[112:113]
	v_cvt_pk_bf16_f32 v104, v108, v109
	v_cvt_pk_bf16_f32 v105, v110, v111
	v_cvt_pk_bf16_f32 v106, v116, v117
	v_cvt_pk_bf16_f32 v107, v114, v115
	v_lshl_add_u64 v[118:119], v[118:119], 0, v[186:187]
	v_pk_add_f32 v[100:101], v[100:101], v[164:165]
	global_store_dwordx4 v[118:119], v[104:107], off sc1
	v_pk_add_f32 v[102:103], v[102:103], v[166:167]
	v_pk_add_f32 v[96:97], v[96:97], v[160:161]
	v_mul_f32_e32 v106, v109, v109
	v_pk_add_f32 v[104:105], v[98:99], v[162:163]
	v_cvt_pk_bf16_f32 v98, v100, v101
	v_mul_f32_e32 v101, v101, v101
	v_fmac_f32_e32 v106, v108, v108
	v_fmac_f32_e32 v101, v100, v100
	v_fmac_f32_e32 v106, v110, v110
	v_fmac_f32_e32 v101, v102, v102
	v_fmac_f32_e32 v106, v111, v111
	v_fmac_f32_e32 v101, v103, v103
	v_fmac_f32_e32 v106, v116, v116
	v_fmac_f32_e32 v101, v96, v96
	v_fmac_f32_e32 v106, v117, v117
	v_fmac_f32_e32 v101, v97, v97
	v_fmac_f32_e32 v106, v114, v114
	v_fmac_f32_e32 v101, v104, v104
	v_fmac_f32_e32 v106, v115, v115
	v_fmac_f32_e32 v101, v105, v105
	v_add_f32_e32 v106, v106, v101
	ds_bpermute_b32 v107, v201, v106
	v_cvt_pk_bf16_f32 v100, v96, v97
	v_lshl_add_u64 v[96:97], s[10:11], 0, v[112:113]
	v_cvt_pk_bf16_f32 v99, v102, v103
	v_lshl_add_u64 v[102:103], v[96:97], 0, v[186:187]
	s_waitcnt lgkmcnt(0)
	v_add_f32_e32 v96, v106, v107
	ds_bpermute_b32 v97, v202, v96
	v_add_co_u32_e32 v102, vcc, s61, v102
	v_cvt_pk_bf16_f32 v101, v104, v105
	s_nop 0
	v_addc_co_u32_e32 v103, vcc, 0, v103, vcc
	global_store_dwordx4 v[102:103], v[98:101], off offset:256 sc1
	s_and_saveexec_b64 s[28:29], s[2:3]
	s_cbranch_execz .LBB0_626
	s_waitcnt lgkmcnt(0)
	v_add_f32_e32 v98, v96, v97
	v_lshl_add_u64 v[96:97], v[196:197], 2, s[14:15]
	global_atomic_add_f32 v[96:97], v98, off
.LBB0_626:
	s_or_b64 exec, exec, s[28:29]
	s_waitcnt lgkmcnt(0)
	v_lshlrev_b64 v[96:97], 12, v[194:195]
	v_pk_add_f32 v[94:95], v[94:95], v[158:159]
	v_pk_add_f32 v[92:93], v[92:93], v[156:157]
	v_pk_add_f32 v[98:99], v[90:91], v[154:155]
	v_pk_add_f32 v[100:101], v[88:89], v[152:153]
	v_lshl_add_u64 v[102:103], s[18:19], 0, v[96:97]
	v_cvt_pk_bf16_f32 v88, v92, v93
	v_cvt_pk_bf16_f32 v89, v94, v95
	v_cvt_pk_bf16_f32 v90, v100, v101
	v_cvt_pk_bf16_f32 v91, v98, v99
	v_lshl_add_u64 v[102:103], v[102:103], 0, v[186:187]
	v_pk_add_f32 v[84:85], v[84:85], v[148:149]
	global_store_dwordx4 v[102:103], v[88:91], off sc1
	v_pk_add_f32 v[86:87], v[86:87], v[150:151]
	v_pk_add_f32 v[80:81], v[80:81], v[144:145]
	v_mul_f32_e32 v90, v93, v93
	v_pk_add_f32 v[88:89], v[82:83], v[146:147]
	v_cvt_pk_bf16_f32 v82, v84, v85
	v_mul_f32_e32 v85, v85, v85
	v_fmac_f32_e32 v90, v92, v92
	v_fmac_f32_e32 v85, v84, v84
	v_fmac_f32_e32 v90, v94, v94
	v_fmac_f32_e32 v85, v86, v86
	v_fmac_f32_e32 v90, v95, v95
	v_fmac_f32_e32 v85, v87, v87
	v_fmac_f32_e32 v90, v100, v100
	v_fmac_f32_e32 v85, v80, v80
	v_fmac_f32_e32 v90, v101, v101
	v_fmac_f32_e32 v85, v81, v81
	v_fmac_f32_e32 v90, v98, v98
	v_fmac_f32_e32 v85, v88, v88
	v_fmac_f32_e32 v90, v99, v99
	v_fmac_f32_e32 v85, v89, v89
	v_add_f32_e32 v90, v90, v85
	ds_bpermute_b32 v91, v201, v90
	v_cvt_pk_bf16_f32 v84, v80, v81
	v_lshl_add_u64 v[80:81], s[10:11], 0, v[96:97]
	v_cvt_pk_bf16_f32 v83, v86, v87
	v_lshl_add_u64 v[86:87], v[80:81], 0, v[186:187]
	s_waitcnt lgkmcnt(0)
	v_add_f32_e32 v80, v90, v91
	ds_bpermute_b32 v81, v202, v80
	v_add_co_u32_e32 v86, vcc, s61, v86
	v_cvt_pk_bf16_f32 v85, v88, v89
	s_nop 0
	v_addc_co_u32_e32 v87, vcc, 0, v87, vcc
	global_store_dwordx4 v[86:87], v[82:85], off offset:256 sc1
	s_and_saveexec_b64 s[28:29], s[2:3]
	s_cbranch_execz .LBB0_628
	s_waitcnt lgkmcnt(0)
	v_add_f32_e32 v82, v80, v81
	v_lshl_add_u64 v[80:81], v[194:195], 2, s[14:15]
	global_atomic_add_f32 v[80:81], v82, off
.LBB0_628:
	s_or_b64 exec, exec, s[28:29]
	s_waitcnt lgkmcnt(0)
	v_lshlrev_b64 v[80:81], 12, v[192:193]
	v_pk_add_f32 v[78:79], v[78:79], v[142:143]
	v_pk_add_f32 v[76:77], v[76:77], v[140:141]
	v_pk_add_f32 v[82:83], v[74:75], v[138:139]
	v_pk_add_f32 v[84:85], v[72:73], v[136:137]
	v_lshl_add_u64 v[86:87], s[18:19], 0, v[80:81]
	v_cvt_pk_bf16_f32 v72, v76, v77
	v_cvt_pk_bf16_f32 v73, v78, v79
	v_cvt_pk_bf16_f32 v74, v84, v85
	v_cvt_pk_bf16_f32 v75, v82, v83
	v_lshl_add_u64 v[86:87], v[86:87], 0, v[186:187]
	v_pk_add_f32 v[68:69], v[68:69], v[132:133]
	global_store_dwordx4 v[86:87], v[72:75], off sc1
	v_pk_add_f32 v[70:71], v[70:71], v[134:135]
	v_pk_add_f32 v[64:65], v[64:65], v[128:129]
	v_mul_f32_e32 v74, v77, v77
	v_pk_add_f32 v[72:73], v[66:67], v[130:131]
	v_cvt_pk_bf16_f32 v66, v68, v69
	v_mul_f32_e32 v69, v69, v69
	v_fmac_f32_e32 v74, v76, v76
	v_fmac_f32_e32 v69, v68, v68
	v_fmac_f32_e32 v74, v78, v78
	v_fmac_f32_e32 v69, v70, v70
	v_fmac_f32_e32 v74, v79, v79
	v_fmac_f32_e32 v69, v71, v71
	v_fmac_f32_e32 v74, v84, v84
	v_fmac_f32_e32 v69, v64, v64
	v_fmac_f32_e32 v74, v85, v85
	v_fmac_f32_e32 v69, v65, v65
	v_fmac_f32_e32 v74, v82, v82
	v_fmac_f32_e32 v69, v72, v72
	v_fmac_f32_e32 v74, v83, v83
	v_fmac_f32_e32 v69, v73, v73
	v_add_f32_e32 v74, v74, v69
	ds_bpermute_b32 v75, v201, v74
	v_cvt_pk_bf16_f32 v68, v64, v65
	v_lshl_add_u64 v[64:65], s[10:11], 0, v[80:81]
	v_cvt_pk_bf16_f32 v67, v70, v71
	v_lshl_add_u64 v[70:71], v[64:65], 0, v[186:187]
	s_waitcnt lgkmcnt(0)
	v_add_f32_e32 v64, v74, v75
	ds_bpermute_b32 v65, v202, v64
	v_add_co_u32_e32 v70, vcc, s61, v70
	v_cvt_pk_bf16_f32 v69, v72, v73
	s_nop 0
	v_addc_co_u32_e32 v71, vcc, 0, v71, vcc
	global_store_dwordx4 v[70:71], v[66:69], off offset:256 sc1
	s_and_saveexec_b64 s[28:29], s[2:3]
	s_cbranch_execz .LBB0_630
	s_waitcnt lgkmcnt(0)
	v_add_f32_e32 v66, v64, v65
	v_lshl_add_u64 v[64:65], v[192:193], 2, s[14:15]
	global_atomic_add_f32 v[64:65], v66, off
; DI u32x2 pk4(f32x4 v) { u32x2 r; r.x = pk2(v[0], v[1]); r.y = pk2(v[2], v[3]); return r; }
; DI float bf_lo(unsigned w) { return __uint_as_float(w << 16); }
; DI float bf_hi(unsigned w) { return __uint_as_float(w & 0xffff0000u); }
; #define COLS4 _Pragma("unroll") for (int bj = 0; bj < 2; ++bj) _Pragma("unroll") for (int n = 0; n < 2; ++n)
;     DI void operator()(const Acc& acc, const Unit& u, int wr, int wc, int fr, int fq) const {
;     ...
;             for (int ai = 0; ai < 2; ++ai) if (ai == 0 || !hf) {
;                 f32x4 xo[4][2][2];
; #pragma unroll
;                 for (int m = 0; m < 4; ++m) { const size_t o = (size_t)(row0 + ai * HALF + m * 16) * 2048 + colp;
;                     if (PH == 4) { COLS4 xo[m][bj][n] = *(const f32x4*)(p.x + o + bj * HALF + n * 4); }
;                     else {
; #pragma unroll
;                         for (int bj = 0; bj < 2; ++bj) { const u32x4 w = *(const u32x4*)(WSB(OFF_XB) + o + bj * HALF);
;                             xo[m][bj][0] = (f32x4){bf_lo(w.x), bf_hi(w.x), bf_lo(w.y), bf_hi(w.y)}; xo[m][bj][1] = (f32x4){bf_lo(w.z), bf_hi(w.z), bf_lo(w.w), bf_hi(w.w)}; } } }
; #pragma unroll
;                 for (int m = 0; m < 4; ++m) { const int r = row0 + ai * HALF + m * 16; const size_t o = (size_t)r * 2048 + colp; float part = 0.f;
; #pragma unroll
;                     for (int bj = 0; bj < 2; ++bj) { const f32x4 x0 = xo[m][bj][0] + acc[ai][bj][m][0], x1 = xo[m][bj][1] + acc[ai][bj][m][1];
;                         const u32x2 h0 = pk4(x0), h1 = pk4(x1);
;                         *(u32x4*)(WSB(OFF_XB) + o + bj * HALF) = (u32x4){h0.x, h0.y, h1.x, h1.y};
;                         part += x0[0] * x0[0] + x0[1] * x0[1] + x0[2] * x0[2] + x0[3] * x0[3] + x1[0] * x1[0] + x1[1] * x1[1] + x1[2] * x1[2] + x1[3] * x1[3]; }
;                     part += __shfl_xor(part, 16); part += __shfl_xor(part, 32);
;                     if (fq == 0) unsafeAtomicAdd(ssq + r, part);
;                 }
.LBB0_630:
	s_or_b64 exec, exec, s[28:29]
	v_add_u32_e32 v118, 0x80, v190
	v_ashrrev_i32_e32 v119, 31, v118
	s_waitcnt lgkmcnt(0)
	v_lshlrev_b64 v[64:65], 13, v[118:119]
	v_lshl_add_u64 v[64:65], v[188:189], 0, v[64:65]
	global_load_dwordx4 v[120:123], v[64:65], off
	global_load_dwordx4 v[124:127], v[64:65], off offset:16
	global_load_dwordx4 v[128:131], v[64:65], off offset:512
	global_load_dwordx4 v[132:135], v[64:65], off offset:528
	v_add_u32_e32 v116, 0x90, v190
	v_add_u32_e32 v114, 0xa0, v190
	v_add_u32_e32 v112, 0xb0, v190
	v_ashrrev_i32_e32 v117, 31, v116
	v_ashrrev_i32_e32 v115, 31, v114
	v_ashrrev_i32_e32 v113, 31, v112
	v_lshlrev_b64 v[64:65], 13, v[116:117]
	v_lshlrev_b64 v[66:67], 13, v[114:115]
	v_lshlrev_b64 v[68:69], 13, v[112:113]
	v_lshl_add_u64 v[64:65], v[188:189], 0, v[64:65]
	v_lshl_add_u64 v[66:67], v[188:189], 0, v[66:67]
	v_lshl_add_u64 v[68:69], v[188:189], 0, v[68:69]
	global_load_dwordx4 v[104:107], v[64:65], off offset:16
	global_load_dwordx4 v[108:111], v[64:65], off
	global_load_dwordx4 v[96:99], v[64:65], off offset:528
	global_load_dwordx4 v[100:103], v[64:65], off offset:512
	global_load_dwordx4 v[88:91], v[66:67], off offset:16
	global_load_dwordx4 v[92:95], v[66:67], off
	global_load_dwordx4 v[80:83], v[66:67], off offset:528
	global_load_dwordx4 v[84:87], v[66:67], off offset:512
	global_load_dwordx4 v[72:75], v[68:69], off offset:16
	global_load_dwordx4 v[76:79], v[68:69], off
	s_nop 0
	global_load_dwordx4 v[64:67], v[68:69], off offset:528
	s_nop 0
	global_load_dwordx4 v[68:71], v[68:69], off offset:512
	v_lshlrev_b64 v[136:137], 12, v[118:119]
	v_lshl_add_u64 v[138:139], s[18:19], 0, v[136:137]
	v_lshl_add_u64 v[138:139], v[138:139], 0, v[186:187]
	v_lshl_add_u64 v[136:137], s[10:11], 0, v[136:137]
	v_lshl_add_u64 v[136:137], v[136:137], 0, v[186:187]
	s_waitcnt vmcnt(15)
	v_pk_add_f32 v[60:61], v[60:61], v[120:121]
	s_waitcnt vmcnt(14)
	v_pk_add_f32 v[56:57], v[56:57], v[124:125]
	s_waitcnt vmcnt(13)
	v_pk_add_f32 v[120:121], v[52:53], v[128:129]
	s_waitcnt vmcnt(12)
	v_pk_add_f32 v[124:125], v[48:49], v[132:133]
	v_cvt_pk_bf16_f32 v48, v60, v61
	v_mul_f32_e32 v53, v61, v61
	v_mul_f32_e32 v61, v121, v121
	v_pk_add_f32 v[62:63], v[62:63], v[122:123]
	v_pk_add_f32 v[54:55], v[54:55], v[130:131]
	v_fmac_f32_e32 v53, v60, v60
	v_fmac_f32_e32 v61, v120, v120
	v_fmac_f32_e32 v53, v62, v62
	v_fmac_f32_e32 v61, v54, v54
	v_fmac_f32_e32 v53, v63, v63
	v_fmac_f32_e32 v61, v55, v55
	v_fmac_f32_e32 v53, v56, v56
	v_fmac_f32_e32 v61, v124, v124
	v_pk_add_f32 v[58:59], v[58:59], v[126:127]
	v_pk_add_f32 v[122:123], v[50:51], v[134:135]
	v_fmac_f32_e32 v53, v57, v57
	v_fmac_f32_e32 v61, v125, v125
	v_fmac_f32_e32 v53, v58, v58
	v_fmac_f32_e32 v61, v122, v122
	v_fmac_f32_e32 v53, v59, v59
	v_fmac_f32_e32 v61, v123, v123
	v_cvt_pk_bf16_f32 v50, v56, v57
	v_add_f32_e32 v56, v53, v61
	ds_bpermute_b32 v57, v201, v56
	v_cvt_pk_bf16_f32 v49, v62, v63
	v_cvt_pk_bf16_f32 v51, v58, v59
	global_store_dwordx4 v[138:139], v[48:51], off sc1
	v_cvt_pk_bf16_f32 v52, v120, v121
	v_cvt_pk_bf16_f32 v53, v54, v55
	s_waitcnt lgkmcnt(0)
	v_add_f32_e32 v48, v56, v57
	ds_bpermute_b32 v49, v202, v48
	v_add_co_u32_e32 v50, vcc, s61, v136
	v_cvt_pk_bf16_f32 v54, v124, v125
	v_cvt_pk_bf16_f32 v55, v122, v123
	v_addc_co_u32_e32 v51, vcc, 0, v137, vcc
	global_store_dwordx4 v[50:51], v[52:55], off offset:256 sc1
	s_and_saveexec_b64 s[28:29], s[2:3]
	s_cbranch_execz .LBB0_632
	s_waitcnt lgkmcnt(0)
	v_add_f32_e32 v50, v48, v49
	v_lshl_add_u64 v[48:49], v[118:119], 2, s[14:15]
	global_atomic_add_f32 v[48:49], v50, off
.LBB0_632:
	s_or_b64 exec, exec, s[28:29]
	s_waitcnt lgkmcnt(0)
	v_lshlrev_b64 v[48:49], 12, v[116:117]
	s_waitcnt vmcnt(12)
	v_pk_add_f32 v[46:47], v[46:47], v[110:111]
	v_pk_add_f32 v[44:45], v[44:45], v[108:109]
	v_pk_add_f32 v[50:51], v[42:43], v[106:107]
	v_pk_add_f32 v[52:53], v[40:41], v[104:105]
	v_lshl_add_u64 v[54:55], s[18:19], 0, v[48:49]
	v_cvt_pk_bf16_f32 v40, v44, v45
	v_cvt_pk_bf16_f32 v41, v46, v47
	v_cvt_pk_bf16_f32 v42, v52, v53
	v_cvt_pk_bf16_f32 v43, v50, v51
	v_lshl_add_u64 v[54:55], v[54:55], 0, v[186:187]
	s_waitcnt vmcnt(10)
	v_pk_add_f32 v[36:37], v[36:37], v[100:101]
	global_store_dwordx4 v[54:55], v[40:43], off sc1
	v_pk_add_f32 v[38:39], v[38:39], v[102:103]
	v_pk_add_f32 v[32:33], v[32:33], v[96:97]
	v_mul_f32_e32 v42, v45, v45
	v_pk_add_f32 v[40:41], v[34:35], v[98:99]
	v_cvt_pk_bf16_f32 v34, v36, v37
	v_mul_f32_e32 v37, v37, v37
	v_fmac_f32_e32 v42, v44, v44
	v_fmac_f32_e32 v37, v36, v36
	v_fmac_f32_e32 v42, v46, v46
	v_fmac_f32_e32 v37, v38, v38
	v_fmac_f32_e32 v42, v47, v47
	v_fmac_f32_e32 v37, v39, v39
	v_fmac_f32_e32 v42, v52, v52
	v_fmac_f32_e32 v37, v32, v32
	v_fmac_f32_e32 v42, v53, v53
	v_fmac_f32_e32 v37, v33, v33
	v_fmac_f32_e32 v42, v50, v50
	v_fmac_f32_e32 v37, v40, v40
	v_fmac_f32_e32 v42, v51, v51
	v_fmac_f32_e32 v37, v41, v41
	v_add_f32_e32 v42, v42, v37
	ds_bpermute_b32 v43, v201, v42
	v_cvt_pk_bf16_f32 v36, v32, v33
	v_lshl_add_u64 v[32:33], s[10:11], 0, v[48:49]
	v_cvt_pk_bf16_f32 v35, v38, v39
	v_lshl_add_u64 v[38:39], v[32:33], 0, v[186:187]
	s_waitcnt lgkmcnt(0)
	v_add_f32_e32 v32, v42, v43
	ds_bpermute_b32 v33, v202, v32
	v_add_co_u32_e32 v38, vcc, s61, v38
	v_cvt_pk_bf16_f32 v37, v40, v41
	s_nop 0
	v_addc_co_u32_e32 v39, vcc, 0, v39, vcc
	global_store_dwordx4 v[38:39], v[34:37], off offset:256 sc1
	s_and_saveexec_b64 s[28:29], s[2:3]
	s_cbranch_execz .LBB0_634
	s_waitcnt lgkmcnt(0)
	v_add_f32_e32 v34, v32, v33
	v_lshl_add_u64 v[32:33], v[116:117], 2, s[14:15]
	global_atomic_add_f32 v[32:33], v34, off
; DI u32x2 pk4(f32x4 v) { u32x2 r; r.x = pk2(v[0], v[1]); r.y = pk2(v[2], v[3]); return r; }
; DI float bf_lo(unsigned w) { return __uint_as_float(w << 16); }
; DI float bf_hi(unsigned w) { return __uint_as_float(w & 0xffff0000u); }
; #define COLS4 _Pragma("unroll") for (int bj = 0; bj < 2; ++bj) _Pragma("unroll") for (int n = 0; n < 2; ++n)
;     DI void operator()(const Acc& acc, const Unit& u, int wr, int wc, int fr, int fq) const {
;     ...
;             for (int ai = 0; ai < 2; ++ai) if (ai == 0 || !hf) {
;                 f32x4 xo[4][2][2];
; #pragma unroll
;                 for (int m = 0; m < 4; ++m) { const size_t o = (size_t)(row0 + ai * HALF + m * 16) * 2048 + colp;
;                     if (PH == 4) { COLS4 xo[m][bj][n] = *(const f32x4*)(p.x + o + bj * HALF + n * 4); }
;                     else {
; #pragma unroll
;                         for (int bj = 0; bj < 2; ++bj) { const u32x4 w = *(const u32x4*)(WSB(OFF_XB) + o + bj * HALF);
;                             xo[m][bj][0] = (f32x4){bf_lo(w.x), bf_hi(w.x), bf_lo(w.y), bf_hi(w.y)}; xo[m][bj][1] = (f32x4){bf_lo(w.z), bf_hi(w.z), bf_lo(w.w), bf_hi(w.w)}; } } }
; #pragma unroll
;                 for (int m = 0; m < 4; ++m) { const int r = row0 + ai * HALF + m * 16; const size_t o = (size_t)r * 2048 + colp; float part = 0.f;
; #pragma unroll
;                     for (int bj = 0; bj < 2; ++bj) { const f32x4 x0 = xo[m][bj][0] + acc[ai][bj][m][0], x1 = xo[m][bj][1] + acc[ai][bj][m][1];
;                         const u32x2 h0 = pk4(x0), h1 = pk4(x1);
;                         *(u32x4*)(WSB(OFF_XB) + o + bj * HALF) = (u32x4){h0.x, h0.y, h1.x, h1.y};
;                         part += x0[0] * x0[0] + x0[1] * x0[1] + x0[2] * x0[2] + x0[3] * x0[3] + x1[0] * x1[0] + x1[1] * x1[1] + x1[2] * x1[2] + x1[3] * x1[3]; }
;                     part += __shfl_xor(part, 16); part += __shfl_xor(part, 32);
;                     if (fq == 0) unsafeAtomicAdd(ssq + r, part);
;                 }
.LBB0_634:
	s_or_b64 exec, exec, s[28:29]
	s_waitcnt lgkmcnt(0)
	v_lshlrev_b64 v[32:33], 12, v[114:115]
	s_waitcnt vmcnt(10)
	v_pk_add_f32 v[30:31], v[30:31], v[94:95]
	v_pk_add_f32 v[28:29], v[28:29], v[92:93]
	v_pk_add_f32 v[34:35], v[26:27], v[90:91]
	v_pk_add_f32 v[36:37], v[24:25], v[88:89]
	v_lshl_add_u64 v[38:39], s[18:19], 0, v[32:33]
	v_cvt_pk_bf16_f32 v24, v28, v29
	v_cvt_pk_bf16_f32 v25, v30, v31
	v_cvt_pk_bf16_f32 v26, v36, v37
	v_cvt_pk_bf16_f32 v27, v34, v35
	v_lshl_add_u64 v[38:39], v[38:39], 0, v[186:187]
	s_waitcnt vmcnt(8)
	v_pk_add_f32 v[20:21], v[20:21], v[84:85]
	global_store_dwordx4 v[38:39], v[24:27], off sc1
	v_pk_add_f32 v[22:23], v[22:23], v[86:87]
	v_pk_add_f32 v[16:17], v[16:17], v[80:81]
	v_mul_f32_e32 v26, v29, v29
	v_pk_add_f32 v[24:25], v[18:19], v[82:83]
	v_cvt_pk_bf16_f32 v18, v20, v21
	v_mul_f32_e32 v21, v21, v21
	v_fmac_f32_e32 v26, v28, v28
	v_fmac_f32_e32 v21, v20, v20
	v_fmac_f32_e32 v26, v30, v30
	v_fmac_f32_e32 v21, v22, v22
	v_fmac_f32_e32 v26, v31, v31
	v_fmac_f32_e32 v21, v23, v23
	v_fmac_f32_e32 v26, v36, v36
	v_fmac_f32_e32 v21, v16, v16
	v_fmac_f32_e32 v26, v37, v37
	v_fmac_f32_e32 v21, v17, v17
	v_fmac_f32_e32 v26, v34, v34
	v_fmac_f32_e32 v21, v24, v24
	v_fmac_f32_e32 v26, v35, v35
	v_fmac_f32_e32 v21, v25, v25
	v_add_f32_e32 v26, v26, v21
	ds_bpermute_b32 v27, v201, v26
	v_cvt_pk_bf16_f32 v20, v16, v17
	v_lshl_add_u64 v[16:17], s[10:11], 0, v[32:33]
	v_cvt_pk_bf16_f32 v19, v22, v23
	v_lshl_add_u64 v[22:23], v[16:17], 0, v[186:187]
	s_waitcnt lgkmcnt(0)
	v_add_f32_e32 v16, v26, v27
	ds_bpermute_b32 v17, v202, v16
	v_add_co_u32_e32 v22, vcc, s61, v22
	v_cvt_pk_bf16_f32 v21, v24, v25
	s_nop 0
	v_addc_co_u32_e32 v23, vcc, 0, v23, vcc
	global_store_dwordx4 v[22:23], v[18:21], off offset:256 sc1
	s_and_saveexec_b64 s[28:29], s[2:3]
	s_cbranch_execz .LBB0_636
	s_waitcnt lgkmcnt(0)
	v_add_f32_e32 v18, v16, v17
	v_lshl_add_u64 v[16:17], v[114:115], 2, s[14:15]
	global_atomic_add_f32 v[16:17], v18, off
.LBB0_636:
	s_or_b64 exec, exec, s[28:29]
	s_waitcnt lgkmcnt(0)
	v_lshlrev_b64 v[16:17], 12, v[112:113]
	s_waitcnt vmcnt(8)
	v_pk_add_f32 v[14:15], v[14:15], v[78:79]
	v_pk_add_f32 v[12:13], v[12:13], v[76:77]
	v_pk_add_f32 v[18:19], v[10:11], v[74:75]
	v_pk_add_f32 v[20:21], v[8:9], v[72:73]
	v_lshl_add_u64 v[22:23], s[18:19], 0, v[16:17]
	v_cvt_pk_bf16_f32 v8, v12, v13
	v_cvt_pk_bf16_f32 v9, v14, v15
	v_cvt_pk_bf16_f32 v10, v20, v21
	v_cvt_pk_bf16_f32 v11, v18, v19
	v_lshl_add_u64 v[22:23], v[22:23], 0, v[186:187]
	s_waitcnt vmcnt(6)
	v_pk_add_f32 v[4:5], v[4:5], v[68:69]
	global_store_dwordx4 v[22:23], v[8:11], off sc1
	v_pk_add_f32 v[6:7], v[6:7], v[70:71]
	v_pk_add_f32 v[0:1], v[0:1], v[64:65]
	v_mul_f32_e32 v10, v13, v13
	v_pk_add_f32 v[8:9], v[2:3], v[66:67]
	v_cvt_pk_bf16_f32 v2, v4, v5
	v_mul_f32_e32 v5, v5, v5
	v_fmac_f32_e32 v10, v12, v12
	v_fmac_f32_e32 v5, v4, v4
	v_fmac_f32_e32 v10, v14, v14
	v_fmac_f32_e32 v5, v6, v6
	v_fmac_f32_e32 v10, v15, v15
	v_fmac_f32_e32 v5, v7, v7
	v_fmac_f32_e32 v10, v20, v20
	v_fmac_f32_e32 v5, v0, v0
	v_fmac_f32_e32 v10, v21, v21
	v_fmac_f32_e32 v5, v1, v1
	v_fmac_f32_e32 v10, v18, v18
	v_fmac_f32_e32 v5, v8, v8
	v_fmac_f32_e32 v10, v19, v19
	v_fmac_f32_e32 v5, v9, v9
	v_add_f32_e32 v10, v10, v5
	ds_bpermute_b32 v11, v201, v10
	v_cvt_pk_bf16_f32 v4, v0, v1
	v_lshl_add_u64 v[0:1], s[10:11], 0, v[16:17]
	v_cvt_pk_bf16_f32 v3, v6, v7
	v_lshl_add_u64 v[6:7], v[0:1], 0, v[186:187]
	s_waitcnt lgkmcnt(0)
	v_add_f32_e32 v0, v10, v11
	ds_bpermute_b32 v1, v202, v0
	v_add_co_u32_e32 v6, vcc, s61, v6
	v_cvt_pk_bf16_f32 v5, v8, v9
	s_nop 0
	v_addc_co_u32_e32 v7, vcc, 0, v7, vcc
	global_store_dwordx4 v[6:7], v[2:5], off offset:256 sc1
	s_and_saveexec_b64 s[28:29], s[2:3]
	s_cbranch_execz .LBB0_613
	s_waitcnt lgkmcnt(0)
	v_add_f32_e32 v2, v0, v1
	v_lshl_add_u64 v[0:1], v[112:113], 2, s[14:15]
	global_atomic_add_f32 v[0:1], v2, off
	s_branch .LBB0_613

; #define PG8_STAGE(bufoff, gbase, voff) do { _Pragma("unroll") for (int _i = 0; _i < 2; ++_i) \
;         __builtin_amdgcn_global_load_lds((const unsigned*)((const char*)(gbase) + (voff)[_i]), (LAS unsigned*)(lds + (bufoff) + ldsw + _i * 8192), 16, 0, 0); } while (0)
; #define PG8_LDA(dst, b, h) do { _Pragma("unroll") for (int m = 0; m < 4; ++m) _Pragma("unroll") for (int k = 0; k < 2; ++k) dst[m][k] = *(const LAS bf16x8*)(lds + PG8_SA(b, h) + aoff + m * 2048 + k * 1024); } while (0)
; #define PG8_LDB(dst, b, h) do { _Pragma("unroll") for (int n = 0; n < 2; ++n) _Pragma("unroll") for (int k = 0; k < 2; ++k) dst[n][k] = *(const LAS bf16x8*)(lds + PG8_SB(b, h) + boff + n * 2048 + k * 1024); } while (0)
; #define PG8_WAIT_V(n) asm volatile("s_waitcnt vmcnt(" #n ")" ::: "memory")
; #define PG8_WAIT_L(n) asm volatile("s_waitcnt lgkmcnt(" #n ")" ::: "memory")
; #define PG8_BAR __builtin_amdgcn_s_barrier()
; #define PG8_SCHED __builtin_amdgcn_sched_barrier(0)
; template <class Epi>
; DI void gemm_phase(LAS unsigned char* lds, int wid, int K, int lda, int ldb, bool bperm, const Sched3& S, const Epi& E) {
;     ...
;             PG8_LDB(B0, 0, 0); PG8_SCHED; PG8_LDA(At, 0, 0); PG8_STAGE(PG8_SA(1, 1), a1 + hA, voffA);
;             PG8_WAIT_L(8); PG8_BAR; PG8_WAIT_L(0); PG8_MMA(0, 0, At, B0); PG8_BAR; PG8_SCHED;
;             PG8_LDB(B1, 0, 1); PG8_STAGE(PG8_SB(0, 0), b2, voffB);
;             PG8_BAR; PG8_WAIT_L(0); PG8_MMA(0, 1, At, B1); PG8_BAR;
;             PG8_LDA(At, 0, 1); PG8_STAGE(PG8_SA(0, 0), a2, voffA);
;             PG8_BAR; PG8_WAIT_L(0); if (full) PG8_MMA(1, 0, At, B0); PG8_BAR; PG8_SCHED;
;             PG8_STAGE(PG8_SB(0, 1), b2 + hstepB, voffB);
;             PG8_WAIT_V(6); PG8_BAR; if (full) PG8_MMA(1, 1, At, B1); PG8_BAR;
;             PG8_LDB(B0, 1, 0); PG8_SCHED; PG8_LDA(At, 1, 0); PG8_STAGE(PG8_SA(0, 1), a2 + h2, voffA);
;             PG8_WAIT_L(8); PG8_BAR; PG8_WAIT_L(0); PG8_MMA(0, 0, At, B0); PG8_BAR; PG8_SCHED;
;             PG8_LDB(B1, 1, 1); PG8_STAGE(PG8_SB(1, 0), b3, voffB);
;             PG8_BAR; PG8_WAIT_L(0); PG8_MMA(0, 1, At, B1); PG8_BAR;
;             PG8_LDA(At, 1, 1); PG8_STAGE(PG8_SA(1, 0), a3, voffA);
;             PG8_BAR; PG8_WAIT_L(0); if (full) PG8_MMA(1, 0, At, B0); PG8_BAR; PG8_SCHED;
;             PG8_STAGE(PG8_SB(1, 1), b3 + hstepB, voffB);
;             PG8_WAIT_V(6); PG8_BAR; if (full) PG8_MMA(1, 1, At, B1); PG8_BAR;
.LBB0_785:
	ds_read_b128 v[128:131], v185
	ds_read_b128 v[132:135], v185 offset:1024
	ds_read_b128 v[136:139], v185 offset:2048
	ds_read_b128 v[140:143], v185 offset:3072
	s_add_u32 s28, s26, 0x100
	s_addc_u32 s29, s27, 0
	s_cmpk_eq_i32 s62, 0x54
	s_cselect_b32 s37, s23, s29
	s_cselect_b32 s36, s22, s28
	s_cselect_b32 s31, s25, s61
	s_cselect_b32 s30, s24, s60
	v_lshl_add_u64 v[178:179], s[26:27], 0, v[156:157]
	s_add_i32 m0, s44, 0xc000
	ds_read_b128 v[144:147], v186
	ds_read_b128 v[148:151], v186 offset:1024
	ds_read_b128 v[162:165], v186 offset:2048
	ds_read_b128 v[166:169], v186 offset:3072
	ds_read_b128 v[170:173], v186 offset:4096
	ds_read_b128 v[174:177], v186 offset:5120
	ds_read_b128 v[188:191], v186 offset:6144
	ds_read_b128 v[192:195], v186 offset:7168
	global_load_lds_dwordx4 v[178:179], off
	v_lshl_add_u64 v[178:179], s[26:27], 0, v[158:159]
	s_add_i32 m0, s44, 0xe000
	s_nop 0
	global_load_lds_dwordx4 v[178:179], off
	s_waitcnt lgkmcnt(8)
	s_barrier
	s_waitcnt lgkmcnt(0)
	s_setprio 1
	s_waitcnt lgkmcnt(0)
	v_mfma_f32_16x16x32_bf16 v[124:127], v[128:131], v[144:147], v[124:127]
	v_mfma_f32_16x16x32_bf16 v[120:123], v[136:139], v[144:147], v[120:123]
	v_mfma_f32_16x16x32_bf16 v[108:111], v[128:131], v[162:165], v[108:111]
	v_mfma_f32_16x16x32_bf16 v[104:107], v[136:139], v[162:165], v[104:107]
	v_mfma_f32_16x16x32_bf16 v[92:95], v[128:131], v[170:173], v[92:95]
	v_mfma_f32_16x16x32_bf16 v[88:91], v[136:139], v[170:173], v[88:91]
	v_mfma_f32_16x16x32_bf16 v[76:79], v[128:131], v[188:191], v[76:79]
	v_mfma_f32_16x16x32_bf16 v[72:75], v[136:139], v[188:191], v[72:75]
	v_mfma_f32_16x16x32_bf16 v[124:127], v[132:135], v[148:151], v[124:127]
	v_mfma_f32_16x16x32_bf16 v[120:123], v[140:143], v[148:151], v[120:123]
	v_mfma_f32_16x16x32_bf16 v[108:111], v[132:135], v[166:169], v[108:111]
	v_mfma_f32_16x16x32_bf16 v[104:107], v[140:143], v[166:169], v[104:107]
	v_mfma_f32_16x16x32_bf16 v[92:95], v[132:135], v[174:177], v[92:95]
	v_mfma_f32_16x16x32_bf16 v[88:91], v[140:143], v[174:177], v[88:91]
	v_mfma_f32_16x16x32_bf16 v[76:79], v[132:135], v[192:195], v[76:79]
	v_mfma_f32_16x16x32_bf16 v[72:75], v[140:143], v[192:195], v[72:75]
	s_setprio 0
	s_barrier
	s_add_i32 s26, s53, s43
	v_lshl_add_u64 v[178:179], s[30:31], 0, v[152:153]
	s_mov_b32 m0, s26
	ds_read_b128 v[196:199], v187
	ds_read_b128 v[200:203], v187 offset:1024
	ds_read_b128 v[204:207], v187 offset:2048
	ds_read_b128 v[208:211], v187 offset:3072
	global_load_lds_dwordx4 v[178:179], off
	v_lshl_add_u64 v[212:213], s[30:31], 0, v[154:155]
	s_add_i32 m0, s26, 0x2000
	s_nop 0
	global_load_lds_dwordx4 v[212:213], off
	s_barrier
	s_waitcnt lgkmcnt(0)
	s_setprio 1
	s_waitcnt lgkmcnt(0)
	v_mfma_f32_16x16x32_bf16 v[116:119], v[196:199], v[144:147], v[116:119]
	v_mfma_f32_16x16x32_bf16 v[112:115], v[204:207], v[144:147], v[112:115]
	v_mfma_f32_16x16x32_bf16 v[100:103], v[196:199], v[162:165], v[100:103]
	v_mfma_f32_16x16x32_bf16 v[96:99], v[204:207], v[162:165], v[96:99]
	v_mfma_f32_16x16x32_bf16 v[84:87], v[196:199], v[170:173], v[84:87]
	v_mfma_f32_16x16x32_bf16 v[80:83], v[204:207], v[170:173], v[80:83]
	v_mfma_f32_16x16x32_bf16 v[68:71], v[196:199], v[188:191], v[68:71]
	v_mfma_f32_16x16x32_bf16 v[64:67], v[204:207], v[188:191], v[64:67]
	v_mfma_f32_16x16x32_bf16 v[116:119], v[200:203], v[148:151], v[116:119]
	v_mfma_f32_16x16x32_bf16 v[112:115], v[208:211], v[148:151], v[112:115]
	v_mfma_f32_16x16x32_bf16 v[100:103], v[200:203], v[166:169], v[100:103]
	v_mfma_f32_16x16x32_bf16 v[96:99], v[208:211], v[166:169], v[96:99]
	v_mfma_f32_16x16x32_bf16 v[84:87], v[200:203], v[174:177], v[84:87]
	v_mfma_f32_16x16x32_bf16 v[80:83], v[208:211], v[174:177], v[80:83]
	v_mfma_f32_16x16x32_bf16 v[68:71], v[200:203], v[192:195], v[68:71]
	v_mfma_f32_16x16x32_bf16 v[64:67], v[208:211], v[192:195], v[64:67]
	s_setprio 0
	s_mov_b32 m0, s44
	v_lshl_add_u64 v[214:215], s[36:37], 0, v[152:153]
	s_barrier
	ds_read_b128 v[144:147], v186 offset:16384
	ds_read_b128 v[148:151], v186 offset:17408
	ds_read_b128 v[162:165], v186 offset:18432
	ds_read_b128 v[166:169], v186 offset:19456
	ds_read_b128 v[170:173], v186 offset:20480
	ds_read_b128 v[174:177], v186 offset:21504
	ds_read_b128 v[188:191], v186 offset:22528
	ds_read_b128 v[192:195], v186 offset:23552
	global_load_lds_dwordx4 v[214:215], off
	v_lshl_add_u64 v[216:217], s[36:37], 0, v[154:155]
	s_mov_b32 m0, s45
	s_nop 0
	global_load_lds_dwordx4 v[216:217], off
	s_barrier
	s_waitcnt lgkmcnt(0)
	s_setprio 1
	s_waitcnt lgkmcnt(0)
	v_mfma_f32_16x16x32_bf16 v[60:63], v[128:131], v[144:147], v[60:63]
	v_mfma_f32_16x16x32_bf16 v[56:59], v[136:139], v[144:147], v[56:59]
	v_mfma_f32_16x16x32_bf16 v[44:47], v[128:131], v[162:165], v[44:47]
	v_mfma_f32_16x16x32_bf16 v[40:43], v[136:139], v[162:165], v[40:43]
	v_mfma_f32_16x16x32_bf16 v[28:31], v[128:131], v[170:173], v[28:31]
	v_mfma_f32_16x16x32_bf16 v[24:27], v[136:139], v[170:173], v[24:27]
	v_mfma_f32_16x16x32_bf16 v[12:15], v[128:131], v[188:191], v[12:15]
	v_mfma_f32_16x16x32_bf16 v[8:11], v[136:139], v[188:191], v[8:11]
	v_mfma_f32_16x16x32_bf16 v[60:63], v[132:135], v[148:151], v[60:63]
	v_mfma_f32_16x16x32_bf16 v[56:59], v[140:143], v[148:151], v[56:59]
	v_mfma_f32_16x16x32_bf16 v[44:47], v[132:135], v[166:169], v[44:47]
	v_mfma_f32_16x16x32_bf16 v[40:43], v[140:143], v[166:169], v[40:43]
	v_mfma_f32_16x16x32_bf16 v[28:31], v[132:135], v[174:177], v[28:31]
	v_mfma_f32_16x16x32_bf16 v[24:27], v[140:143], v[174:177], v[24:27]
	v_mfma_f32_16x16x32_bf16 v[12:15], v[132:135], v[192:195], v[12:15]
	v_mfma_f32_16x16x32_bf16 v[8:11], v[140:143], v[192:195], v[8:11]
	s_setprio 0
	s_barrier
; #define PG8_STAGE(bufoff, gbase, voff) do { _Pragma("unroll") for (int _i = 0; _i < 2; ++_i) \
;         __builtin_amdgcn_global_load_lds((const unsigned*)((const char*)(gbase) + (voff)[_i]), (LAS unsigned*)(lds + (bufoff) + ldsw + _i * 8192), 16, 0, 0); } while (0)
; #define PG8_LDA(dst, b, h) do { _Pragma("unroll") for (int m = 0; m < 4; ++m) _Pragma("unroll") for (int k = 0; k < 2; ++k) dst[m][k] = *(const LAS bf16x8*)(lds + PG8_SA(b, h) + aoff + m * 2048 + k * 1024); } while (0)
; #define PG8_LDB(dst, b, h) do { _Pragma("unroll") for (int n = 0; n < 2; ++n) _Pragma("unroll") for (int k = 0; k < 2; ++k) dst[n][k] = *(const LAS bf16x8*)(lds + PG8_SB(b, h) + boff + n * 2048 + k * 1024); } while (0)
; #define PG8_WAIT_V(n) asm volatile("s_waitcnt vmcnt(" #n ")" ::: "memory")
; #define PG8_WAIT_L(n) asm volatile("s_waitcnt lgkmcnt(" #n ")" ::: "memory")
; #define PG8_BAR __builtin_amdgcn_s_barrier()
; #define PG8_SCHED __builtin_amdgcn_sched_barrier(0)
; template <class Epi>
; DI void gemm_phase(LAS unsigned char* lds, int wid, int K, int lda, int ldb, bool bperm, const Sched3& S, const Epi& E) {
;     ...
;             PG8_LDB(B0, 0, 0); PG8_SCHED; PG8_LDA(At, 0, 0); PG8_STAGE(PG8_SA(1, 1), a1 + hA, voffA);
;             PG8_WAIT_L(8); PG8_BAR; PG8_WAIT_L(0); PG8_MMA(0, 0, At, B0); PG8_BAR; PG8_SCHED;
;             PG8_LDB(B1, 0, 1); PG8_STAGE(PG8_SB(0, 0), b2, voffB);
;             PG8_BAR; PG8_WAIT_L(0); PG8_MMA(0, 1, At, B1); PG8_BAR;
;             PG8_LDA(At, 0, 1); PG8_STAGE(PG8_SA(0, 0), a2, voffA);
;             PG8_BAR; PG8_WAIT_L(0); if (full) PG8_MMA(1, 0, At, B0); PG8_BAR; PG8_SCHED;
;             PG8_STAGE(PG8_SB(0, 1), b2 + hstepB, voffB);
;             PG8_WAIT_V(6); PG8_BAR; if (full) PG8_MMA(1, 1, At, B1); PG8_BAR;
;             PG8_LDB(B0, 1, 0); PG8_SCHED; PG8_LDA(At, 1, 0); PG8_STAGE(PG8_SA(0, 1), a2 + h2, voffA);
;             PG8_WAIT_L(8); PG8_BAR; PG8_WAIT_L(0); PG8_MMA(0, 0, At, B0); PG8_BAR; PG8_SCHED;
;             PG8_LDB(B1, 1, 1); PG8_STAGE(PG8_SB(1, 0), b3, voffB);
;             PG8_BAR; PG8_WAIT_L(0); PG8_MMA(0, 1, At, B1); PG8_BAR;
;             PG8_LDA(At, 1, 1); PG8_STAGE(PG8_SA(1, 0), a3, voffA);
;             PG8_BAR; PG8_WAIT_L(0); if (full) PG8_MMA(1, 0, At, B0); PG8_BAR; PG8_SCHED;
;             PG8_STAGE(PG8_SB(1, 1), b3 + hstepB, voffB);
;             PG8_WAIT_V(6); PG8_BAR; if (full) PG8_MMA(1, 1, At, B1); PG8_BAR;
	s_add_u32 s26, s30, 0x160000
	s_addc_u32 s27, s31, 0
	s_add_i32 s63, s54, s43
	v_lshl_add_u64 v[128:129], s[26:27], 0, v[152:153]
	s_mov_b32 m0, s63
	s_nop 0
	global_load_lds_dwordx4 v[128:129], off
	v_lshl_add_u64 v[128:129], s[26:27], 0, v[154:155]
	s_add_i32 m0, s63, 0x2000
	s_nop 0
	global_load_lds_dwordx4 v[128:129], off
	s_waitcnt vmcnt(6)
	s_barrier
	s_setprio 1
	v_mfma_f32_16x16x32_bf16 v[52:55], v[196:199], v[144:147], v[52:55]
	v_mfma_f32_16x16x32_bf16 v[48:51], v[204:207], v[144:147], v[48:51]
	v_mfma_f32_16x16x32_bf16 v[36:39], v[196:199], v[162:165], v[36:39]
	v_mfma_f32_16x16x32_bf16 v[32:35], v[204:207], v[162:165], v[32:35]
	v_mfma_f32_16x16x32_bf16 v[20:23], v[196:199], v[170:173], v[20:23]
	v_mfma_f32_16x16x32_bf16 v[16:19], v[204:207], v[170:173], v[16:19]
	v_mfma_f32_16x16x32_bf16 v[4:7], v[196:199], v[188:191], v[4:7]
	v_mfma_f32_16x16x32_bf16 v[0:3], v[204:207], v[188:191], v[0:3]
	v_mfma_f32_16x16x32_bf16 v[52:55], v[200:203], v[148:151], v[52:55]
	v_mfma_f32_16x16x32_bf16 v[48:51], v[208:211], v[148:151], v[48:51]
	v_mfma_f32_16x16x32_bf16 v[36:39], v[200:203], v[166:169], v[36:39]
	v_mfma_f32_16x16x32_bf16 v[32:35], v[208:211], v[166:169], v[32:35]
	v_mfma_f32_16x16x32_bf16 v[20:23], v[200:203], v[174:177], v[20:23]
	v_mfma_f32_16x16x32_bf16 v[16:19], v[208:211], v[174:177], v[16:19]
	v_mfma_f32_16x16x32_bf16 v[4:7], v[200:203], v[192:195], v[4:7]
	v_mfma_f32_16x16x32_bf16 v[0:3], v[208:211], v[192:195], v[0:3]
	s_setprio 0
	s_add_i32 s63, 0, 0x18000
	v_add_u32_e32 v140, s63, v181
	s_barrier
	ds_read_b128 v[128:131], v140
	ds_read_b128 v[132:135], v140 offset:1024
	ds_read_b128 v[136:139], v140 offset:2048
	ds_read_b128 v[140:143], v140 offset:3072
	s_add_u32 s26, s36, 0x160000
	s_addc_u32 s27, s37, 0
	s_mov_b32 m0, s46
	v_lshl_add_u64 v[196:197], s[26:27], 0, v[152:153]
	ds_read_b128 v[144:147], v186 offset:32768
	ds_read_b128 v[148:151], v186 offset:33792
	ds_read_b128 v[162:165], v186 offset:34816
	ds_read_b128 v[166:169], v186 offset:35840
	ds_read_b128 v[170:173], v186 offset:36864
	ds_read_b128 v[174:177], v186 offset:37888
	ds_read_b128 v[188:191], v186 offset:38912
	ds_read_b128 v[192:195], v186 offset:39936
	global_load_lds_dwordx4 v[196:197], off
	v_lshl_add_u64 v[196:197], s[26:27], 0, v[154:155]
	s_mov_b32 m0, s47
	s_nop 0
	global_load_lds_dwordx4 v[196:197], off
	s_waitcnt lgkmcnt(8)
	s_barrier
	s_waitcnt lgkmcnt(0)
	s_setprio 1
	s_waitcnt lgkmcnt(0)
	v_mfma_f32_16x16x32_bf16 v[124:127], v[128:131], v[144:147], v[124:127]
	v_mfma_f32_16x16x32_bf16 v[120:123], v[136:139], v[144:147], v[120:123]
	v_mfma_f32_16x16x32_bf16 v[108:111], v[128:131], v[162:165], v[108:111]
	v_mfma_f32_16x16x32_bf16 v[104:107], v[136:139], v[162:165], v[104:107]
	v_mfma_f32_16x16x32_bf16 v[92:95], v[128:131], v[170:173], v[92:95]
	v_mfma_f32_16x16x32_bf16 v[88:91], v[136:139], v[170:173], v[88:91]
	v_mfma_f32_16x16x32_bf16 v[76:79], v[128:131], v[188:191], v[76:79]
	v_mfma_f32_16x16x32_bf16 v[72:75], v[136:139], v[188:191], v[72:75]
	v_mfma_f32_16x16x32_bf16 v[124:127], v[132:135], v[148:151], v[124:127]
	v_mfma_f32_16x16x32_bf16 v[120:123], v[140:143], v[148:151], v[120:123]
	v_mfma_f32_16x16x32_bf16 v[108:111], v[132:135], v[166:169], v[108:111]
	v_mfma_f32_16x16x32_bf16 v[104:107], v[140:143], v[166:169], v[104:107]
	v_mfma_f32_16x16x32_bf16 v[92:95], v[132:135], v[174:177], v[92:95]
	v_mfma_f32_16x16x32_bf16 v[88:91], v[140:143], v[174:177], v[88:91]
	v_mfma_f32_16x16x32_bf16 v[76:79], v[132:135], v[192:195], v[76:79]
	v_mfma_f32_16x16x32_bf16 v[72:75], v[140:143], v[192:195], v[72:75]
	s_setprio 0
	s_barrier
	s_add_i32 s36, 0, 0x1c000
	s_add_i32 s26, s63, s43
	v_add_u32_e32 v208, s36, v181
	v_lshl_add_u64 v[178:179], v[178:179], 0, s[12:13]
	s_mov_b32 m0, s26
	ds_read_b128 v[196:199], v208
	ds_read_b128 v[200:203], v208 offset:1024
	ds_read_b128 v[204:207], v208 offset:2048
	ds_read_b128 v[208:211], v208 offset:3072
	global_load_lds_dwordx4 v[178:179], off
	v_lshl_add_u64 v[178:179], v[212:213], 0, s[12:13]
	s_add_i32 m0, s26, 0x2000
	s_nop 0
	global_load_lds_dwordx4 v[178:179], off
	s_barrier
	s_waitcnt lgkmcnt(0)
	s_setprio 1
	s_waitcnt lgkmcnt(0)
	v_mfma_f32_16x16x32_bf16 v[116:119], v[196:199], v[144:147], v[116:119]
	v_mfma_f32_16x16x32_bf16 v[112:115], v[204:207], v[144:147], v[112:115]
	v_mfma_f32_16x16x32_bf16 v[100:103], v[196:199], v[162:165], v[100:103]
	v_mfma_f32_16x16x32_bf16 v[96:99], v[204:207], v[162:165], v[96:99]
	v_mfma_f32_16x16x32_bf16 v[84:87], v[196:199], v[170:173], v[84:87]
	v_mfma_f32_16x16x32_bf16 v[80:83], v[204:207], v[170:173], v[80:83]
	v_mfma_f32_16x16x32_bf16 v[68:71], v[196:199], v[188:191], v[68:71]
	v_mfma_f32_16x16x32_bf16 v[64:67], v[204:207], v[188:191], v[64:67]
	v_mfma_f32_16x16x32_bf16 v[116:119], v[200:203], v[148:151], v[116:119]
	v_mfma_f32_16x16x32_bf16 v[112:115], v[208:211], v[148:151], v[112:115]
	v_mfma_f32_16x16x32_bf16 v[100:103], v[200:203], v[166:169], v[100:103]
	v_mfma_f32_16x16x32_bf16 v[96:99], v[208:211], v[166:169], v[96:99]
	v_mfma_f32_16x16x32_bf16 v[84:87], v[200:203], v[174:177], v[84:87]
	v_mfma_f32_16x16x32_bf16 v[80:83], v[208:211], v[174:177], v[80:83]
	v_mfma_f32_16x16x32_bf16 v[68:71], v[200:203], v[192:195], v[68:71]
	v_mfma_f32_16x16x32_bf16 v[64:67], v[208:211], v[192:195], v[64:67]
	s_setprio 0
	s_mov_b32 m0, s49
	v_lshl_add_u64 v[178:179], v[214:215], 0, s[12:13]
	s_barrier
	ds_read_b128 v[144:147], v186 offset:49152
	ds_read_b128 v[148:151], v186 offset:50176
	ds_read_b128 v[162:165], v186 offset:51200
	ds_read_b128 v[166:169], v186 offset:52224
	ds_read_b128 v[170:173], v186 offset:53248
	ds_read_b128 v[174:177], v186 offset:54272
	ds_read_b128 v[188:191], v186 offset:55296
	ds_read_b128 v[192:195], v186 offset:56320
	global_load_lds_dwordx4 v[178:179], off
	v_lshl_add_u64 v[178:179], v[216:217], 0, s[12:13]
	s_mov_b32 m0, s50
	s_nop 0
	global_load_lds_dwordx4 v[178:179], off
	s_barrier
; template <class Epi>
; DI void gemm_phase(LAS unsigned char* lds, int wid, int K, int lda, int ldb, bool bperm, const Sched3& S, const Epi& E) {
;     ...
;             PG8_WAIT_V(6); PG8_BAR; if (full) PG8_MMA(1, 1, At, B1); PG8_BAR;
;             PG8_LDB(B0, 1, 0); PG8_SCHED; PG8_LDA(At, 1, 0); PG8_STAGE(PG8_SA(0, 1), a2 + h2, voffA);
;             PG8_WAIT_L(8); PG8_BAR; PG8_WAIT_L(0); PG8_MMA(0, 0, At, B0); PG8_BAR; PG8_SCHED;
;             PG8_LDB(B1, 1, 1); PG8_STAGE(PG8_SB(1, 0), b3, voffB);
;             PG8_BAR; PG8_WAIT_L(0); PG8_MMA(0, 1, At, B1); PG8_BAR;
;             PG8_LDA(At, 1, 1); PG8_STAGE(PG8_SA(1, 0), a3, voffA);
;             PG8_BAR; PG8_WAIT_L(0); if (full) PG8_MMA(1, 0, At, B0); PG8_BAR; PG8_SCHED;
;             PG8_STAGE(PG8_SB(1, 1), b3 + hstepB, voffB);
;             PG8_WAIT_V(6); PG8_BAR; if (full) PG8_MMA(1, 1, At, B1); PG8_BAR;
;     DI void operator()(const Acc& acc, const Unit& u, int wr, int wc, int fr, int fq) const {
;     ...
;             for (int ai = 0; ai < 2; ++ai) if (ai == 0 || !hf) {
;                 f32x4 xo[4][2][2];
; #pragma unroll
;                 for (int m = 0; m < 4; ++m) { const size_t o = (size_t)(row0 + ai * HALF + m * 16) * 2048 + colp;
;                     if (PH == 4) { COLS4 xo[m][bj][n] = *(const f32x4*)(p.x + o + bj * HALF + n * 4); }
;                     else {
; #pragma unroll
;                         for (int bj = 0; bj < 2; ++bj) { const u32x4 w = *(const u32x4*)(WSB(OFF_XB) + o + bj * HALF);
;                             xo[m][bj][0] = (f32x4){bf_lo(w.x), bf_hi(w.x), bf_lo(w.y), bf_hi(w.y)}; xo[m][bj][1] = (f32x4){bf_lo(w.z), bf_hi(w.z), bf_lo(w.w), bf_hi(w.w)}; } } }
; #pragma unroll
;                 for (int m = 0; m < 4; ++m) { const int r = row0 + ai * HALF + m * 16; const size_t o = (size_t)r * 2048 + colp; float part = 0.f;
; #pragma unroll
;                     for (int bj = 0; bj < 2; ++bj) { const f32x4 x0 = xo[m][bj][0] + acc[ai][bj][m][0], x1 = xo[m][bj][1] + acc[ai][bj][m][1];
;                         const u32x2 h0 = pk4(x0), h1 = pk4(x1);
;                         *(u32x4*)(WSB(OFF_XB) + o + bj * HALF) = (u32x4){h0.x, h0.y, h1.x, h1.y};
;                         part += x0[0] * x0[0] + x0[1] * x0[1] + x0[2] * x0[2] + x0[3] * x0[3] + x1[0] * x1[0] + x1[1] * x1[1] + x1[2] * x1[2] + x1[3] * x1[3]; }
;                     part += __shfl_xor(part, 16); part += __shfl_xor(part, 32);
	s_waitcnt lgkmcnt(0)
	s_setprio 1
	s_waitcnt lgkmcnt(0)
	v_mfma_f32_16x16x32_bf16 v[60:63], v[128:131], v[144:147], v[60:63]
	v_mfma_f32_16x16x32_bf16 v[56:59], v[136:139], v[144:147], v[56:59]
	v_mfma_f32_16x16x32_bf16 v[44:47], v[128:131], v[162:165], v[44:47]
	v_mfma_f32_16x16x32_bf16 v[40:43], v[136:139], v[162:165], v[40:43]
	v_mfma_f32_16x16x32_bf16 v[28:31], v[128:131], v[170:173], v[28:31]
	v_mfma_f32_16x16x32_bf16 v[24:27], v[136:139], v[170:173], v[24:27]
	v_mfma_f32_16x16x32_bf16 v[12:15], v[128:131], v[188:191], v[12:15]
	v_mfma_f32_16x16x32_bf16 v[8:11], v[136:139], v[188:191], v[8:11]
	v_mfma_f32_16x16x32_bf16 v[60:63], v[132:135], v[148:151], v[60:63]
	v_mfma_f32_16x16x32_bf16 v[56:59], v[140:143], v[148:151], v[56:59]
	v_mfma_f32_16x16x32_bf16 v[44:47], v[132:135], v[166:169], v[44:47]
	v_mfma_f32_16x16x32_bf16 v[40:43], v[140:143], v[166:169], v[40:43]
	v_mfma_f32_16x16x32_bf16 v[28:31], v[132:135], v[174:177], v[28:31]
	v_mfma_f32_16x16x32_bf16 v[24:27], v[140:143], v[174:177], v[24:27]
	v_mfma_f32_16x16x32_bf16 v[12:15], v[132:135], v[192:195], v[12:15]
	v_mfma_f32_16x16x32_bf16 v[8:11], v[140:143], v[192:195], v[8:11]
	s_setprio 0
	s_barrier
	s_add_u32 s26, s30, 0x160080
	s_addc_u32 s27, s31, 0
	s_add_i32 s30, s36, s43
	v_lshl_add_u64 v[128:129], s[26:27], 0, v[152:153]
	s_mov_b32 m0, s30
	s_nop 0
	global_load_lds_dwordx4 v[128:129], off
	v_lshl_add_u64 v[128:129], s[26:27], 0, v[154:155]
	s_add_i32 m0, s30, 0x2000
	s_nop 0
	global_load_lds_dwordx4 v[128:129], off
	s_waitcnt vmcnt(6)
	s_barrier
	s_setprio 1
	v_mfma_f32_16x16x32_bf16 v[52:55], v[196:199], v[144:147], v[52:55]
	v_mfma_f32_16x16x32_bf16 v[48:51], v[204:207], v[144:147], v[48:51]
	v_mfma_f32_16x16x32_bf16 v[36:39], v[196:199], v[162:165], v[36:39]
	v_mfma_f32_16x16x32_bf16 v[32:35], v[204:207], v[162:165], v[32:35]
	v_mfma_f32_16x16x32_bf16 v[20:23], v[196:199], v[170:173], v[20:23]
	v_mfma_f32_16x16x32_bf16 v[16:19], v[204:207], v[170:173], v[16:19]
	v_mfma_f32_16x16x32_bf16 v[4:7], v[196:199], v[188:191], v[4:7]
	v_mfma_f32_16x16x32_bf16 v[0:3], v[204:207], v[188:191], v[0:3]
	v_mfma_f32_16x16x32_bf16 v[52:55], v[200:203], v[148:151], v[52:55]
	v_mfma_f32_16x16x32_bf16 v[48:51], v[208:211], v[148:151], v[48:51]
	v_mfma_f32_16x16x32_bf16 v[36:39], v[200:203], v[166:169], v[36:39]
	v_mfma_f32_16x16x32_bf16 v[32:35], v[208:211], v[166:169], v[32:35]
	v_mfma_f32_16x16x32_bf16 v[20:23], v[200:203], v[174:177], v[20:23]
	v_mfma_f32_16x16x32_bf16 v[16:19], v[208:211], v[174:177], v[16:19]
	v_mfma_f32_16x16x32_bf16 v[4:7], v[200:203], v[192:195], v[4:7]
	v_mfma_f32_16x16x32_bf16 v[0:3], v[208:211], v[192:195], v[0:3]
	s_setprio 0
	s_add_i32 s62, s62, 2
	s_add_u32 s60, s60, 0x100
	s_addc_u32 s61, s61, 0
	s_cmpk_gt_u32 s62, 0x55
	s_mov_b64 s[26:27], s[28:29]
	s_barrier
	s_cbranch_scc0 .LBB0_785
	v_lshl_add_u32 v128, s58, 8, v182
	v_lshl_add_u32 v166, s59, 8, v180
	v_ashrrev_i32_e32 v129, 31, v128
	v_lshlrev_b64 v[162:163], 1, v[128:129]
	v_ashrrev_i32_e32 v167, 31, v166
	v_lshl_add_u64 v[164:165], s[16:17], 0, v[162:163]
	v_lshlrev_b64 v[196:197], 12, v[166:167]
	v_lshl_add_u64 v[128:129], v[164:165], 0, v[196:197]
	global_load_dwordx4 v[188:191], v[128:129], off
	global_load_dwordx4 v[192:195], v[128:129], off offset:256
	v_or_b32_e32 v176, 16, v166
	v_or_b32_e32 v172, 32, v166
	v_or_b32_e32 v168, 48, v166
	v_ashrrev_i32_e32 v177, 31, v176
	v_ashrrev_i32_e32 v173, 31, v172
	v_ashrrev_i32_e32 v169, 31, v168
	v_lshlrev_b64 v[178:179], 12, v[176:177]
	v_lshlrev_b64 v[174:175], 12, v[172:173]
	v_lshlrev_b64 v[170:171], 12, v[168:169]
	v_lshl_add_u64 v[128:129], v[164:165], 0, v[178:179]
	v_lshl_add_u64 v[130:131], v[164:165], 0, v[174:175]
	v_lshl_add_u64 v[198:199], v[164:165], 0, v[170:171]
	global_load_dwordx4 v[148:151], v[128:129], off
	global_load_dwordx4 v[144:147], v[128:129], off offset:256
	global_load_dwordx4 v[140:143], v[130:131], off
	global_load_dwordx4 v[136:139], v[130:131], off offset:256
	global_load_dwordx4 v[132:135], v[198:199], off
	s_nop 0
	global_load_dwordx4 v[128:131], v[198:199], off offset:256
	v_lshl_add_u64 v[198:199], s[16:17], 0, v[196:197]
	v_lshl_add_u64 v[198:199], v[198:199], 0, v[162:163]
	v_lshl_add_u64 v[196:197], s[10:11], 0, v[196:197]
	v_lshl_add_u64 v[196:197], v[196:197], 0, v[162:163]
	s_waitcnt vmcnt(0)
	v_lshlrev_b32_e32 v200, 16, v188
	v_and_b32_e32 v201, 0xffff0000, v188
	v_lshlrev_b32_e32 v188, 16, v189
	v_and_b32_e32 v189, 0xffff0000, v189
	v_lshlrev_b32_e32 v204, 16, v192
	v_and_b32_e32 v205, 0xffff0000, v192
	v_lshlrev_b32_e32 v192, 16, v193
	v_and_b32_e32 v193, 0xffff0000, v193
	v_lshlrev_b32_e32 v206, 16, v194
	v_and_b32_e32 v207, 0xffff0000, v194
	v_pk_add_f32 v[126:127], v[126:127], v[188:189]
	v_pk_add_f32 v[124:125], v[124:125], v[200:201]
	v_pk_add_f32 v[188:189], v[116:117], v[204:205]
	v_pk_add_f32 v[118:119], v[118:119], v[192:193]
	v_pk_add_f32 v[192:193], v[112:113], v[206:207]
	v_cvt_pk_bf16_f32 v112, v124, v125
	v_mul_f32_e32 v117, v125, v125
	v_mul_f32_e32 v125, v189, v189
	v_fmac_f32_e32 v117, v124, v124
	v_fmac_f32_e32 v125, v188, v188
	v_lshlrev_b32_e32 v202, 16, v190
	v_and_b32_e32 v203, 0xffff0000, v190
	v_fmac_f32_e32 v117, v126, v126
	v_fmac_f32_e32 v125, v118, v118
	v_pk_add_f32 v[120:121], v[120:121], v[202:203]
	v_fmac_f32_e32 v117, v127, v127
	v_fmac_f32_e32 v125, v119, v119
	v_lshlrev_b32_e32 v190, 16, v191
	v_and_b32_e32 v191, 0xffff0000, v191
	v_lshlrev_b32_e32 v194, 16, v195
	v_and_b32_e32 v195, 0xffff0000, v195
	v_fmac_f32_e32 v117, v120, v120
	v_fmac_f32_e32 v125, v192, v192
	v_pk_add_f32 v[122:123], v[122:123], v[190:191]
	v_pk_add_f32 v[190:191], v[114:115], v[194:195]
	v_fmac_f32_e32 v117, v121, v121
	v_fmac_f32_e32 v125, v193, v193
	v_fmac_f32_e32 v117, v122, v122
	v_fmac_f32_e32 v125, v190, v190
	v_fmac_f32_e32 v117, v123, v123
	v_fmac_f32_e32 v125, v191, v191
	v_cvt_pk_bf16_f32 v114, v120, v121
	v_add_f32_e32 v120, v117, v125
	ds_bpermute_b32 v121, v183, v120
	v_cvt_pk_bf16_f32 v113, v126, v127
	v_cvt_pk_bf16_f32 v115, v122, v123
	global_store_dwordx4 v[198:199], v[112:115], off sc1
	v_cvt_pk_bf16_f32 v116, v188, v189
	v_cvt_pk_bf16_f32 v117, v118, v119
	s_waitcnt lgkmcnt(0)
	v_add_f32_e32 v112, v120, v121
	ds_bpermute_b32 v113, v184, v112
	v_add_co_u32_e32 v114, vcc, s55, v196
	v_cvt_pk_bf16_f32 v118, v192, v193
	v_cvt_pk_bf16_f32 v119, v190, v191
	v_addc_co_u32_e32 v115, vcc, 0, v197, vcc
	global_store_dwordx4 v[114:115], v[116:119], off offset:256 sc1
	s_and_saveexec_b64 s[22:23], s[2:3]
	s_cbranch_execz .LBB0_788
	s_waitcnt lgkmcnt(0)
	v_add_f32_e32 v114, v112, v113
	v_lshl_add_u64 v[112:113], v[166:167], 2, s[14:15]
	global_atomic_add_f32 v[112:113], v114, off
; DI u32x2 pk4(f32x4 v) { u32x2 r; r.x = pk2(v[0], v[1]); r.y = pk2(v[2], v[3]); return r; }
; DI float bf_lo(unsigned w) { return __uint_as_float(w << 16); }
; DI float bf_hi(unsigned w) { return __uint_as_float(w & 0xffff0000u); }
; #define COLS4 _Pragma("unroll") for (int bj = 0; bj < 2; ++bj) _Pragma("unroll") for (int n = 0; n < 2; ++n)
;     DI void operator()(const Acc& acc, const Unit& u, int wr, int wc, int fr, int fq) const {
;     ...
;             for (int ai = 0; ai < 2; ++ai) if (ai == 0 || !hf) {
;                 f32x4 xo[4][2][2];
; #pragma unroll
;                 for (int m = 0; m < 4; ++m) { const size_t o = (size_t)(row0 + ai * HALF + m * 16) * 2048 + colp;
;                     if (PH == 4) { COLS4 xo[m][bj][n] = *(const f32x4*)(p.x + o + bj * HALF + n * 4); }
;                     else {
; #pragma unroll
;                         for (int bj = 0; bj < 2; ++bj) { const u32x4 w = *(const u32x4*)(WSB(OFF_XB) + o + bj * HALF);
;                             xo[m][bj][0] = (f32x4){bf_lo(w.x), bf_hi(w.x), bf_lo(w.y), bf_hi(w.y)}; xo[m][bj][1] = (f32x4){bf_lo(w.z), bf_hi(w.z), bf_lo(w.w), bf_hi(w.w)}; } } }
; #pragma unroll
;                 for (int m = 0; m < 4; ++m) { const int r = row0 + ai * HALF + m * 16; const size_t o = (size_t)r * 2048 + colp; float part = 0.f;
; #pragma unroll
;                     for (int bj = 0; bj < 2; ++bj) { const f32x4 x0 = xo[m][bj][0] + acc[ai][bj][m][0], x1 = xo[m][bj][1] + acc[ai][bj][m][1];
;                         const u32x2 h0 = pk4(x0), h1 = pk4(x1);
;                         *(u32x4*)(WSB(OFF_XB) + o + bj * HALF) = (u32x4){h0.x, h0.y, h1.x, h1.y};
;                         part += x0[0] * x0[0] + x0[1] * x0[1] + x0[2] * x0[2] + x0[3] * x0[3] + x1[0] * x1[0] + x1[1] * x1[1] + x1[2] * x1[2] + x1[3] * x1[3]; }
;                     part += __shfl_xor(part, 16); part += __shfl_xor(part, 32);
;                     if (fq == 0) unsafeAtomicAdd(ssq + r, part);
;                 }
.LBB0_788:
	s_or_b64 exec, exec, s[22:23]
	v_lshlrev_b32_e32 v112, 16, v148
	s_waitcnt lgkmcnt(0)
	v_and_b32_e32 v113, 0xffff0000, v148
	v_lshlrev_b32_e32 v114, 16, v149
	v_and_b32_e32 v115, 0xffff0000, v149
	v_lshlrev_b32_e32 v116, 16, v150
	v_and_b32_e32 v117, 0xffff0000, v150
	v_lshlrev_b32_e32 v118, 16, v151
	v_and_b32_e32 v119, 0xffff0000, v151
	v_lshlrev_b32_e32 v120, 16, v144
	v_and_b32_e32 v121, 0xffff0000, v144
	v_pk_add_f32 v[110:111], v[110:111], v[114:115]
	v_pk_add_f32 v[108:109], v[108:109], v[112:113]
	v_pk_add_f32 v[112:113], v[106:107], v[118:119]
	v_pk_add_f32 v[114:115], v[104:105], v[116:117]
	v_lshl_add_u64 v[116:117], s[16:17], 0, v[178:179]
	v_lshlrev_b32_e32 v126, 16, v147
	v_and_b32_e32 v127, 0xffff0000, v147
	v_cvt_pk_bf16_f32 v104, v108, v109
	v_cvt_pk_bf16_f32 v105, v110, v111
	v_cvt_pk_bf16_f32 v106, v114, v115
	v_cvt_pk_bf16_f32 v107, v112, v113
	v_lshl_add_u64 v[116:117], v[116:117], 0, v[162:163]
	v_pk_add_f32 v[100:101], v[100:101], v[120:121]
	v_lshlrev_b32_e32 v122, 16, v145
	v_and_b32_e32 v123, 0xffff0000, v145
	global_store_dwordx4 v[116:117], v[104:107], off sc1
	v_pk_add_f32 v[102:103], v[102:103], v[122:123]
	v_lshlrev_b32_e32 v124, 16, v146
	v_mul_f32_e32 v106, v109, v109
	v_pk_add_f32 v[104:105], v[98:99], v[126:127]
	v_cvt_pk_bf16_f32 v98, v100, v101
	v_mul_f32_e32 v101, v101, v101
	v_fmac_f32_e32 v106, v108, v108
	v_fmac_f32_e32 v101, v100, v100
	v_and_b32_e32 v125, 0xffff0000, v146
	v_fmac_f32_e32 v106, v110, v110
	v_fmac_f32_e32 v101, v102, v102
	v_fmac_f32_e32 v106, v111, v111
	v_pk_add_f32 v[96:97], v[96:97], v[124:125]
	v_fmac_f32_e32 v101, v103, v103
	v_fmac_f32_e32 v106, v114, v114
	v_fmac_f32_e32 v101, v96, v96
	v_fmac_f32_e32 v106, v115, v115
	v_fmac_f32_e32 v101, v97, v97
	v_fmac_f32_e32 v106, v112, v112
	v_fmac_f32_e32 v101, v104, v104
	v_fmac_f32_e32 v106, v113, v113
	v_fmac_f32_e32 v101, v105, v105
	v_add_f32_e32 v106, v106, v101
	ds_bpermute_b32 v107, v183, v106
	v_cvt_pk_bf16_f32 v100, v96, v97
	v_lshl_add_u64 v[96:97], s[10:11], 0, v[178:179]
	v_cvt_pk_bf16_f32 v99, v102, v103
	v_lshl_add_u64 v[102:103], v[96:97], 0, v[162:163]
	s_waitcnt lgkmcnt(0)
	v_add_f32_e32 v96, v106, v107
	ds_bpermute_b32 v97, v184, v96
	v_add_co_u32_e32 v102, vcc, s55, v102
	v_cvt_pk_bf16_f32 v101, v104, v105
	s_nop 0
	v_addc_co_u32_e32 v103, vcc, 0, v103, vcc
	global_store_dwordx4 v[102:103], v[98:101], off offset:256 sc1
	s_and_saveexec_b64 s[22:23], s[2:3]
	s_cbranch_execz .LBB0_790
	s_waitcnt lgkmcnt(0)
	v_add_f32_e32 v98, v96, v97
	v_lshl_add_u64 v[96:97], v[176:177], 2, s[14:15]
	global_atomic_add_f32 v[96:97], v98, off
.LBB0_790:
	s_or_b64 exec, exec, s[22:23]
	v_lshlrev_b32_e32 v96, 16, v140
	s_waitcnt lgkmcnt(0)
	v_and_b32_e32 v97, 0xffff0000, v140
	v_lshlrev_b32_e32 v98, 16, v141
	v_and_b32_e32 v99, 0xffff0000, v141
	v_lshlrev_b32_e32 v100, 16, v142
	v_and_b32_e32 v101, 0xffff0000, v142
	v_lshlrev_b32_e32 v102, 16, v143
	v_and_b32_e32 v103, 0xffff0000, v143
	v_lshlrev_b32_e32 v104, 16, v136
	v_and_b32_e32 v105, 0xffff0000, v136
	v_pk_add_f32 v[94:95], v[94:95], v[98:99]
	v_pk_add_f32 v[92:93], v[92:93], v[96:97]
	v_pk_add_f32 v[96:97], v[90:91], v[102:103]
	v_pk_add_f32 v[98:99], v[88:89], v[100:101]
	v_lshl_add_u64 v[100:101], s[16:17], 0, v[174:175]
	v_lshlrev_b32_e32 v110, 16, v139
	v_and_b32_e32 v111, 0xffff0000, v139
	v_cvt_pk_bf16_f32 v88, v92, v93
	v_cvt_pk_bf16_f32 v89, v94, v95
	v_cvt_pk_bf16_f32 v90, v98, v99
	v_cvt_pk_bf16_f32 v91, v96, v97
	v_lshl_add_u64 v[100:101], v[100:101], 0, v[162:163]
	v_pk_add_f32 v[84:85], v[84:85], v[104:105]
	v_lshlrev_b32_e32 v106, 16, v137
	v_and_b32_e32 v107, 0xffff0000, v137
	global_store_dwordx4 v[100:101], v[88:91], off sc1
	v_pk_add_f32 v[86:87], v[86:87], v[106:107]
	v_lshlrev_b32_e32 v108, 16, v138
	v_mul_f32_e32 v90, v93, v93
	v_pk_add_f32 v[88:89], v[82:83], v[110:111]
	v_cvt_pk_bf16_f32 v82, v84, v85
	v_mul_f32_e32 v85, v85, v85
	v_fmac_f32_e32 v90, v92, v92
	v_fmac_f32_e32 v85, v84, v84
	v_and_b32_e32 v109, 0xffff0000, v138
	v_fmac_f32_e32 v90, v94, v94
	v_fmac_f32_e32 v85, v86, v86
	v_fmac_f32_e32 v90, v95, v95
	v_pk_add_f32 v[80:81], v[80:81], v[108:109]
	v_fmac_f32_e32 v85, v87, v87
	v_fmac_f32_e32 v90, v98, v98
	v_fmac_f32_e32 v85, v80, v80
	v_fmac_f32_e32 v90, v99, v99
	v_fmac_f32_e32 v85, v81, v81
	v_fmac_f32_e32 v90, v96, v96
	v_fmac_f32_e32 v85, v88, v88
	v_fmac_f32_e32 v90, v97, v97
	v_fmac_f32_e32 v85, v89, v89
	v_add_f32_e32 v90, v90, v85
	ds_bpermute_b32 v91, v183, v90
	v_cvt_pk_bf16_f32 v84, v80, v81
	v_lshl_add_u64 v[80:81], s[10:11], 0, v[174:175]
	v_cvt_pk_bf16_f32 v83, v86, v87
	v_lshl_add_u64 v[86:87], v[80:81], 0, v[162:163]
	s_waitcnt lgkmcnt(0)
	v_add_f32_e32 v80, v90, v91
	ds_bpermute_b32 v81, v184, v80
	v_add_co_u32_e32 v86, vcc, s55, v86
	v_cvt_pk_bf16_f32 v85, v88, v89
	s_nop 0
	v_addc_co_u32_e32 v87, vcc, 0, v87, vcc
	global_store_dwordx4 v[86:87], v[82:85], off offset:256 sc1
	s_and_saveexec_b64 s[22:23], s[2:3]
	s_cbranch_execz .LBB0_792
	s_waitcnt lgkmcnt(0)
	v_add_f32_e32 v82, v80, v81
	v_lshl_add_u64 v[80:81], v[172:173], 2, s[14:15]
	global_atomic_add_f32 v[80:81], v82, off
; DI u32x2 pk4(f32x4 v) { u32x2 r; r.x = pk2(v[0], v[1]); r.y = pk2(v[2], v[3]); return r; }
; DI float bf_lo(unsigned w) { return __uint_as_float(w << 16); }
; DI float bf_hi(unsigned w) { return __uint_as_float(w & 0xffff0000u); }
; #define COLS4 _Pragma("unroll") for (int bj = 0; bj < 2; ++bj) _Pragma("unroll") for (int n = 0; n < 2; ++n)
;     DI void operator()(const Acc& acc, const Unit& u, int wr, int wc, int fr, int fq) const {
;     ...
;             for (int ai = 0; ai < 2; ++ai) if (ai == 0 || !hf) {
;                 f32x4 xo[4][2][2];
; #pragma unroll
;                 for (int m = 0; m < 4; ++m) { const size_t o = (size_t)(row0 + ai * HALF + m * 16) * 2048 + colp;
;                     if (PH == 4) { COLS4 xo[m][bj][n] = *(const f32x4*)(p.x + o + bj * HALF + n * 4); }
;                     else {
; #pragma unroll
;                         for (int bj = 0; bj < 2; ++bj) { const u32x4 w = *(const u32x4*)(WSB(OFF_XB) + o + bj * HALF);
;                             xo[m][bj][0] = (f32x4){bf_lo(w.x), bf_hi(w.x), bf_lo(w.y), bf_hi(w.y)}; xo[m][bj][1] = (f32x4){bf_lo(w.z), bf_hi(w.z), bf_lo(w.w), bf_hi(w.w)}; } } }
; #pragma unroll
;                 for (int m = 0; m < 4; ++m) { const int r = row0 + ai * HALF + m * 16; const size_t o = (size_t)r * 2048 + colp; float part = 0.f;
; #pragma unroll
;                     for (int bj = 0; bj < 2; ++bj) { const f32x4 x0 = xo[m][bj][0] + acc[ai][bj][m][0], x1 = xo[m][bj][1] + acc[ai][bj][m][1];
;                         const u32x2 h0 = pk4(x0), h1 = pk4(x1);
;                         *(u32x4*)(WSB(OFF_XB) + o + bj * HALF) = (u32x4){h0.x, h0.y, h1.x, h1.y};
;                         part += x0[0] * x0[0] + x0[1] * x0[1] + x0[2] * x0[2] + x0[3] * x0[3] + x1[0] * x1[0] + x1[1] * x1[1] + x1[2] * x1[2] + x1[3] * x1[3]; }
;                     part += __shfl_xor(part, 16); part += __shfl_xor(part, 32);
;                     if (fq == 0) unsafeAtomicAdd(ssq + r, part);
;                 }
.LBB0_792:
	s_or_b64 exec, exec, s[22:23]
	v_lshlrev_b32_e32 v80, 16, v132
	s_waitcnt lgkmcnt(0)
	v_and_b32_e32 v81, 0xffff0000, v132
	v_lshlrev_b32_e32 v82, 16, v133
	v_and_b32_e32 v83, 0xffff0000, v133
	v_lshlrev_b32_e32 v84, 16, v134
	v_and_b32_e32 v85, 0xffff0000, v134
	v_lshlrev_b32_e32 v86, 16, v135
	v_and_b32_e32 v87, 0xffff0000, v135
	v_lshlrev_b32_e32 v88, 16, v128
	v_and_b32_e32 v89, 0xffff0000, v128
	v_pk_add_f32 v[78:79], v[78:79], v[82:83]
	v_pk_add_f32 v[76:77], v[76:77], v[80:81]
	v_pk_add_f32 v[80:81], v[74:75], v[86:87]
	v_pk_add_f32 v[82:83], v[72:73], v[84:85]
	v_lshl_add_u64 v[84:85], s[16:17], 0, v[170:171]
	v_lshlrev_b32_e32 v94, 16, v131
	v_and_b32_e32 v95, 0xffff0000, v131
	v_cvt_pk_bf16_f32 v72, v76, v77
	v_cvt_pk_bf16_f32 v73, v78, v79
	v_cvt_pk_bf16_f32 v74, v82, v83
	v_cvt_pk_bf16_f32 v75, v80, v81
	v_lshl_add_u64 v[84:85], v[84:85], 0, v[162:163]
	v_pk_add_f32 v[68:69], v[68:69], v[88:89]
	v_lshlrev_b32_e32 v90, 16, v129
	v_and_b32_e32 v91, 0xffff0000, v129
	global_store_dwordx4 v[84:85], v[72:75], off sc1
	v_pk_add_f32 v[70:71], v[70:71], v[90:91]
	v_lshlrev_b32_e32 v92, 16, v130
	v_mul_f32_e32 v74, v77, v77
	v_pk_add_f32 v[72:73], v[66:67], v[94:95]
	v_cvt_pk_bf16_f32 v66, v68, v69
	v_mul_f32_e32 v69, v69, v69
	v_fmac_f32_e32 v74, v76, v76
	v_fmac_f32_e32 v69, v68, v68
	v_and_b32_e32 v93, 0xffff0000, v130
	v_fmac_f32_e32 v74, v78, v78
	v_fmac_f32_e32 v69, v70, v70
	v_fmac_f32_e32 v74, v79, v79
	v_pk_add_f32 v[64:65], v[64:65], v[92:93]
	v_fmac_f32_e32 v69, v71, v71
	v_fmac_f32_e32 v74, v82, v82
	v_fmac_f32_e32 v69, v64, v64
	v_fmac_f32_e32 v74, v83, v83
	v_fmac_f32_e32 v69, v65, v65
	v_fmac_f32_e32 v74, v80, v80
	v_fmac_f32_e32 v69, v72, v72
	v_fmac_f32_e32 v74, v81, v81
	v_fmac_f32_e32 v69, v73, v73
	v_add_f32_e32 v74, v74, v69
	ds_bpermute_b32 v75, v183, v74
	v_cvt_pk_bf16_f32 v68, v64, v65
	v_lshl_add_u64 v[64:65], s[10:11], 0, v[170:171]
	v_cvt_pk_bf16_f32 v67, v70, v71
	v_lshl_add_u64 v[70:71], v[64:65], 0, v[162:163]
	s_waitcnt lgkmcnt(0)
	v_add_f32_e32 v64, v74, v75
	ds_bpermute_b32 v65, v184, v64
	v_add_co_u32_e32 v70, vcc, s55, v70
	v_cvt_pk_bf16_f32 v69, v72, v73
	s_nop 0
	v_addc_co_u32_e32 v71, vcc, 0, v71, vcc
	global_store_dwordx4 v[70:71], v[66:69], off offset:256 sc1
	s_and_saveexec_b64 s[22:23], s[2:3]
	s_cbranch_execz .LBB0_794
	s_waitcnt lgkmcnt(0)
	v_add_f32_e32 v66, v64, v65
	v_lshl_add_u64 v[64:65], v[168:169], 2, s[14:15]
	global_atomic_add_f32 v[64:65], v66, off
.LBB0_794:
	s_or_b64 exec, exec, s[22:23]
	v_add_u32_e32 v100, 0x80, v166
	v_ashrrev_i32_e32 v101, 31, v100
	v_lshlrev_b64 v[110:111], 12, v[100:101]
	s_waitcnt lgkmcnt(0)
	v_lshl_add_u64 v[64:65], v[164:165], 0, v[110:111]
	global_load_dwordx4 v[102:105], v[64:65], off
	global_load_dwordx4 v[106:109], v[64:65], off offset:256
	v_add_u32_e32 v96, 0x90, v166
	v_add_u32_e32 v92, 0xa0, v166
	v_add_u32_e32 v88, 0xb0, v166
	v_ashrrev_i32_e32 v97, 31, v96
	v_ashrrev_i32_e32 v93, 31, v92
	v_ashrrev_i32_e32 v89, 31, v88
	v_lshlrev_b64 v[98:99], 12, v[96:97]
	v_lshlrev_b64 v[94:95], 12, v[92:93]
	v_lshlrev_b64 v[90:91], 12, v[88:89]
	v_lshl_add_u64 v[64:65], v[164:165], 0, v[98:99]
	v_lshl_add_u64 v[66:67], v[164:165], 0, v[94:95]
	v_lshl_add_u64 v[112:113], v[164:165], 0, v[90:91]
	global_load_dwordx4 v[84:87], v[64:65], off
	global_load_dwordx4 v[80:83], v[64:65], off offset:256
	global_load_dwordx4 v[76:79], v[66:67], off
	global_load_dwordx4 v[72:75], v[66:67], off offset:256
	global_load_dwordx4 v[68:71], v[112:113], off
	s_nop 0
	global_load_dwordx4 v[64:67], v[112:113], off offset:256
	v_lshl_add_u64 v[112:113], s[16:17], 0, v[110:111]
	v_lshl_add_u64 v[112:113], v[112:113], 0, v[162:163]
	v_lshl_add_u64 v[110:111], s[10:11], 0, v[110:111]
	v_lshl_add_u64 v[110:111], v[110:111], 0, v[162:163]
	s_waitcnt vmcnt(7)
	v_lshlrev_b32_e32 v114, 16, v102
	v_and_b32_e32 v115, 0xffff0000, v102
	v_lshlrev_b32_e32 v102, 16, v103
	v_and_b32_e32 v103, 0xffff0000, v103
	s_waitcnt vmcnt(6)
	v_lshlrev_b32_e32 v118, 16, v106
	v_and_b32_e32 v119, 0xffff0000, v106
	v_lshlrev_b32_e32 v106, 16, v107
	v_and_b32_e32 v107, 0xffff0000, v107
	v_lshlrev_b32_e32 v120, 16, v108
	v_and_b32_e32 v121, 0xffff0000, v108
	v_pk_add_f32 v[62:63], v[62:63], v[102:103]
	v_pk_add_f32 v[60:61], v[60:61], v[114:115]
	v_pk_add_f32 v[102:103], v[52:53], v[118:119]
	v_pk_add_f32 v[54:55], v[54:55], v[106:107]
	v_pk_add_f32 v[106:107], v[48:49], v[120:121]
	v_cvt_pk_bf16_f32 v48, v60, v61
	v_mul_f32_e32 v53, v61, v61
	v_mul_f32_e32 v61, v103, v103
	v_fmac_f32_e32 v53, v60, v60
	v_fmac_f32_e32 v61, v102, v102
	v_lshlrev_b32_e32 v116, 16, v104
	v_and_b32_e32 v117, 0xffff0000, v104
	v_fmac_f32_e32 v53, v62, v62
	v_fmac_f32_e32 v61, v54, v54
	v_pk_add_f32 v[56:57], v[56:57], v[116:117]
	v_fmac_f32_e32 v53, v63, v63
	v_fmac_f32_e32 v61, v55, v55
	v_lshlrev_b32_e32 v104, 16, v105
	v_and_b32_e32 v105, 0xffff0000, v105
	v_lshlrev_b32_e32 v108, 16, v109
	v_and_b32_e32 v109, 0xffff0000, v109
	v_fmac_f32_e32 v53, v56, v56
	v_fmac_f32_e32 v61, v106, v106
	v_pk_add_f32 v[58:59], v[58:59], v[104:105]
	v_pk_add_f32 v[104:105], v[50:51], v[108:109]
	v_fmac_f32_e32 v53, v57, v57
	v_fmac_f32_e32 v61, v107, v107
	v_fmac_f32_e32 v53, v58, v58
	v_fmac_f32_e32 v61, v104, v104
	v_fmac_f32_e32 v53, v59, v59
	v_fmac_f32_e32 v61, v105, v105
	v_cvt_pk_bf16_f32 v50, v56, v57
	v_add_f32_e32 v56, v53, v61
	ds_bpermute_b32 v57, v183, v56
	v_cvt_pk_bf16_f32 v49, v62, v63
	v_cvt_pk_bf16_f32 v51, v58, v59
	global_store_dwordx4 v[112:113], v[48:51], off sc1
	v_cvt_pk_bf16_f32 v52, v102, v103
	v_cvt_pk_bf16_f32 v53, v54, v55
	s_waitcnt lgkmcnt(0)
	v_add_f32_e32 v48, v56, v57
	ds_bpermute_b32 v49, v184, v48
	v_add_co_u32_e32 v50, vcc, s55, v110
	v_cvt_pk_bf16_f32 v54, v106, v107
	v_cvt_pk_bf16_f32 v55, v104, v105
	v_addc_co_u32_e32 v51, vcc, 0, v111, vcc
	global_store_dwordx4 v[50:51], v[52:55], off offset:256 sc1
	s_and_saveexec_b64 s[22:23], s[2:3]
	s_cbranch_execz .LBB0_796
	s_waitcnt lgkmcnt(0)
	v_add_f32_e32 v50, v48, v49
	v_lshl_add_u64 v[48:49], v[100:101], 2, s[14:15]
	global_atomic_add_f32 v[48:49], v50, off
; DI u32x2 pk4(f32x4 v) { u32x2 r; r.x = pk2(v[0], v[1]); r.y = pk2(v[2], v[3]); return r; }
; DI float bf_lo(unsigned w) { return __uint_as_float(w << 16); }
; DI float bf_hi(unsigned w) { return __uint_as_float(w & 0xffff0000u); }
; #define COLS4 _Pragma("unroll") for (int bj = 0; bj < 2; ++bj) _Pragma("unroll") for (int n = 0; n < 2; ++n)
;     DI void operator()(const Acc& acc, const Unit& u, int wr, int wc, int fr, int fq) const {
;     ...
;             for (int ai = 0; ai < 2; ++ai) if (ai == 0 || !hf) {
;                 f32x4 xo[4][2][2];
; #pragma unroll
;                 for (int m = 0; m < 4; ++m) { const size_t o = (size_t)(row0 + ai * HALF + m * 16) * 2048 + colp;
;                     if (PH == 4) { COLS4 xo[m][bj][n] = *(const f32x4*)(p.x + o + bj * HALF + n * 4); }
;                     else {
; #pragma unroll
;                         for (int bj = 0; bj < 2; ++bj) { const u32x4 w = *(const u32x4*)(WSB(OFF_XB) + o + bj * HALF);
;                             xo[m][bj][0] = (f32x4){bf_lo(w.x), bf_hi(w.x), bf_lo(w.y), bf_hi(w.y)}; xo[m][bj][1] = (f32x4){bf_lo(w.z), bf_hi(w.z), bf_lo(w.w), bf_hi(w.w)}; } } }
; #pragma unroll
;                 for (int m = 0; m < 4; ++m) { const int r = row0 + ai * HALF + m * 16; const size_t o = (size_t)r * 2048 + colp; float part = 0.f;
; #pragma unroll
;                     for (int bj = 0; bj < 2; ++bj) { const f32x4 x0 = xo[m][bj][0] + acc[ai][bj][m][0], x1 = xo[m][bj][1] + acc[ai][bj][m][1];
;                         const u32x2 h0 = pk4(x0), h1 = pk4(x1);
;                         *(u32x4*)(WSB(OFF_XB) + o + bj * HALF) = (u32x4){h0.x, h0.y, h1.x, h1.y};
;                         part += x0[0] * x0[0] + x0[1] * x0[1] + x0[2] * x0[2] + x0[3] * x0[3] + x1[0] * x1[0] + x1[1] * x1[1] + x1[2] * x1[2] + x1[3] * x1[3]; }
;                     part += __shfl_xor(part, 16); part += __shfl_xor(part, 32);
;                     if (fq == 0) unsafeAtomicAdd(ssq + r, part);
;                 }
.LBB0_796:
	s_or_b64 exec, exec, s[22:23]
	s_waitcnt vmcnt(7)
	v_lshlrev_b32_e32 v48, 16, v84
	s_waitcnt lgkmcnt(0)
	v_and_b32_e32 v49, 0xffff0000, v84
	v_lshlrev_b32_e32 v50, 16, v85
	v_and_b32_e32 v51, 0xffff0000, v85
	v_lshlrev_b32_e32 v52, 16, v86
	v_and_b32_e32 v53, 0xffff0000, v86
	v_lshlrev_b32_e32 v54, 16, v87
	v_and_b32_e32 v55, 0xffff0000, v87
	s_waitcnt vmcnt(6)
	v_lshlrev_b32_e32 v56, 16, v80
	v_and_b32_e32 v57, 0xffff0000, v80
	v_pk_add_f32 v[46:47], v[46:47], v[50:51]
	v_pk_add_f32 v[44:45], v[44:45], v[48:49]
	v_pk_add_f32 v[48:49], v[42:43], v[54:55]
	v_pk_add_f32 v[50:51], v[40:41], v[52:53]
	v_lshl_add_u64 v[52:53], s[16:17], 0, v[98:99]
	v_lshlrev_b32_e32 v62, 16, v83
	v_and_b32_e32 v63, 0xffff0000, v83
	v_cvt_pk_bf16_f32 v40, v44, v45
	v_cvt_pk_bf16_f32 v41, v46, v47
	v_cvt_pk_bf16_f32 v42, v50, v51
	v_cvt_pk_bf16_f32 v43, v48, v49
	v_lshl_add_u64 v[52:53], v[52:53], 0, v[162:163]
	v_pk_add_f32 v[36:37], v[36:37], v[56:57]
	v_lshlrev_b32_e32 v58, 16, v81
	v_and_b32_e32 v59, 0xffff0000, v81
	global_store_dwordx4 v[52:53], v[40:43], off sc1
	v_pk_add_f32 v[38:39], v[38:39], v[58:59]
	v_lshlrev_b32_e32 v60, 16, v82
	v_mul_f32_e32 v42, v45, v45
	v_pk_add_f32 v[40:41], v[34:35], v[62:63]
	v_cvt_pk_bf16_f32 v34, v36, v37
	v_mul_f32_e32 v37, v37, v37
	v_fmac_f32_e32 v42, v44, v44
	v_fmac_f32_e32 v37, v36, v36
	v_and_b32_e32 v61, 0xffff0000, v82
	v_fmac_f32_e32 v42, v46, v46
	v_fmac_f32_e32 v37, v38, v38
	v_fmac_f32_e32 v42, v47, v47
	v_pk_add_f32 v[32:33], v[32:33], v[60:61]
	v_fmac_f32_e32 v37, v39, v39
	v_fmac_f32_e32 v42, v50, v50
	v_fmac_f32_e32 v37, v32, v32
	v_fmac_f32_e32 v42, v51, v51
	v_fmac_f32_e32 v37, v33, v33
	v_fmac_f32_e32 v42, v48, v48
	v_fmac_f32_e32 v37, v40, v40
	v_fmac_f32_e32 v42, v49, v49
	v_fmac_f32_e32 v37, v41, v41
	v_add_f32_e32 v42, v42, v37
	ds_bpermute_b32 v43, v183, v42
	v_cvt_pk_bf16_f32 v36, v32, v33
	v_lshl_add_u64 v[32:33], s[10:11], 0, v[98:99]
	v_cvt_pk_bf16_f32 v35, v38, v39
	v_lshl_add_u64 v[38:39], v[32:33], 0, v[162:163]
	s_waitcnt lgkmcnt(0)
	v_add_f32_e32 v32, v42, v43
	ds_bpermute_b32 v33, v184, v32
	v_add_co_u32_e32 v38, vcc, s55, v38
	v_cvt_pk_bf16_f32 v37, v40, v41
	s_nop 0
	v_addc_co_u32_e32 v39, vcc, 0, v39, vcc
	global_store_dwordx4 v[38:39], v[34:37], off offset:256 sc1
	s_and_saveexec_b64 s[22:23], s[2:3]
	s_cbranch_execz .LBB0_798
	s_waitcnt lgkmcnt(0)
	v_add_f32_e32 v34, v32, v33
	v_lshl_add_u64 v[32:33], v[96:97], 2, s[14:15]
	global_atomic_add_f32 v[32:33], v34, off
; DI u32x2 pk4(f32x4 v) { u32x2 r; r.x = pk2(v[0], v[1]); r.y = pk2(v[2], v[3]); return r; }
; DI float bf_lo(unsigned w) { return __uint_as_float(w << 16); }
; DI float bf_hi(unsigned w) { return __uint_as_float(w & 0xffff0000u); }
; #define COLS4 _Pragma("unroll") for (int bj = 0; bj < 2; ++bj) _Pragma("unroll") for (int n = 0; n < 2; ++n)
;     DI void operator()(const Acc& acc, const Unit& u, int wr, int wc, int fr, int fq) const {
;     ...
;             for (int ai = 0; ai < 2; ++ai) if (ai == 0 || !hf) {
;                 f32x4 xo[4][2][2];
; #pragma unroll
;                 for (int m = 0; m < 4; ++m) { const size_t o = (size_t)(row0 + ai * HALF + m * 16) * 2048 + colp;
;                     if (PH == 4) { COLS4 xo[m][bj][n] = *(const f32x4*)(p.x + o + bj * HALF + n * 4); }
;                     else {
; #pragma unroll
;                         for (int bj = 0; bj < 2; ++bj) { const u32x4 w = *(const u32x4*)(WSB(OFF_XB) + o + bj * HALF);
;                             xo[m][bj][0] = (f32x4){bf_lo(w.x), bf_hi(w.x), bf_lo(w.y), bf_hi(w.y)}; xo[m][bj][1] = (f32x4){bf_lo(w.z), bf_hi(w.z), bf_lo(w.w), bf_hi(w.w)}; } } }
; #pragma unroll
;                 for (int m = 0; m < 4; ++m) { const int r = row0 + ai * HALF + m * 16; const size_t o = (size_t)r * 2048 + colp; float part = 0.f;
; #pragma unroll
;                     for (int bj = 0; bj < 2; ++bj) { const f32x4 x0 = xo[m][bj][0] + acc[ai][bj][m][0], x1 = xo[m][bj][1] + acc[ai][bj][m][1];
;                         const u32x2 h0 = pk4(x0), h1 = pk4(x1);
;                         *(u32x4*)(WSB(OFF_XB) + o + bj * HALF) = (u32x4){h0.x, h0.y, h1.x, h1.y};
;                         part += x0[0] * x0[0] + x0[1] * x0[1] + x0[2] * x0[2] + x0[3] * x0[3] + x1[0] * x1[0] + x1[1] * x1[1] + x1[2] * x1[2] + x1[3] * x1[3]; }
;                     part += __shfl_xor(part, 16); part += __shfl_xor(part, 32);
;                     if (fq == 0) unsafeAtomicAdd(ssq + r, part);
;                 }
.LBB0_798:
	s_or_b64 exec, exec, s[22:23]
	s_waitcnt vmcnt(7)
	v_lshlrev_b32_e32 v32, 16, v76
	s_waitcnt lgkmcnt(0)
	v_and_b32_e32 v33, 0xffff0000, v76
	v_lshlrev_b32_e32 v34, 16, v77
	v_and_b32_e32 v35, 0xffff0000, v77
	v_lshlrev_b32_e32 v36, 16, v78
	v_and_b32_e32 v37, 0xffff0000, v78
	v_lshlrev_b32_e32 v38, 16, v79
	v_and_b32_e32 v39, 0xffff0000, v79
	s_waitcnt vmcnt(6)
	v_lshlrev_b32_e32 v40, 16, v72
	v_and_b32_e32 v41, 0xffff0000, v72
	v_pk_add_f32 v[30:31], v[30:31], v[34:35]
	v_pk_add_f32 v[28:29], v[28:29], v[32:33]
	v_pk_add_f32 v[32:33], v[26:27], v[38:39]
	v_pk_add_f32 v[34:35], v[24:25], v[36:37]
	v_lshl_add_u64 v[36:37], s[16:17], 0, v[94:95]
	v_lshlrev_b32_e32 v46, 16, v75
	v_and_b32_e32 v47, 0xffff0000, v75
	v_cvt_pk_bf16_f32 v24, v28, v29
	v_cvt_pk_bf16_f32 v25, v30, v31
	v_cvt_pk_bf16_f32 v26, v34, v35
	v_cvt_pk_bf16_f32 v27, v32, v33
	v_lshl_add_u64 v[36:37], v[36:37], 0, v[162:163]
	v_pk_add_f32 v[20:21], v[20:21], v[40:41]
	v_lshlrev_b32_e32 v42, 16, v73
	v_and_b32_e32 v43, 0xffff0000, v73
	global_store_dwordx4 v[36:37], v[24:27], off sc1
	v_pk_add_f32 v[22:23], v[22:23], v[42:43]
	v_lshlrev_b32_e32 v44, 16, v74
	v_mul_f32_e32 v26, v29, v29
	v_pk_add_f32 v[24:25], v[18:19], v[46:47]
	v_cvt_pk_bf16_f32 v18, v20, v21
	v_mul_f32_e32 v21, v21, v21
	v_fmac_f32_e32 v26, v28, v28
	v_fmac_f32_e32 v21, v20, v20
	v_and_b32_e32 v45, 0xffff0000, v74
	v_fmac_f32_e32 v26, v30, v30
	v_fmac_f32_e32 v21, v22, v22
	v_fmac_f32_e32 v26, v31, v31
	v_pk_add_f32 v[16:17], v[16:17], v[44:45]
	v_fmac_f32_e32 v21, v23, v23
	v_fmac_f32_e32 v26, v34, v34
	v_fmac_f32_e32 v21, v16, v16
	v_fmac_f32_e32 v26, v35, v35
	v_fmac_f32_e32 v21, v17, v17
	v_fmac_f32_e32 v26, v32, v32
	v_fmac_f32_e32 v21, v24, v24
	v_fmac_f32_e32 v26, v33, v33
	v_fmac_f32_e32 v21, v25, v25
	v_add_f32_e32 v26, v26, v21
	ds_bpermute_b32 v27, v183, v26
	v_cvt_pk_bf16_f32 v20, v16, v17
	v_lshl_add_u64 v[16:17], s[10:11], 0, v[94:95]
	v_cvt_pk_bf16_f32 v19, v22, v23
	v_lshl_add_u64 v[22:23], v[16:17], 0, v[162:163]
	s_waitcnt lgkmcnt(0)
	v_add_f32_e32 v16, v26, v27
	ds_bpermute_b32 v17, v184, v16
	v_add_co_u32_e32 v22, vcc, s55, v22
	v_cvt_pk_bf16_f32 v21, v24, v25
	s_nop 0
	v_addc_co_u32_e32 v23, vcc, 0, v23, vcc
	global_store_dwordx4 v[22:23], v[18:21], off offset:256 sc1
	s_and_saveexec_b64 s[22:23], s[2:3]
	s_cbranch_execz .LBB0_800
	s_waitcnt lgkmcnt(0)
	v_add_f32_e32 v18, v16, v17
	v_lshl_add_u64 v[16:17], v[92:93], 2, s[14:15]
	global_atomic_add_f32 v[16:17], v18, off
.LBB0_800:
	s_or_b64 exec, exec, s[22:23]
	s_waitcnt vmcnt(7)
	v_lshlrev_b32_e32 v16, 16, v68
	s_waitcnt lgkmcnt(0)
	v_and_b32_e32 v17, 0xffff0000, v68
	v_lshlrev_b32_e32 v18, 16, v69
	v_and_b32_e32 v19, 0xffff0000, v69
	v_lshlrev_b32_e32 v20, 16, v70
	v_and_b32_e32 v21, 0xffff0000, v70
	v_lshlrev_b32_e32 v22, 16, v71
	v_and_b32_e32 v23, 0xffff0000, v71
	s_waitcnt vmcnt(6)
	v_lshlrev_b32_e32 v24, 16, v64
	v_and_b32_e32 v25, 0xffff0000, v64
	v_pk_add_f32 v[14:15], v[14:15], v[18:19]
	v_pk_add_f32 v[12:13], v[12:13], v[16:17]
	v_pk_add_f32 v[16:17], v[10:11], v[22:23]
	v_pk_add_f32 v[18:19], v[8:9], v[20:21]
	v_lshl_add_u64 v[20:21], s[16:17], 0, v[90:91]
	v_lshlrev_b32_e32 v30, 16, v67
	v_and_b32_e32 v31, 0xffff0000, v67
	v_cvt_pk_bf16_f32 v8, v12, v13
	v_cvt_pk_bf16_f32 v9, v14, v15
	v_cvt_pk_bf16_f32 v10, v18, v19
	v_cvt_pk_bf16_f32 v11, v16, v17
	v_lshl_add_u64 v[20:21], v[20:21], 0, v[162:163]
	v_pk_add_f32 v[4:5], v[4:5], v[24:25]
	v_lshlrev_b32_e32 v26, 16, v65
	v_and_b32_e32 v27, 0xffff0000, v65
	global_store_dwordx4 v[20:21], v[8:11], off sc1
	v_pk_add_f32 v[6:7], v[6:7], v[26:27]
	v_lshlrev_b32_e32 v28, 16, v66
	v_mul_f32_e32 v10, v13, v13
	v_pk_add_f32 v[8:9], v[2:3], v[30:31]
	v_cvt_pk_bf16_f32 v2, v4, v5
	v_mul_f32_e32 v5, v5, v5
	v_fmac_f32_e32 v10, v12, v12
	v_fmac_f32_e32 v5, v4, v4
	v_and_b32_e32 v29, 0xffff0000, v66
	v_fmac_f32_e32 v10, v14, v14
	v_fmac_f32_e32 v5, v6, v6
	v_fmac_f32_e32 v10, v15, v15
	v_pk_add_f32 v[0:1], v[0:1], v[28:29]
	v_fmac_f32_e32 v5, v7, v7
	v_fmac_f32_e32 v10, v18, v18
	v_fmac_f32_e32 v5, v0, v0
	v_fmac_f32_e32 v10, v19, v19
	v_fmac_f32_e32 v5, v1, v1
	v_fmac_f32_e32 v10, v16, v16
	v_fmac_f32_e32 v5, v8, v8
	v_fmac_f32_e32 v10, v17, v17
	v_fmac_f32_e32 v5, v9, v9
	v_add_f32_e32 v10, v10, v5
	ds_bpermute_b32 v11, v183, v10
	v_cvt_pk_bf16_f32 v4, v0, v1
	v_lshl_add_u64 v[0:1], s[10:11], 0, v[90:91]
	v_cvt_pk_bf16_f32 v3, v6, v7
	v_lshl_add_u64 v[6:7], v[0:1], 0, v[162:163]
	s_waitcnt lgkmcnt(0)
	v_add_f32_e32 v0, v10, v11
	ds_bpermute_b32 v1, v184, v0
	v_add_co_u32_e32 v6, vcc, s55, v6
	v_cvt_pk_bf16_f32 v5, v8, v9
	s_nop 0
	v_addc_co_u32_e32 v7, vcc, 0, v7, vcc
	global_store_dwordx4 v[6:7], v[2:5], off offset:256 sc1
	s_and_saveexec_b64 s[22:23], s[2:3]
	s_cbranch_execz .LBB0_777
	s_waitcnt lgkmcnt(0)
	v_add_f32_e32 v2, v0, v1
	v_lshl_add_u64 v[0:1], v[88:89], 2, s[14:15]
	global_atomic_add_f32 v[0:1], v2, off
	s_branch .LBB0_777

; #define PG8_STAGE(bufoff, gbase, voff) do { _Pragma("unroll") for (int _i = 0; _i < 2; ++_i) \
;         __builtin_amdgcn_global_load_lds((const unsigned*)((const char*)(gbase) + (voff)[_i]), (LAS unsigned*)(lds + (bufoff) + ldsw + _i * 8192), 16, 0, 0); } while (0)
; #define PG8_LDA(dst, b, h) do { _Pragma("unroll") for (int m = 0; m < 4; ++m) _Pragma("unroll") for (int k = 0; k < 2; ++k) dst[m][k] = *(const LAS bf16x8*)(lds + PG8_SA(b, h) + aoff + m * 2048 + k * 1024); } while (0)
; #define PG8_LDB(dst, b, h) do { _Pragma("unroll") for (int n = 0; n < 2; ++n) _Pragma("unroll") for (int k = 0; k < 2; ++k) dst[n][k] = *(const LAS bf16x8*)(lds + PG8_SB(b, h) + boff + n * 2048 + k * 1024); } while (0)
; #define PG8_WAIT_V(n) asm volatile("s_waitcnt vmcnt(" #n ")" ::: "memory")
; #define PG8_WAIT_L(n) asm volatile("s_waitcnt lgkmcnt(" #n ")" ::: "memory")
; #define PG8_BAR __builtin_amdgcn_s_barrier()
; #define PG8_SCHED __builtin_amdgcn_sched_barrier(0)
; template <class Epi>
; DI void gemm_phase(LAS unsigned char* lds, int wid, int K, int lda, int ldb, bool bperm, const Sched3& S, const Epi& E) {
;     ...
;             PG8_LDB(B0, 0, 0); PG8_SCHED; PG8_LDA(At, 0, 0); PG8_STAGE(PG8_SA(1, 1), a1 + hA, voffA);
;             PG8_WAIT_L(8); PG8_BAR; PG8_WAIT_L(0); PG8_MMA(0, 0, At, B0); PG8_BAR; PG8_SCHED;
;             PG8_LDB(B1, 0, 1); PG8_STAGE(PG8_SB(0, 0), b2, voffB);
;             PG8_BAR; PG8_WAIT_L(0); PG8_MMA(0, 1, At, B1); PG8_BAR;
;             PG8_LDA(At, 0, 1); PG8_STAGE(PG8_SA(0, 0), a2, voffA);
;             PG8_BAR; PG8_WAIT_L(0); if (full) PG8_MMA(1, 0, At, B0); PG8_BAR; PG8_SCHED;
;             PG8_STAGE(PG8_SB(0, 1), b2 + hstepB, voffB);
;             PG8_WAIT_V(6); PG8_BAR; if (full) PG8_MMA(1, 1, At, B1); PG8_BAR;
;             PG8_LDB(B0, 1, 0); PG8_SCHED; PG8_LDA(At, 1, 0); PG8_STAGE(PG8_SA(0, 1), a2 + h2, voffA);
;             PG8_WAIT_L(8); PG8_BAR; PG8_WAIT_L(0); PG8_MMA(0, 0, At, B0); PG8_BAR; PG8_SCHED;
;             PG8_LDB(B1, 1, 1); PG8_STAGE(PG8_SB(1, 0), b3, voffB);
;             PG8_BAR; PG8_WAIT_L(0); PG8_MMA(0, 1, At, B1); PG8_BAR;
;             PG8_LDA(At, 1, 1); PG8_STAGE(PG8_SA(1, 0), a3, voffA);
;             PG8_BAR; PG8_WAIT_L(0); if (full) PG8_MMA(1, 0, At, B0); PG8_BAR; PG8_SCHED;
;             PG8_STAGE(PG8_SB(1, 1), b3 + hstepB, voffB);
;             PG8_WAIT_V(6); PG8_BAR; if (full) PG8_MMA(1, 1, At, B1); PG8_BAR;
.LBB0_1176:
	ds_read_b128 v[128:131], v185
	ds_read_b128 v[132:135], v185 offset:1024
	ds_read_b128 v[136:139], v185 offset:2048
	ds_read_b128 v[140:143], v185 offset:3072
	s_add_u32 s38, s36, 0xfff80080
	s_addc_u32 s39, s37, -1
	s_cmp_eq_u32 s27, 28
	s_cselect_b32 s41, s29, s39
	s_cselect_b32 s40, s28, s38
	s_cselect_b32 s39, s31, s21
	s_cselect_b32 s38, s30, s19
	v_lshl_add_u64 v[178:179], s[36:37], 0, v[156:157]
	s_add_i32 m0, s48, 0xc000
	ds_read_b128 v[144:147], v186
	ds_read_b128 v[148:151], v186 offset:1024
	ds_read_b128 v[162:165], v186 offset:2048
	ds_read_b128 v[166:169], v186 offset:3072
	ds_read_b128 v[170:173], v186 offset:4096
	ds_read_b128 v[174:177], v186 offset:5120
	ds_read_b128 v[188:191], v186 offset:6144
	ds_read_b128 v[192:195], v186 offset:7168
	global_load_lds_dwordx4 v[178:179], off
	v_lshl_add_u64 v[178:179], s[36:37], 0, v[158:159]
	s_add_i32 m0, s48, 0xe000
	s_nop 0
	global_load_lds_dwordx4 v[178:179], off
	s_waitcnt lgkmcnt(8)
	s_barrier
	s_waitcnt lgkmcnt(0)
	s_setprio 1
	s_waitcnt lgkmcnt(0)
	v_mfma_f32_16x16x32_bf16 v[124:127], v[128:131], v[144:147], v[124:127]
	v_mfma_f32_16x16x32_bf16 v[120:123], v[136:139], v[144:147], v[120:123]
	v_mfma_f32_16x16x32_bf16 v[108:111], v[128:131], v[162:165], v[108:111]
	v_mfma_f32_16x16x32_bf16 v[104:107], v[136:139], v[162:165], v[104:107]
	v_mfma_f32_16x16x32_bf16 v[92:95], v[128:131], v[170:173], v[92:95]
	v_mfma_f32_16x16x32_bf16 v[88:91], v[136:139], v[170:173], v[88:91]
	v_mfma_f32_16x16x32_bf16 v[76:79], v[128:131], v[188:191], v[76:79]
	v_mfma_f32_16x16x32_bf16 v[72:75], v[136:139], v[188:191], v[72:75]
	v_mfma_f32_16x16x32_bf16 v[124:127], v[132:135], v[148:151], v[124:127]
	v_mfma_f32_16x16x32_bf16 v[120:123], v[140:143], v[148:151], v[120:123]
	v_mfma_f32_16x16x32_bf16 v[108:111], v[132:135], v[166:169], v[108:111]
	v_mfma_f32_16x16x32_bf16 v[104:107], v[140:143], v[166:169], v[104:107]
	v_mfma_f32_16x16x32_bf16 v[92:95], v[132:135], v[174:177], v[92:95]
	v_mfma_f32_16x16x32_bf16 v[88:91], v[140:143], v[174:177], v[88:91]
	v_mfma_f32_16x16x32_bf16 v[76:79], v[132:135], v[192:195], v[76:79]
	v_mfma_f32_16x16x32_bf16 v[72:75], v[140:143], v[192:195], v[72:75]
	s_setprio 0
	s_barrier
	s_add_i32 s61, s57, s47
	v_lshl_add_u64 v[178:179], s[38:39], 0, v[152:153]
	s_mov_b32 m0, s61
	ds_read_b128 v[196:199], v187
	ds_read_b128 v[200:203], v187 offset:1024
	ds_read_b128 v[204:207], v187 offset:2048
	ds_read_b128 v[208:211], v187 offset:3072
	global_load_lds_dwordx4 v[178:179], off
	v_lshl_add_u64 v[212:213], s[38:39], 0, v[154:155]
	s_add_i32 m0, s61, 0x2000
	s_nop 0
	global_load_lds_dwordx4 v[212:213], off
	s_barrier
	s_waitcnt lgkmcnt(0)
	s_setprio 1
	s_waitcnt lgkmcnt(0)
	v_mfma_f32_16x16x32_bf16 v[116:119], v[196:199], v[144:147], v[116:119]
	v_mfma_f32_16x16x32_bf16 v[112:115], v[204:207], v[144:147], v[112:115]
	v_mfma_f32_16x16x32_bf16 v[100:103], v[196:199], v[162:165], v[100:103]
	v_mfma_f32_16x16x32_bf16 v[96:99], v[204:207], v[162:165], v[96:99]
	v_mfma_f32_16x16x32_bf16 v[84:87], v[196:199], v[170:173], v[84:87]
	v_mfma_f32_16x16x32_bf16 v[80:83], v[204:207], v[170:173], v[80:83]
	v_mfma_f32_16x16x32_bf16 v[68:71], v[196:199], v[188:191], v[68:71]
	v_mfma_f32_16x16x32_bf16 v[64:67], v[204:207], v[188:191], v[64:67]
	v_mfma_f32_16x16x32_bf16 v[116:119], v[200:203], v[148:151], v[116:119]
	v_mfma_f32_16x16x32_bf16 v[112:115], v[208:211], v[148:151], v[112:115]
	v_mfma_f32_16x16x32_bf16 v[100:103], v[200:203], v[166:169], v[100:103]
	v_mfma_f32_16x16x32_bf16 v[96:99], v[208:211], v[166:169], v[96:99]
	v_mfma_f32_16x16x32_bf16 v[84:87], v[200:203], v[174:177], v[84:87]
	v_mfma_f32_16x16x32_bf16 v[80:83], v[208:211], v[174:177], v[80:83]
	v_mfma_f32_16x16x32_bf16 v[68:71], v[200:203], v[192:195], v[68:71]
	v_mfma_f32_16x16x32_bf16 v[64:67], v[208:211], v[192:195], v[64:67]
	s_setprio 0
	s_mov_b32 m0, s48
	v_lshl_add_u64 v[214:215], s[40:41], 0, v[152:153]
	s_barrier
	ds_read_b128 v[144:147], v186 offset:16384
	ds_read_b128 v[148:151], v186 offset:17408
	ds_read_b128 v[162:165], v186 offset:18432
	ds_read_b128 v[166:169], v186 offset:19456
	ds_read_b128 v[170:173], v186 offset:20480
	ds_read_b128 v[174:177], v186 offset:21504
	ds_read_b128 v[188:191], v186 offset:22528
	ds_read_b128 v[192:195], v186 offset:23552
	global_load_lds_dwordx4 v[214:215], off
	v_lshl_add_u64 v[216:217], s[40:41], 0, v[154:155]
	s_mov_b32 m0, s49
	s_nop 0
	global_load_lds_dwordx4 v[216:217], off
	s_barrier
	s_waitcnt lgkmcnt(0)
	s_setprio 1
	s_waitcnt lgkmcnt(0)
	v_mfma_f32_16x16x32_bf16 v[60:63], v[128:131], v[144:147], v[60:63]
	v_mfma_f32_16x16x32_bf16 v[56:59], v[136:139], v[144:147], v[56:59]
	v_mfma_f32_16x16x32_bf16 v[44:47], v[128:131], v[162:165], v[44:47]
	v_mfma_f32_16x16x32_bf16 v[40:43], v[136:139], v[162:165], v[40:43]
	v_mfma_f32_16x16x32_bf16 v[28:31], v[128:131], v[170:173], v[28:31]
	v_mfma_f32_16x16x32_bf16 v[24:27], v[136:139], v[170:173], v[24:27]
	v_mfma_f32_16x16x32_bf16 v[12:15], v[128:131], v[188:191], v[12:15]
	v_mfma_f32_16x16x32_bf16 v[8:11], v[136:139], v[188:191], v[8:11]
	v_mfma_f32_16x16x32_bf16 v[60:63], v[132:135], v[148:151], v[60:63]
	v_mfma_f32_16x16x32_bf16 v[56:59], v[140:143], v[148:151], v[56:59]
	v_mfma_f32_16x16x32_bf16 v[44:47], v[132:135], v[166:169], v[44:47]
	v_mfma_f32_16x16x32_bf16 v[40:43], v[140:143], v[166:169], v[40:43]
	v_mfma_f32_16x16x32_bf16 v[28:31], v[132:135], v[174:177], v[28:31]
	v_mfma_f32_16x16x32_bf16 v[24:27], v[140:143], v[174:177], v[24:27]
	v_mfma_f32_16x16x32_bf16 v[12:15], v[132:135], v[192:195], v[12:15]
	v_mfma_f32_16x16x32_bf16 v[8:11], v[140:143], v[192:195], v[8:11]
	s_setprio 0
	s_barrier
; #define PG8_STAGE(bufoff, gbase, voff) do { _Pragma("unroll") for (int _i = 0; _i < 2; ++_i) \
;         __builtin_amdgcn_global_load_lds((const unsigned*)((const char*)(gbase) + (voff)[_i]), (LAS unsigned*)(lds + (bufoff) + ldsw + _i * 8192), 16, 0, 0); } while (0)
; #define PG8_LDA(dst, b, h) do { _Pragma("unroll") for (int m = 0; m < 4; ++m) _Pragma("unroll") for (int k = 0; k < 2; ++k) dst[m][k] = *(const LAS bf16x8*)(lds + PG8_SA(b, h) + aoff + m * 2048 + k * 1024); } while (0)
; #define PG8_LDB(dst, b, h) do { _Pragma("unroll") for (int n = 0; n < 2; ++n) _Pragma("unroll") for (int k = 0; k < 2; ++k) dst[n][k] = *(const LAS bf16x8*)(lds + PG8_SB(b, h) + boff + n * 2048 + k * 1024); } while (0)
; #define PG8_WAIT_V(n) asm volatile("s_waitcnt vmcnt(" #n ")" ::: "memory")
; #define PG8_WAIT_L(n) asm volatile("s_waitcnt lgkmcnt(" #n ")" ::: "memory")
; #define PG8_BAR __builtin_amdgcn_s_barrier()
; #define PG8_SCHED __builtin_amdgcn_sched_barrier(0)
; template <class Epi>
; DI void gemm_phase(LAS unsigned char* lds, int wid, int K, int lda, int ldb, bool bperm, const Sched3& S, const Epi& E) {
;     ...
;             PG8_LDB(B0, 0, 0); PG8_SCHED; PG8_LDA(At, 0, 0); PG8_STAGE(PG8_SA(1, 1), a1 + hA, voffA);
;             PG8_WAIT_L(8); PG8_BAR; PG8_WAIT_L(0); PG8_MMA(0, 0, At, B0); PG8_BAR; PG8_SCHED;
;             PG8_LDB(B1, 0, 1); PG8_STAGE(PG8_SB(0, 0), b2, voffB);
;             PG8_BAR; PG8_WAIT_L(0); PG8_MMA(0, 1, At, B1); PG8_BAR;
;             PG8_LDA(At, 0, 1); PG8_STAGE(PG8_SA(0, 0), a2, voffA);
;             PG8_BAR; PG8_WAIT_L(0); if (full) PG8_MMA(1, 0, At, B0); PG8_BAR; PG8_SCHED;
;             PG8_STAGE(PG8_SB(0, 1), b2 + hstepB, voffB);
;             PG8_WAIT_V(6); PG8_BAR; if (full) PG8_MMA(1, 1, At, B1); PG8_BAR;
;             PG8_LDB(B0, 1, 0); PG8_SCHED; PG8_LDA(At, 1, 0); PG8_STAGE(PG8_SA(0, 1), a2 + h2, voffA);
;             PG8_WAIT_L(8); PG8_BAR; PG8_WAIT_L(0); PG8_MMA(0, 0, At, B0); PG8_BAR; PG8_SCHED;
;             PG8_LDB(B1, 1, 1); PG8_STAGE(PG8_SB(1, 0), b3, voffB);
;             PG8_BAR; PG8_WAIT_L(0); PG8_MMA(0, 1, At, B1); PG8_BAR;
;             PG8_LDA(At, 1, 1); PG8_STAGE(PG8_SA(1, 0), a3, voffA);
;             PG8_BAR; PG8_WAIT_L(0); if (full) PG8_MMA(1, 0, At, B0); PG8_BAR; PG8_SCHED;
;             PG8_STAGE(PG8_SB(1, 1), b3 + hstepB, voffB);
;             PG8_WAIT_V(6); PG8_BAR; if (full) PG8_MMA(1, 1, At, B1); PG8_BAR;
	s_add_u32 s62, s38, 0x80000
	s_addc_u32 s63, s39, 0
	s_add_i32 s61, s58, s47
	v_lshl_add_u64 v[128:129], s[62:63], 0, v[152:153]
	s_mov_b32 m0, s61
	s_nop 0
	global_load_lds_dwordx4 v[128:129], off
	v_lshl_add_u64 v[128:129], s[62:63], 0, v[154:155]
	s_add_i32 m0, s61, 0x2000
	s_nop 0
	global_load_lds_dwordx4 v[128:129], off
	s_waitcnt vmcnt(6)
	s_barrier
	s_setprio 1
	v_mfma_f32_16x16x32_bf16 v[52:55], v[196:199], v[144:147], v[52:55]
	v_mfma_f32_16x16x32_bf16 v[48:51], v[204:207], v[144:147], v[48:51]
	v_mfma_f32_16x16x32_bf16 v[36:39], v[196:199], v[162:165], v[36:39]
	v_mfma_f32_16x16x32_bf16 v[32:35], v[204:207], v[162:165], v[32:35]
	v_mfma_f32_16x16x32_bf16 v[20:23], v[196:199], v[170:173], v[20:23]
	v_mfma_f32_16x16x32_bf16 v[16:19], v[204:207], v[170:173], v[16:19]
	v_mfma_f32_16x16x32_bf16 v[4:7], v[196:199], v[188:191], v[4:7]
	v_mfma_f32_16x16x32_bf16 v[0:3], v[204:207], v[188:191], v[0:3]
	v_mfma_f32_16x16x32_bf16 v[52:55], v[200:203], v[148:151], v[52:55]
	v_mfma_f32_16x16x32_bf16 v[48:51], v[208:211], v[148:151], v[48:51]
	v_mfma_f32_16x16x32_bf16 v[36:39], v[200:203], v[166:169], v[36:39]
	v_mfma_f32_16x16x32_bf16 v[32:35], v[208:211], v[166:169], v[32:35]
	v_mfma_f32_16x16x32_bf16 v[20:23], v[200:203], v[174:177], v[20:23]
	v_mfma_f32_16x16x32_bf16 v[16:19], v[208:211], v[174:177], v[16:19]
	v_mfma_f32_16x16x32_bf16 v[4:7], v[200:203], v[192:195], v[4:7]
	v_mfma_f32_16x16x32_bf16 v[0:3], v[208:211], v[192:195], v[0:3]
	s_setprio 0
	s_add_i32 s61, 0, 0x18000
	v_add_u32_e32 v140, s61, v181
	s_barrier
	ds_read_b128 v[128:131], v140
	ds_read_b128 v[132:135], v140 offset:1024
	ds_read_b128 v[136:139], v140 offset:2048
	ds_read_b128 v[140:143], v140 offset:3072
	s_add_u32 s40, s40, 0x80000
	s_addc_u32 s41, s41, 0
	s_mov_b32 m0, s50
	v_lshl_add_u64 v[196:197], s[40:41], 0, v[152:153]
	ds_read_b128 v[144:147], v186 offset:32768
	ds_read_b128 v[148:151], v186 offset:33792
	ds_read_b128 v[162:165], v186 offset:34816
	ds_read_b128 v[166:169], v186 offset:35840
	ds_read_b128 v[170:173], v186 offset:36864
	ds_read_b128 v[174:177], v186 offset:37888
	ds_read_b128 v[188:191], v186 offset:38912
	ds_read_b128 v[192:195], v186 offset:39936
	global_load_lds_dwordx4 v[196:197], off
	v_lshl_add_u64 v[196:197], s[40:41], 0, v[154:155]
	s_mov_b32 m0, s51
	s_nop 0
	global_load_lds_dwordx4 v[196:197], off
	s_waitcnt lgkmcnt(8)
	s_barrier
	s_waitcnt lgkmcnt(0)
	s_setprio 1
	s_waitcnt lgkmcnt(0)
	v_mfma_f32_16x16x32_bf16 v[124:127], v[128:131], v[144:147], v[124:127]
	v_mfma_f32_16x16x32_bf16 v[120:123], v[136:139], v[144:147], v[120:123]
	v_mfma_f32_16x16x32_bf16 v[108:111], v[128:131], v[162:165], v[108:111]
	v_mfma_f32_16x16x32_bf16 v[104:107], v[136:139], v[162:165], v[104:107]
	v_mfma_f32_16x16x32_bf16 v[92:95], v[128:131], v[170:173], v[92:95]
	v_mfma_f32_16x16x32_bf16 v[88:91], v[136:139], v[170:173], v[88:91]
	v_mfma_f32_16x16x32_bf16 v[76:79], v[128:131], v[188:191], v[76:79]
	v_mfma_f32_16x16x32_bf16 v[72:75], v[136:139], v[188:191], v[72:75]
	v_mfma_f32_16x16x32_bf16 v[124:127], v[132:135], v[148:151], v[124:127]
	v_mfma_f32_16x16x32_bf16 v[120:123], v[140:143], v[148:151], v[120:123]
	v_mfma_f32_16x16x32_bf16 v[108:111], v[132:135], v[166:169], v[108:111]
	v_mfma_f32_16x16x32_bf16 v[104:107], v[140:143], v[166:169], v[104:107]
	v_mfma_f32_16x16x32_bf16 v[92:95], v[132:135], v[174:177], v[92:95]
	v_mfma_f32_16x16x32_bf16 v[88:91], v[140:143], v[174:177], v[88:91]
	v_mfma_f32_16x16x32_bf16 v[76:79], v[132:135], v[192:195], v[76:79]
	v_mfma_f32_16x16x32_bf16 v[72:75], v[140:143], v[192:195], v[72:75]
	s_setprio 0
	s_barrier
	s_add_i32 s40, 0, 0x1c000
	s_add_i32 s41, s61, s47
	v_add_u32_e32 v208, s40, v181
	v_lshl_add_u64 v[178:179], v[178:179], 0, s[12:13]
	s_mov_b32 m0, s41
	ds_read_b128 v[196:199], v208
	ds_read_b128 v[200:203], v208 offset:1024
	ds_read_b128 v[204:207], v208 offset:2048
	ds_read_b128 v[208:211], v208 offset:3072
	global_load_lds_dwordx4 v[178:179], off
	v_lshl_add_u64 v[178:179], v[212:213], 0, s[12:13]
	s_add_i32 m0, s41, 0x2000
	s_nop 0
	global_load_lds_dwordx4 v[178:179], off
	s_barrier
	s_waitcnt lgkmcnt(0)
	s_setprio 1
	s_waitcnt lgkmcnt(0)
	v_mfma_f32_16x16x32_bf16 v[116:119], v[196:199], v[144:147], v[116:119]
	v_mfma_f32_16x16x32_bf16 v[112:115], v[204:207], v[144:147], v[112:115]
	v_mfma_f32_16x16x32_bf16 v[100:103], v[196:199], v[162:165], v[100:103]
	v_mfma_f32_16x16x32_bf16 v[96:99], v[204:207], v[162:165], v[96:99]
	v_mfma_f32_16x16x32_bf16 v[84:87], v[196:199], v[170:173], v[84:87]
	v_mfma_f32_16x16x32_bf16 v[80:83], v[204:207], v[170:173], v[80:83]
	v_mfma_f32_16x16x32_bf16 v[68:71], v[196:199], v[188:191], v[68:71]
	v_mfma_f32_16x16x32_bf16 v[64:67], v[204:207], v[188:191], v[64:67]
	v_mfma_f32_16x16x32_bf16 v[116:119], v[200:203], v[148:151], v[116:119]
	v_mfma_f32_16x16x32_bf16 v[112:115], v[208:211], v[148:151], v[112:115]
	v_mfma_f32_16x16x32_bf16 v[100:103], v[200:203], v[166:169], v[100:103]
	v_mfma_f32_16x16x32_bf16 v[96:99], v[208:211], v[166:169], v[96:99]
	v_mfma_f32_16x16x32_bf16 v[84:87], v[200:203], v[174:177], v[84:87]
	v_mfma_f32_16x16x32_bf16 v[80:83], v[208:211], v[174:177], v[80:83]
	v_mfma_f32_16x16x32_bf16 v[68:71], v[200:203], v[192:195], v[68:71]
	v_mfma_f32_16x16x32_bf16 v[64:67], v[208:211], v[192:195], v[64:67]
	s_setprio 0
	s_mov_b32 m0, s53
	v_lshl_add_u64 v[178:179], v[214:215], 0, s[12:13]
	s_barrier
	ds_read_b128 v[144:147], v186 offset:49152
	ds_read_b128 v[148:151], v186 offset:50176
	ds_read_b128 v[162:165], v186 offset:51200
	ds_read_b128 v[166:169], v186 offset:52224
	ds_read_b128 v[170:173], v186 offset:53248
	ds_read_b128 v[174:177], v186 offset:54272
	ds_read_b128 v[188:191], v186 offset:55296
	ds_read_b128 v[192:195], v186 offset:56320
	global_load_lds_dwordx4 v[178:179], off
	v_lshl_add_u64 v[178:179], v[216:217], 0, s[12:13]
	s_mov_b32 m0, s54
	s_nop 0
	global_load_lds_dwordx4 v[178:179], off
	s_barrier
; template <class Epi>
; DI void gemm_phase(LAS unsigned char* lds, int wid, int K, int lda, int ldb, bool bperm, const Sched3& S, const Epi& E) {
;     ...
;             PG8_WAIT_V(6); PG8_BAR; if (full) PG8_MMA(1, 1, At, B1); PG8_BAR;
;             PG8_LDB(B0, 1, 0); PG8_SCHED; PG8_LDA(At, 1, 0); PG8_STAGE(PG8_SA(0, 1), a2 + h2, voffA);
;             PG8_WAIT_L(8); PG8_BAR; PG8_WAIT_L(0); PG8_MMA(0, 0, At, B0); PG8_BAR; PG8_SCHED;
;             PG8_LDB(B1, 1, 1); PG8_STAGE(PG8_SB(1, 0), b3, voffB);
;             PG8_BAR; PG8_WAIT_L(0); PG8_MMA(0, 1, At, B1); PG8_BAR;
;             PG8_LDA(At, 1, 1); PG8_STAGE(PG8_SA(1, 0), a3, voffA);
;             PG8_BAR; PG8_WAIT_L(0); if (full) PG8_MMA(1, 0, At, B0); PG8_BAR; PG8_SCHED;
;             PG8_STAGE(PG8_SB(1, 1), b3 + hstepB, voffB);
;             PG8_WAIT_V(6); PG8_BAR; if (full) PG8_MMA(1, 1, At, B1); PG8_BAR;
;     DI void operator()(const Acc& acc, const Unit& u, int wr, int wc, int fr, int fq) const {
;     ...
;             for (int ai = 0; ai < 2; ++ai) if (ai == 0 || !hf) {
;                 f32x4 xo[4][2][2];
; #pragma unroll
;                 for (int m = 0; m < 4; ++m) { const size_t o = (size_t)(row0 + ai * HALF + m * 16) * 2048 + colp;
;                     if (PH == 4) { COLS4 xo[m][bj][n] = *(const f32x4*)(p.x + o + bj * HALF + n * 4); }
;                     else {
; #pragma unroll
;                         for (int bj = 0; bj < 2; ++bj) { const u32x4 w = *(const u32x4*)(WSB(OFF_XB) + o + bj * HALF);
;                             xo[m][bj][0] = (f32x4){bf_lo(w.x), bf_hi(w.x), bf_lo(w.y), bf_hi(w.y)}; xo[m][bj][1] = (f32x4){bf_lo(w.z), bf_hi(w.z), bf_lo(w.w), bf_hi(w.w)}; } } }
; #pragma unroll
;                 for (int m = 0; m < 4; ++m) { const int r = row0 + ai * HALF + m * 16; const size_t o = (size_t)r * 2048 + colp; float part = 0.f;
; #pragma unroll
;                     for (int bj = 0; bj < 2; ++bj) { const f32x4 x0 = xo[m][bj][0] + acc[ai][bj][m][0], x1 = xo[m][bj][1] + acc[ai][bj][m][1];
;                         const u32x2 h0 = pk4(x0), h1 = pk4(x1);
;                         *(u32x4*)(WSB(OFF_XB) + o + bj * HALF) = (u32x4){h0.x, h0.y, h1.x, h1.y};
;                         part += x0[0] * x0[0] + x0[1] * x0[1] + x0[2] * x0[2] + x0[3] * x0[3] + x1[0] * x1[0] + x1[1] * x1[1] + x1[2] * x1[2] + x1[3] * x1[3]; }
;                     part += __shfl_xor(part, 16); part += __shfl_xor(part, 32);
	s_waitcnt lgkmcnt(0)
	s_setprio 1
	s_waitcnt lgkmcnt(0)
	v_mfma_f32_16x16x32_bf16 v[60:63], v[128:131], v[144:147], v[60:63]
	v_mfma_f32_16x16x32_bf16 v[56:59], v[136:139], v[144:147], v[56:59]
	v_mfma_f32_16x16x32_bf16 v[44:47], v[128:131], v[162:165], v[44:47]
	v_mfma_f32_16x16x32_bf16 v[40:43], v[136:139], v[162:165], v[40:43]
	v_mfma_f32_16x16x32_bf16 v[28:31], v[128:131], v[170:173], v[28:31]
	v_mfma_f32_16x16x32_bf16 v[24:27], v[136:139], v[170:173], v[24:27]
	v_mfma_f32_16x16x32_bf16 v[12:15], v[128:131], v[188:191], v[12:15]
	v_mfma_f32_16x16x32_bf16 v[8:11], v[136:139], v[188:191], v[8:11]
	v_mfma_f32_16x16x32_bf16 v[60:63], v[132:135], v[148:151], v[60:63]
	v_mfma_f32_16x16x32_bf16 v[56:59], v[140:143], v[148:151], v[56:59]
	v_mfma_f32_16x16x32_bf16 v[44:47], v[132:135], v[166:169], v[44:47]
	v_mfma_f32_16x16x32_bf16 v[40:43], v[140:143], v[166:169], v[40:43]
	v_mfma_f32_16x16x32_bf16 v[28:31], v[132:135], v[174:177], v[28:31]
	v_mfma_f32_16x16x32_bf16 v[24:27], v[140:143], v[174:177], v[24:27]
	v_mfma_f32_16x16x32_bf16 v[12:15], v[132:135], v[192:195], v[12:15]
	v_mfma_f32_16x16x32_bf16 v[8:11], v[140:143], v[192:195], v[8:11]
	s_setprio 0
	s_barrier
	s_add_u32 s38, s38, 0x80080
	s_addc_u32 s39, s39, 0
	s_add_i32 s40, s40, s47
	v_lshl_add_u64 v[128:129], s[38:39], 0, v[152:153]
	s_mov_b32 m0, s40
	s_nop 0
	global_load_lds_dwordx4 v[128:129], off
	v_lshl_add_u64 v[128:129], s[38:39], 0, v[154:155]
	s_add_i32 m0, s40, 0x2000
	s_nop 0
	global_load_lds_dwordx4 v[128:129], off
	s_waitcnt vmcnt(6)
	s_barrier
	s_setprio 1
	v_mfma_f32_16x16x32_bf16 v[52:55], v[196:199], v[144:147], v[52:55]
	v_mfma_f32_16x16x32_bf16 v[48:51], v[204:207], v[144:147], v[48:51]
	v_mfma_f32_16x16x32_bf16 v[36:39], v[196:199], v[162:165], v[36:39]
	v_mfma_f32_16x16x32_bf16 v[32:35], v[204:207], v[162:165], v[32:35]
	v_mfma_f32_16x16x32_bf16 v[20:23], v[196:199], v[170:173], v[20:23]
	v_mfma_f32_16x16x32_bf16 v[16:19], v[204:207], v[170:173], v[16:19]
	v_mfma_f32_16x16x32_bf16 v[4:7], v[196:199], v[188:191], v[4:7]
	v_mfma_f32_16x16x32_bf16 v[0:3], v[204:207], v[188:191], v[0:3]
	v_mfma_f32_16x16x32_bf16 v[52:55], v[200:203], v[148:151], v[52:55]
	v_mfma_f32_16x16x32_bf16 v[48:51], v[208:211], v[148:151], v[48:51]
	v_mfma_f32_16x16x32_bf16 v[36:39], v[200:203], v[166:169], v[36:39]
	v_mfma_f32_16x16x32_bf16 v[32:35], v[208:211], v[166:169], v[32:35]
	v_mfma_f32_16x16x32_bf16 v[20:23], v[200:203], v[174:177], v[20:23]
	v_mfma_f32_16x16x32_bf16 v[16:19], v[208:211], v[174:177], v[16:19]
	v_mfma_f32_16x16x32_bf16 v[4:7], v[200:203], v[192:195], v[4:7]
	v_mfma_f32_16x16x32_bf16 v[0:3], v[208:211], v[192:195], v[0:3]
	s_setprio 0
	s_add_i32 s27, s27, 2
	s_add_u32 s36, s36, 0x100
	s_addc_u32 s37, s37, 0
	s_add_u32 s19, s19, 0x100
	s_addc_u32 s21, s21, 0
	s_cmp_gt_u32 s27, 29
	s_barrier
	s_cbranch_scc0 .LBB0_1176
	v_lshl_add_u32 v128, s60, 8, v182
	v_lshl_add_u32 v166, s26, 8, v180
	v_ashrrev_i32_e32 v129, 31, v128
	v_lshlrev_b64 v[162:163], 1, v[128:129]
	v_ashrrev_i32_e32 v167, 31, v166
	v_lshl_add_u64 v[164:165], s[16:17], 0, v[162:163]
	v_lshlrev_b64 v[196:197], 12, v[166:167]
	v_lshl_add_u64 v[128:129], v[164:165], 0, v[196:197]
	global_load_dwordx4 v[188:191], v[128:129], off
	global_load_dwordx4 v[192:195], v[128:129], off offset:256
	v_or_b32_e32 v176, 16, v166
	v_or_b32_e32 v172, 32, v166
	v_or_b32_e32 v168, 48, v166
	v_ashrrev_i32_e32 v177, 31, v176
	v_ashrrev_i32_e32 v173, 31, v172
	v_ashrrev_i32_e32 v169, 31, v168
	v_lshlrev_b64 v[178:179], 12, v[176:177]
	v_lshlrev_b64 v[174:175], 12, v[172:173]
	v_lshlrev_b64 v[170:171], 12, v[168:169]
	v_lshl_add_u64 v[128:129], v[164:165], 0, v[178:179]
	v_lshl_add_u64 v[130:131], v[164:165], 0, v[174:175]
	v_lshl_add_u64 v[198:199], v[164:165], 0, v[170:171]
	global_load_dwordx4 v[148:151], v[128:129], off
	global_load_dwordx4 v[144:147], v[128:129], off offset:256
	global_load_dwordx4 v[140:143], v[130:131], off
	global_load_dwordx4 v[136:139], v[130:131], off offset:256
	global_load_dwordx4 v[132:135], v[198:199], off
	s_nop 0
	global_load_dwordx4 v[128:131], v[198:199], off offset:256
	v_lshl_add_u64 v[198:199], s[16:17], 0, v[196:197]
	v_lshl_add_u64 v[198:199], v[198:199], 0, v[162:163]
	v_lshl_add_u64 v[196:197], s[10:11], 0, v[196:197]
	v_lshl_add_u64 v[196:197], v[196:197], 0, v[162:163]
	s_waitcnt vmcnt(0)
	v_lshlrev_b32_e32 v200, 16, v188
	v_and_b32_e32 v201, 0xffff0000, v188
	v_lshlrev_b32_e32 v188, 16, v189
	v_and_b32_e32 v189, 0xffff0000, v189
	v_lshlrev_b32_e32 v204, 16, v192
	v_and_b32_e32 v205, 0xffff0000, v192
	v_lshlrev_b32_e32 v192, 16, v193
	v_and_b32_e32 v193, 0xffff0000, v193
	v_lshlrev_b32_e32 v206, 16, v194
	v_and_b32_e32 v207, 0xffff0000, v194
	v_pk_add_f32 v[126:127], v[126:127], v[188:189]
	v_pk_add_f32 v[124:125], v[124:125], v[200:201]
	v_pk_add_f32 v[188:189], v[116:117], v[204:205]
	v_pk_add_f32 v[118:119], v[118:119], v[192:193]
	v_pk_add_f32 v[192:193], v[112:113], v[206:207]
	v_cvt_pk_bf16_f32 v112, v124, v125
	v_mul_f32_e32 v117, v125, v125
	v_mul_f32_e32 v125, v189, v189
	v_fmac_f32_e32 v117, v124, v124
	v_fmac_f32_e32 v125, v188, v188
	v_lshlrev_b32_e32 v202, 16, v190
	v_and_b32_e32 v203, 0xffff0000, v190
	v_fmac_f32_e32 v117, v126, v126
	v_fmac_f32_e32 v125, v118, v118
	v_pk_add_f32 v[120:121], v[120:121], v[202:203]
	v_fmac_f32_e32 v117, v127, v127
	v_fmac_f32_e32 v125, v119, v119
	v_lshlrev_b32_e32 v190, 16, v191
	v_and_b32_e32 v191, 0xffff0000, v191
	v_lshlrev_b32_e32 v194, 16, v195
	v_and_b32_e32 v195, 0xffff0000, v195
	v_fmac_f32_e32 v117, v120, v120
	v_fmac_f32_e32 v125, v192, v192
	v_pk_add_f32 v[122:123], v[122:123], v[190:191]
	v_pk_add_f32 v[190:191], v[114:115], v[194:195]
	v_fmac_f32_e32 v117, v121, v121
	v_fmac_f32_e32 v125, v193, v193
	v_fmac_f32_e32 v117, v122, v122
	v_fmac_f32_e32 v125, v190, v190
	v_fmac_f32_e32 v117, v123, v123
	v_fmac_f32_e32 v125, v191, v191
	v_cvt_pk_bf16_f32 v114, v120, v121
	v_add_f32_e32 v120, v117, v125
	ds_bpermute_b32 v121, v183, v120
	v_cvt_pk_bf16_f32 v113, v126, v127
	v_cvt_pk_bf16_f32 v115, v122, v123
	global_store_dwordx4 v[198:199], v[112:115], off sc1
	v_cvt_pk_bf16_f32 v116, v188, v189
	v_cvt_pk_bf16_f32 v117, v118, v119
	s_waitcnt lgkmcnt(0)
	v_add_f32_e32 v112, v120, v121
	ds_bpermute_b32 v113, v184, v112
	v_add_co_u32_e32 v114, vcc, s59, v196
	v_cvt_pk_bf16_f32 v118, v192, v193
	v_cvt_pk_bf16_f32 v119, v190, v191
	v_addc_co_u32_e32 v115, vcc, 0, v197, vcc
	global_store_dwordx4 v[114:115], v[116:119], off offset:256 sc1
	s_and_saveexec_b64 s[26:27], s[2:3]
	s_cbranch_execz .LBB0_1179
	s_waitcnt lgkmcnt(0)
	v_add_f32_e32 v114, v112, v113
	v_lshl_add_u64 v[112:113], v[166:167], 2, s[14:15]
	global_atomic_add_f32 v[112:113], v114, off
; DI u32x2 pk4(f32x4 v) { u32x2 r; r.x = pk2(v[0], v[1]); r.y = pk2(v[2], v[3]); return r; }
; DI float bf_lo(unsigned w) { return __uint_as_float(w << 16); }
; DI float bf_hi(unsigned w) { return __uint_as_float(w & 0xffff0000u); }
; #define COLS4 _Pragma("unroll") for (int bj = 0; bj < 2; ++bj) _Pragma("unroll") for (int n = 0; n < 2; ++n)
;     DI void operator()(const Acc& acc, const Unit& u, int wr, int wc, int fr, int fq) const {
;     ...
;             for (int ai = 0; ai < 2; ++ai) if (ai == 0 || !hf) {
;                 f32x4 xo[4][2][2];
; #pragma unroll
;                 for (int m = 0; m < 4; ++m) { const size_t o = (size_t)(row0 + ai * HALF + m * 16) * 2048 + colp;
;                     if (PH == 4) { COLS4 xo[m][bj][n] = *(const f32x4*)(p.x + o + bj * HALF + n * 4); }
;                     else {
; #pragma unroll
;                         for (int bj = 0; bj < 2; ++bj) { const u32x4 w = *(const u32x4*)(WSB(OFF_XB) + o + bj * HALF);
;                             xo[m][bj][0] = (f32x4){bf_lo(w.x), bf_hi(w.x), bf_lo(w.y), bf_hi(w.y)}; xo[m][bj][1] = (f32x4){bf_lo(w.z), bf_hi(w.z), bf_lo(w.w), bf_hi(w.w)}; } } }
; #pragma unroll
;                 for (int m = 0; m < 4; ++m) { const int r = row0 + ai * HALF + m * 16; const size_t o = (size_t)r * 2048 + colp; float part = 0.f;
; #pragma unroll
;                     for (int bj = 0; bj < 2; ++bj) { const f32x4 x0 = xo[m][bj][0] + acc[ai][bj][m][0], x1 = xo[m][bj][1] + acc[ai][bj][m][1];
;                         const u32x2 h0 = pk4(x0), h1 = pk4(x1);
;                         *(u32x4*)(WSB(OFF_XB) + o + bj * HALF) = (u32x4){h0.x, h0.y, h1.x, h1.y};
;                         part += x0[0] * x0[0] + x0[1] * x0[1] + x0[2] * x0[2] + x0[3] * x0[3] + x1[0] * x1[0] + x1[1] * x1[1] + x1[2] * x1[2] + x1[3] * x1[3]; }
;                     part += __shfl_xor(part, 16); part += __shfl_xor(part, 32);
;                     if (fq == 0) unsafeAtomicAdd(ssq + r, part);
;                 }
.LBB0_1179:
	s_or_b64 exec, exec, s[26:27]
	v_lshlrev_b32_e32 v112, 16, v148
	s_waitcnt lgkmcnt(0)
	v_and_b32_e32 v113, 0xffff0000, v148
	v_lshlrev_b32_e32 v114, 16, v149
	v_and_b32_e32 v115, 0xffff0000, v149
	v_lshlrev_b32_e32 v116, 16, v150
	v_and_b32_e32 v117, 0xffff0000, v150
	v_lshlrev_b32_e32 v118, 16, v151
	v_and_b32_e32 v119, 0xffff0000, v151
	v_lshlrev_b32_e32 v120, 16, v144
	v_and_b32_e32 v121, 0xffff0000, v144
	v_pk_add_f32 v[110:111], v[110:111], v[114:115]
	v_pk_add_f32 v[108:109], v[108:109], v[112:113]
	v_pk_add_f32 v[112:113], v[106:107], v[118:119]
	v_pk_add_f32 v[114:115], v[104:105], v[116:117]
	v_lshl_add_u64 v[116:117], s[16:17], 0, v[178:179]
	v_lshlrev_b32_e32 v126, 16, v147
	v_and_b32_e32 v127, 0xffff0000, v147
	v_cvt_pk_bf16_f32 v104, v108, v109
	v_cvt_pk_bf16_f32 v105, v110, v111
	v_cvt_pk_bf16_f32 v106, v114, v115
	v_cvt_pk_bf16_f32 v107, v112, v113
	v_lshl_add_u64 v[116:117], v[116:117], 0, v[162:163]
	v_pk_add_f32 v[100:101], v[100:101], v[120:121]
	v_lshlrev_b32_e32 v122, 16, v145
	v_and_b32_e32 v123, 0xffff0000, v145
	global_store_dwordx4 v[116:117], v[104:107], off sc1
	v_pk_add_f32 v[102:103], v[102:103], v[122:123]
	v_lshlrev_b32_e32 v124, 16, v146
	v_mul_f32_e32 v106, v109, v109
	v_pk_add_f32 v[104:105], v[98:99], v[126:127]
	v_cvt_pk_bf16_f32 v98, v100, v101
	v_mul_f32_e32 v101, v101, v101
	v_fmac_f32_e32 v106, v108, v108
	v_fmac_f32_e32 v101, v100, v100
	v_and_b32_e32 v125, 0xffff0000, v146
	v_fmac_f32_e32 v106, v110, v110
	v_fmac_f32_e32 v101, v102, v102
	v_fmac_f32_e32 v106, v111, v111
	v_pk_add_f32 v[96:97], v[96:97], v[124:125]
	v_fmac_f32_e32 v101, v103, v103
	v_fmac_f32_e32 v106, v114, v114
	v_fmac_f32_e32 v101, v96, v96
	v_fmac_f32_e32 v106, v115, v115
	v_fmac_f32_e32 v101, v97, v97
	v_fmac_f32_e32 v106, v112, v112
	v_fmac_f32_e32 v101, v104, v104
	v_fmac_f32_e32 v106, v113, v113
	v_fmac_f32_e32 v101, v105, v105
	v_add_f32_e32 v106, v106, v101
	ds_bpermute_b32 v107, v183, v106
	v_cvt_pk_bf16_f32 v100, v96, v97
	v_lshl_add_u64 v[96:97], s[10:11], 0, v[178:179]
	v_cvt_pk_bf16_f32 v99, v102, v103
	v_lshl_add_u64 v[102:103], v[96:97], 0, v[162:163]
	s_waitcnt lgkmcnt(0)
	v_add_f32_e32 v96, v106, v107
	ds_bpermute_b32 v97, v184, v96
	v_add_co_u32_e32 v102, vcc, s59, v102
	v_cvt_pk_bf16_f32 v101, v104, v105
	s_nop 0
	v_addc_co_u32_e32 v103, vcc, 0, v103, vcc
	global_store_dwordx4 v[102:103], v[98:101], off offset:256 sc1
	s_and_saveexec_b64 s[26:27], s[2:3]
	s_cbranch_execz .LBB0_1181
	s_waitcnt lgkmcnt(0)
	v_add_f32_e32 v98, v96, v97
	v_lshl_add_u64 v[96:97], v[176:177], 2, s[14:15]
	global_atomic_add_f32 v[96:97], v98, off
.LBB0_1181:
	s_or_b64 exec, exec, s[26:27]
	v_lshlrev_b32_e32 v96, 16, v140
	s_waitcnt lgkmcnt(0)
	v_and_b32_e32 v97, 0xffff0000, v140
	v_lshlrev_b32_e32 v98, 16, v141
	v_and_b32_e32 v99, 0xffff0000, v141
	v_lshlrev_b32_e32 v100, 16, v142
	v_and_b32_e32 v101, 0xffff0000, v142
	v_lshlrev_b32_e32 v102, 16, v143
	v_and_b32_e32 v103, 0xffff0000, v143
	v_lshlrev_b32_e32 v104, 16, v136
	v_and_b32_e32 v105, 0xffff0000, v136
	v_pk_add_f32 v[94:95], v[94:95], v[98:99]
	v_pk_add_f32 v[92:93], v[92:93], v[96:97]
	v_pk_add_f32 v[96:97], v[90:91], v[102:103]
	v_pk_add_f32 v[98:99], v[88:89], v[100:101]
	v_lshl_add_u64 v[100:101], s[16:17], 0, v[174:175]
	v_lshlrev_b32_e32 v110, 16, v139
	v_and_b32_e32 v111, 0xffff0000, v139
	v_cvt_pk_bf16_f32 v88, v92, v93
	v_cvt_pk_bf16_f32 v89, v94, v95
	v_cvt_pk_bf16_f32 v90, v98, v99
	v_cvt_pk_bf16_f32 v91, v96, v97
	v_lshl_add_u64 v[100:101], v[100:101], 0, v[162:163]
	v_pk_add_f32 v[84:85], v[84:85], v[104:105]
	v_lshlrev_b32_e32 v106, 16, v137
	v_and_b32_e32 v107, 0xffff0000, v137
	global_store_dwordx4 v[100:101], v[88:91], off sc1
	v_pk_add_f32 v[86:87], v[86:87], v[106:107]
	v_lshlrev_b32_e32 v108, 16, v138
	v_mul_f32_e32 v90, v93, v93
	v_pk_add_f32 v[88:89], v[82:83], v[110:111]
	v_cvt_pk_bf16_f32 v82, v84, v85
	v_mul_f32_e32 v85, v85, v85
	v_fmac_f32_e32 v90, v92, v92
	v_fmac_f32_e32 v85, v84, v84
	v_and_b32_e32 v109, 0xffff0000, v138
	v_fmac_f32_e32 v90, v94, v94
	v_fmac_f32_e32 v85, v86, v86
	v_fmac_f32_e32 v90, v95, v95
	v_pk_add_f32 v[80:81], v[80:81], v[108:109]
	v_fmac_f32_e32 v85, v87, v87
	v_fmac_f32_e32 v90, v98, v98
	v_fmac_f32_e32 v85, v80, v80
	v_fmac_f32_e32 v90, v99, v99
	v_fmac_f32_e32 v85, v81, v81
	v_fmac_f32_e32 v90, v96, v96
	v_fmac_f32_e32 v85, v88, v88
	v_fmac_f32_e32 v90, v97, v97
	v_fmac_f32_e32 v85, v89, v89
	v_add_f32_e32 v90, v90, v85
	ds_bpermute_b32 v91, v183, v90
	v_cvt_pk_bf16_f32 v84, v80, v81
	v_lshl_add_u64 v[80:81], s[10:11], 0, v[174:175]
	v_cvt_pk_bf16_f32 v83, v86, v87
	v_lshl_add_u64 v[86:87], v[80:81], 0, v[162:163]
	s_waitcnt lgkmcnt(0)
	v_add_f32_e32 v80, v90, v91
	ds_bpermute_b32 v81, v184, v80
	v_add_co_u32_e32 v86, vcc, s59, v86
	v_cvt_pk_bf16_f32 v85, v88, v89
	s_nop 0
	v_addc_co_u32_e32 v87, vcc, 0, v87, vcc
	global_store_dwordx4 v[86:87], v[82:85], off offset:256 sc1
	s_and_saveexec_b64 s[26:27], s[2:3]
	s_cbranch_execz .LBB0_1183
	s_waitcnt lgkmcnt(0)
	v_add_f32_e32 v82, v80, v81
	v_lshl_add_u64 v[80:81], v[172:173], 2, s[14:15]
	global_atomic_add_f32 v[80:81], v82, off
; DI u32x2 pk4(f32x4 v) { u32x2 r; r.x = pk2(v[0], v[1]); r.y = pk2(v[2], v[3]); return r; }
; DI float bf_lo(unsigned w) { return __uint_as_float(w << 16); }
; DI float bf_hi(unsigned w) { return __uint_as_float(w & 0xffff0000u); }
; #define COLS4 _Pragma("unroll") for (int bj = 0; bj < 2; ++bj) _Pragma("unroll") for (int n = 0; n < 2; ++n)
;     DI void operator()(const Acc& acc, const Unit& u, int wr, int wc, int fr, int fq) const {
;     ...
;             for (int ai = 0; ai < 2; ++ai) if (ai == 0 || !hf) {
;                 f32x4 xo[4][2][2];
; #pragma unroll
;                 for (int m = 0; m < 4; ++m) { const size_t o = (size_t)(row0 + ai * HALF + m * 16) * 2048 + colp;
;                     if (PH == 4) { COLS4 xo[m][bj][n] = *(const f32x4*)(p.x + o + bj * HALF + n * 4); }
;                     else {
; #pragma unroll
;                         for (int bj = 0; bj < 2; ++bj) { const u32x4 w = *(const u32x4*)(WSB(OFF_XB) + o + bj * HALF);
;                             xo[m][bj][0] = (f32x4){bf_lo(w.x), bf_hi(w.x), bf_lo(w.y), bf_hi(w.y)}; xo[m][bj][1] = (f32x4){bf_lo(w.z), bf_hi(w.z), bf_lo(w.w), bf_hi(w.w)}; } } }
; #pragma unroll
;                 for (int m = 0; m < 4; ++m) { const int r = row0 + ai * HALF + m * 16; const size_t o = (size_t)r * 2048 + colp; float part = 0.f;
; #pragma unroll
;                     for (int bj = 0; bj < 2; ++bj) { const f32x4 x0 = xo[m][bj][0] + acc[ai][bj][m][0], x1 = xo[m][bj][1] + acc[ai][bj][m][1];
;                         const u32x2 h0 = pk4(x0), h1 = pk4(x1);
;                         *(u32x4*)(WSB(OFF_XB) + o + bj * HALF) = (u32x4){h0.x, h0.y, h1.x, h1.y};
;                         part += x0[0] * x0[0] + x0[1] * x0[1] + x0[2] * x0[2] + x0[3] * x0[3] + x1[0] * x1[0] + x1[1] * x1[1] + x1[2] * x1[2] + x1[3] * x1[3]; }
;                     part += __shfl_xor(part, 16); part += __shfl_xor(part, 32);
;                     if (fq == 0) unsafeAtomicAdd(ssq + r, part);
;                 }
.LBB0_1183:
	s_or_b64 exec, exec, s[26:27]
	v_lshlrev_b32_e32 v80, 16, v132
	s_waitcnt lgkmcnt(0)
	v_and_b32_e32 v81, 0xffff0000, v132
	v_lshlrev_b32_e32 v82, 16, v133
	v_and_b32_e32 v83, 0xffff0000, v133
	v_lshlrev_b32_e32 v84, 16, v134
	v_and_b32_e32 v85, 0xffff0000, v134
	v_lshlrev_b32_e32 v86, 16, v135
	v_and_b32_e32 v87, 0xffff0000, v135
	v_lshlrev_b32_e32 v88, 16, v128
	v_and_b32_e32 v89, 0xffff0000, v128
	v_pk_add_f32 v[78:79], v[78:79], v[82:83]
	v_pk_add_f32 v[76:77], v[76:77], v[80:81]
	v_pk_add_f32 v[80:81], v[74:75], v[86:87]
	v_pk_add_f32 v[82:83], v[72:73], v[84:85]
	v_lshl_add_u64 v[84:85], s[16:17], 0, v[170:171]
	v_lshlrev_b32_e32 v94, 16, v131
	v_and_b32_e32 v95, 0xffff0000, v131
	v_cvt_pk_bf16_f32 v72, v76, v77
	v_cvt_pk_bf16_f32 v73, v78, v79
	v_cvt_pk_bf16_f32 v74, v82, v83
	v_cvt_pk_bf16_f32 v75, v80, v81
	v_lshl_add_u64 v[84:85], v[84:85], 0, v[162:163]
	v_pk_add_f32 v[68:69], v[68:69], v[88:89]
	v_lshlrev_b32_e32 v90, 16, v129
	v_and_b32_e32 v91, 0xffff0000, v129
	global_store_dwordx4 v[84:85], v[72:75], off sc1
	v_pk_add_f32 v[70:71], v[70:71], v[90:91]
	v_lshlrev_b32_e32 v92, 16, v130
	v_mul_f32_e32 v74, v77, v77
	v_pk_add_f32 v[72:73], v[66:67], v[94:95]
	v_cvt_pk_bf16_f32 v66, v68, v69
	v_mul_f32_e32 v69, v69, v69
	v_fmac_f32_e32 v74, v76, v76
	v_fmac_f32_e32 v69, v68, v68
	v_and_b32_e32 v93, 0xffff0000, v130
	v_fmac_f32_e32 v74, v78, v78
	v_fmac_f32_e32 v69, v70, v70
	v_fmac_f32_e32 v74, v79, v79
	v_pk_add_f32 v[64:65], v[64:65], v[92:93]
	v_fmac_f32_e32 v69, v71, v71
	v_fmac_f32_e32 v74, v82, v82
	v_fmac_f32_e32 v69, v64, v64
	v_fmac_f32_e32 v74, v83, v83
	v_fmac_f32_e32 v69, v65, v65
	v_fmac_f32_e32 v74, v80, v80
	v_fmac_f32_e32 v69, v72, v72
	v_fmac_f32_e32 v74, v81, v81
	v_fmac_f32_e32 v69, v73, v73
	v_add_f32_e32 v74, v74, v69
	ds_bpermute_b32 v75, v183, v74
	v_cvt_pk_bf16_f32 v68, v64, v65
	v_lshl_add_u64 v[64:65], s[10:11], 0, v[170:171]
	v_cvt_pk_bf16_f32 v67, v70, v71
	v_lshl_add_u64 v[70:71], v[64:65], 0, v[162:163]
	s_waitcnt lgkmcnt(0)
	v_add_f32_e32 v64, v74, v75
	ds_bpermute_b32 v65, v184, v64
	v_add_co_u32_e32 v70, vcc, s59, v70
	v_cvt_pk_bf16_f32 v69, v72, v73
	s_nop 0
	v_addc_co_u32_e32 v71, vcc, 0, v71, vcc
	global_store_dwordx4 v[70:71], v[66:69], off offset:256 sc1
	s_and_saveexec_b64 s[26:27], s[2:3]
	s_cbranch_execz .LBB0_1185
	s_waitcnt lgkmcnt(0)
	v_add_f32_e32 v66, v64, v65
	v_lshl_add_u64 v[64:65], v[168:169], 2, s[14:15]
	global_atomic_add_f32 v[64:65], v66, off
.LBB0_1185:
	s_or_b64 exec, exec, s[26:27]
	v_add_u32_e32 v100, 0x80, v166
	v_ashrrev_i32_e32 v101, 31, v100
	v_lshlrev_b64 v[110:111], 12, v[100:101]
	s_waitcnt lgkmcnt(0)
	v_lshl_add_u64 v[64:65], v[164:165], 0, v[110:111]
	global_load_dwordx4 v[102:105], v[64:65], off
	global_load_dwordx4 v[106:109], v[64:65], off offset:256
	v_add_u32_e32 v96, 0x90, v166
	v_add_u32_e32 v92, 0xa0, v166
	v_add_u32_e32 v88, 0xb0, v166
	v_ashrrev_i32_e32 v97, 31, v96
	v_ashrrev_i32_e32 v93, 31, v92
	v_ashrrev_i32_e32 v89, 31, v88
	v_lshlrev_b64 v[98:99], 12, v[96:97]
	v_lshlrev_b64 v[94:95], 12, v[92:93]
	v_lshlrev_b64 v[90:91], 12, v[88:89]
	v_lshl_add_u64 v[64:65], v[164:165], 0, v[98:99]
	v_lshl_add_u64 v[66:67], v[164:165], 0, v[94:95]
	v_lshl_add_u64 v[112:113], v[164:165], 0, v[90:91]
	global_load_dwordx4 v[84:87], v[64:65], off
	global_load_dwordx4 v[80:83], v[64:65], off offset:256
	global_load_dwordx4 v[76:79], v[66:67], off
	global_load_dwordx4 v[72:75], v[66:67], off offset:256
	global_load_dwordx4 v[68:71], v[112:113], off
	s_nop 0
	global_load_dwordx4 v[64:67], v[112:113], off offset:256
	v_lshl_add_u64 v[112:113], s[16:17], 0, v[110:111]
	v_lshl_add_u64 v[112:113], v[112:113], 0, v[162:163]
	v_lshl_add_u64 v[110:111], s[10:11], 0, v[110:111]
	v_lshl_add_u64 v[110:111], v[110:111], 0, v[162:163]
	s_waitcnt vmcnt(7)
	v_lshlrev_b32_e32 v114, 16, v102
	v_and_b32_e32 v115, 0xffff0000, v102
	v_lshlrev_b32_e32 v102, 16, v103
	v_and_b32_e32 v103, 0xffff0000, v103
	s_waitcnt vmcnt(6)
	v_lshlrev_b32_e32 v118, 16, v106
	v_and_b32_e32 v119, 0xffff0000, v106
	v_lshlrev_b32_e32 v106, 16, v107
	v_and_b32_e32 v107, 0xffff0000, v107
	v_lshlrev_b32_e32 v120, 16, v108
	v_and_b32_e32 v121, 0xffff0000, v108
	v_pk_add_f32 v[62:63], v[62:63], v[102:103]
	v_pk_add_f32 v[60:61], v[60:61], v[114:115]
	v_pk_add_f32 v[102:103], v[52:53], v[118:119]
	v_pk_add_f32 v[54:55], v[54:55], v[106:107]
	v_pk_add_f32 v[106:107], v[48:49], v[120:121]
	v_cvt_pk_bf16_f32 v48, v60, v61
	v_mul_f32_e32 v53, v61, v61
	v_mul_f32_e32 v61, v103, v103
	v_fmac_f32_e32 v53, v60, v60
	v_fmac_f32_e32 v61, v102, v102
	v_lshlrev_b32_e32 v116, 16, v104
	v_and_b32_e32 v117, 0xffff0000, v104
	v_fmac_f32_e32 v53, v62, v62
	v_fmac_f32_e32 v61, v54, v54
	v_pk_add_f32 v[56:57], v[56:57], v[116:117]
	v_fmac_f32_e32 v53, v63, v63
	v_fmac_f32_e32 v61, v55, v55
	v_lshlrev_b32_e32 v104, 16, v105
	v_and_b32_e32 v105, 0xffff0000, v105
	v_lshlrev_b32_e32 v108, 16, v109
	v_and_b32_e32 v109, 0xffff0000, v109
	v_fmac_f32_e32 v53, v56, v56
	v_fmac_f32_e32 v61, v106, v106
	v_pk_add_f32 v[58:59], v[58:59], v[104:105]
	v_pk_add_f32 v[104:105], v[50:51], v[108:109]
	v_fmac_f32_e32 v53, v57, v57
	v_fmac_f32_e32 v61, v107, v107
	v_fmac_f32_e32 v53, v58, v58
	v_fmac_f32_e32 v61, v104, v104
	v_fmac_f32_e32 v53, v59, v59
	v_fmac_f32_e32 v61, v105, v105
	v_cvt_pk_bf16_f32 v50, v56, v57
	v_add_f32_e32 v56, v53, v61
	ds_bpermute_b32 v57, v183, v56
	v_cvt_pk_bf16_f32 v49, v62, v63
	v_cvt_pk_bf16_f32 v51, v58, v59
	global_store_dwordx4 v[112:113], v[48:51], off sc1
	v_cvt_pk_bf16_f32 v52, v102, v103
	v_cvt_pk_bf16_f32 v53, v54, v55
	s_waitcnt lgkmcnt(0)
	v_add_f32_e32 v48, v56, v57
	ds_bpermute_b32 v49, v184, v48
	v_add_co_u32_e32 v50, vcc, s59, v110
	v_cvt_pk_bf16_f32 v54, v106, v107
	v_cvt_pk_bf16_f32 v55, v104, v105
	v_addc_co_u32_e32 v51, vcc, 0, v111, vcc
	global_store_dwordx4 v[50:51], v[52:55], off offset:256 sc1
	s_and_saveexec_b64 s[26:27], s[2:3]
	s_cbranch_execz .LBB0_1187
	s_waitcnt lgkmcnt(0)
	v_add_f32_e32 v50, v48, v49
	v_lshl_add_u64 v[48:49], v[100:101], 2, s[14:15]
	global_atomic_add_f32 v[48:49], v50, off
; DI u32x2 pk4(f32x4 v) { u32x2 r; r.x = pk2(v[0], v[1]); r.y = pk2(v[2], v[3]); return r; }
; DI float bf_lo(unsigned w) { return __uint_as_float(w << 16); }
; DI float bf_hi(unsigned w) { return __uint_as_float(w & 0xffff0000u); }
; #define COLS4 _Pragma("unroll") for (int bj = 0; bj < 2; ++bj) _Pragma("unroll") for (int n = 0; n < 2; ++n)
;     DI void operator()(const Acc& acc, const Unit& u, int wr, int wc, int fr, int fq) const {
;     ...
;             for (int ai = 0; ai < 2; ++ai) if (ai == 0 || !hf) {
;                 f32x4 xo[4][2][2];
; #pragma unroll
;                 for (int m = 0; m < 4; ++m) { const size_t o = (size_t)(row0 + ai * HALF + m * 16) * 2048 + colp;
;                     if (PH == 4) { COLS4 xo[m][bj][n] = *(const f32x4*)(p.x + o + bj * HALF + n * 4); }
;                     else {
; #pragma unroll
;                         for (int bj = 0; bj < 2; ++bj) { const u32x4 w = *(const u32x4*)(WSB(OFF_XB) + o + bj * HALF);
;                             xo[m][bj][0] = (f32x4){bf_lo(w.x), bf_hi(w.x), bf_lo(w.y), bf_hi(w.y)}; xo[m][bj][1] = (f32x4){bf_lo(w.z), bf_hi(w.z), bf_lo(w.w), bf_hi(w.w)}; } } }
; #pragma unroll
;                 for (int m = 0; m < 4; ++m) { const int r = row0 + ai * HALF + m * 16; const size_t o = (size_t)r * 2048 + colp; float part = 0.f;
; #pragma unroll
;                     for (int bj = 0; bj < 2; ++bj) { const f32x4 x0 = xo[m][bj][0] + acc[ai][bj][m][0], x1 = xo[m][bj][1] + acc[ai][bj][m][1];
;                         const u32x2 h0 = pk4(x0), h1 = pk4(x1);
;                         *(u32x4*)(WSB(OFF_XB) + o + bj * HALF) = (u32x4){h0.x, h0.y, h1.x, h1.y};
;                         part += x0[0] * x0[0] + x0[1] * x0[1] + x0[2] * x0[2] + x0[3] * x0[3] + x1[0] * x1[0] + x1[1] * x1[1] + x1[2] * x1[2] + x1[3] * x1[3]; }
;                     part += __shfl_xor(part, 16); part += __shfl_xor(part, 32);
;                     if (fq == 0) unsafeAtomicAdd(ssq + r, part);
;                 }
.LBB0_1187:
	s_or_b64 exec, exec, s[26:27]
	s_waitcnt vmcnt(7)
	v_lshlrev_b32_e32 v48, 16, v84
	s_waitcnt lgkmcnt(0)
	v_and_b32_e32 v49, 0xffff0000, v84
	v_lshlrev_b32_e32 v50, 16, v85
	v_and_b32_e32 v51, 0xffff0000, v85
	v_lshlrev_b32_e32 v52, 16, v86
	v_and_b32_e32 v53, 0xffff0000, v86
	v_lshlrev_b32_e32 v54, 16, v87
	v_and_b32_e32 v55, 0xffff0000, v87
	s_waitcnt vmcnt(6)
	v_lshlrev_b32_e32 v56, 16, v80
	v_and_b32_e32 v57, 0xffff0000, v80
	v_pk_add_f32 v[46:47], v[46:47], v[50:51]
	v_pk_add_f32 v[44:45], v[44:45], v[48:49]
	v_pk_add_f32 v[48:49], v[42:43], v[54:55]
	v_pk_add_f32 v[50:51], v[40:41], v[52:53]
	v_lshl_add_u64 v[52:53], s[16:17], 0, v[98:99]
	v_lshlrev_b32_e32 v62, 16, v83
	v_and_b32_e32 v63, 0xffff0000, v83
	v_cvt_pk_bf16_f32 v40, v44, v45
	v_cvt_pk_bf16_f32 v41, v46, v47
	v_cvt_pk_bf16_f32 v42, v50, v51
	v_cvt_pk_bf16_f32 v43, v48, v49
	v_lshl_add_u64 v[52:53], v[52:53], 0, v[162:163]
	v_pk_add_f32 v[36:37], v[36:37], v[56:57]
	v_lshlrev_b32_e32 v58, 16, v81
	v_and_b32_e32 v59, 0xffff0000, v81
	global_store_dwordx4 v[52:53], v[40:43], off sc1
	v_pk_add_f32 v[38:39], v[38:39], v[58:59]
	v_lshlrev_b32_e32 v60, 16, v82
	v_mul_f32_e32 v42, v45, v45
	v_pk_add_f32 v[40:41], v[34:35], v[62:63]
	v_cvt_pk_bf16_f32 v34, v36, v37
	v_mul_f32_e32 v37, v37, v37
	v_fmac_f32_e32 v42, v44, v44
	v_fmac_f32_e32 v37, v36, v36
	v_and_b32_e32 v61, 0xffff0000, v82
	v_fmac_f32_e32 v42, v46, v46
	v_fmac_f32_e32 v37, v38, v38
	v_fmac_f32_e32 v42, v47, v47
	v_pk_add_f32 v[32:33], v[32:33], v[60:61]
	v_fmac_f32_e32 v37, v39, v39
	v_fmac_f32_e32 v42, v50, v50
	v_fmac_f32_e32 v37, v32, v32
	v_fmac_f32_e32 v42, v51, v51
	v_fmac_f32_e32 v37, v33, v33
	v_fmac_f32_e32 v42, v48, v48
	v_fmac_f32_e32 v37, v40, v40
	v_fmac_f32_e32 v42, v49, v49
	v_fmac_f32_e32 v37, v41, v41
	v_add_f32_e32 v42, v42, v37
	ds_bpermute_b32 v43, v183, v42
	v_cvt_pk_bf16_f32 v36, v32, v33
	v_lshl_add_u64 v[32:33], s[10:11], 0, v[98:99]
	v_cvt_pk_bf16_f32 v35, v38, v39
	v_lshl_add_u64 v[38:39], v[32:33], 0, v[162:163]
	s_waitcnt lgkmcnt(0)
	v_add_f32_e32 v32, v42, v43
	ds_bpermute_b32 v33, v184, v32
	v_add_co_u32_e32 v38, vcc, s59, v38
	v_cvt_pk_bf16_f32 v37, v40, v41
	s_nop 0
	v_addc_co_u32_e32 v39, vcc, 0, v39, vcc
	global_store_dwordx4 v[38:39], v[34:37], off offset:256 sc1
	s_and_saveexec_b64 s[26:27], s[2:3]
	s_cbranch_execz .LBB0_1189
	s_waitcnt lgkmcnt(0)
	v_add_f32_e32 v34, v32, v33
	v_lshl_add_u64 v[32:33], v[96:97], 2, s[14:15]
	global_atomic_add_f32 v[32:33], v34, off
; DI u32x2 pk4(f32x4 v) { u32x2 r; r.x = pk2(v[0], v[1]); r.y = pk2(v[2], v[3]); return r; }
; DI float bf_lo(unsigned w) { return __uint_as_float(w << 16); }
; DI float bf_hi(unsigned w) { return __uint_as_float(w & 0xffff0000u); }
; #define COLS4 _Pragma("unroll") for (int bj = 0; bj < 2; ++bj) _Pragma("unroll") for (int n = 0; n < 2; ++n)
;     DI void operator()(const Acc& acc, const Unit& u, int wr, int wc, int fr, int fq) const {
;     ...
;             for (int ai = 0; ai < 2; ++ai) if (ai == 0 || !hf) {
;                 f32x4 xo[4][2][2];
; #pragma unroll
;                 for (int m = 0; m < 4; ++m) { const size_t o = (size_t)(row0 + ai * HALF + m * 16) * 2048 + colp;
;                     if (PH == 4) { COLS4 xo[m][bj][n] = *(const f32x4*)(p.x + o + bj * HALF + n * 4); }
;                     else {
; #pragma unroll
;                         for (int bj = 0; bj < 2; ++bj) { const u32x4 w = *(const u32x4*)(WSB(OFF_XB) + o + bj * HALF);
;                             xo[m][bj][0] = (f32x4){bf_lo(w.x), bf_hi(w.x), bf_lo(w.y), bf_hi(w.y)}; xo[m][bj][1] = (f32x4){bf_lo(w.z), bf_hi(w.z), bf_lo(w.w), bf_hi(w.w)}; } } }
; #pragma unroll
;                 for (int m = 0; m < 4; ++m) { const int r = row0 + ai * HALF + m * 16; const size_t o = (size_t)r * 2048 + colp; float part = 0.f;
; #pragma unroll
;                     for (int bj = 0; bj < 2; ++bj) { const f32x4 x0 = xo[m][bj][0] + acc[ai][bj][m][0], x1 = xo[m][bj][1] + acc[ai][bj][m][1];
;                         const u32x2 h0 = pk4(x0), h1 = pk4(x1);
;                         *(u32x4*)(WSB(OFF_XB) + o + bj * HALF) = (u32x4){h0.x, h0.y, h1.x, h1.y};
;                         part += x0[0] * x0[0] + x0[1] * x0[1] + x0[2] * x0[2] + x0[3] * x0[3] + x1[0] * x1[0] + x1[1] * x1[1] + x1[2] * x1[2] + x1[3] * x1[3]; }
;                     part += __shfl_xor(part, 16); part += __shfl_xor(part, 32);
;                     if (fq == 0) unsafeAtomicAdd(ssq + r, part);
;                 }
.LBB0_1189:
	s_or_b64 exec, exec, s[26:27]
	s_waitcnt vmcnt(7)
	v_lshlrev_b32_e32 v32, 16, v76
	s_waitcnt lgkmcnt(0)
	v_and_b32_e32 v33, 0xffff0000, v76
	v_lshlrev_b32_e32 v34, 16, v77
	v_and_b32_e32 v35, 0xffff0000, v77
	v_lshlrev_b32_e32 v36, 16, v78
	v_and_b32_e32 v37, 0xffff0000, v78
	v_lshlrev_b32_e32 v38, 16, v79
	v_and_b32_e32 v39, 0xffff0000, v79
	s_waitcnt vmcnt(6)
	v_lshlrev_b32_e32 v40, 16, v72
	v_and_b32_e32 v41, 0xffff0000, v72
	v_pk_add_f32 v[30:31], v[30:31], v[34:35]
	v_pk_add_f32 v[28:29], v[28:29], v[32:33]
	v_pk_add_f32 v[32:33], v[26:27], v[38:39]
	v_pk_add_f32 v[34:35], v[24:25], v[36:37]
	v_lshl_add_u64 v[36:37], s[16:17], 0, v[94:95]
	v_lshlrev_b32_e32 v46, 16, v75
	v_and_b32_e32 v47, 0xffff0000, v75
	v_cvt_pk_bf16_f32 v24, v28, v29
	v_cvt_pk_bf16_f32 v25, v30, v31
	v_cvt_pk_bf16_f32 v26, v34, v35
	v_cvt_pk_bf16_f32 v27, v32, v33
	v_lshl_add_u64 v[36:37], v[36:37], 0, v[162:163]
	v_pk_add_f32 v[20:21], v[20:21], v[40:41]
	v_lshlrev_b32_e32 v42, 16, v73
	v_and_b32_e32 v43, 0xffff0000, v73
	global_store_dwordx4 v[36:37], v[24:27], off sc1
	v_pk_add_f32 v[22:23], v[22:23], v[42:43]
	v_lshlrev_b32_e32 v44, 16, v74
	v_mul_f32_e32 v26, v29, v29
	v_pk_add_f32 v[24:25], v[18:19], v[46:47]
	v_cvt_pk_bf16_f32 v18, v20, v21
	v_mul_f32_e32 v21, v21, v21
	v_fmac_f32_e32 v26, v28, v28
	v_fmac_f32_e32 v21, v20, v20
	v_and_b32_e32 v45, 0xffff0000, v74
	v_fmac_f32_e32 v26, v30, v30
	v_fmac_f32_e32 v21, v22, v22
	v_fmac_f32_e32 v26, v31, v31
	v_pk_add_f32 v[16:17], v[16:17], v[44:45]
	v_fmac_f32_e32 v21, v23, v23
	v_fmac_f32_e32 v26, v34, v34
	v_fmac_f32_e32 v21, v16, v16
	v_fmac_f32_e32 v26, v35, v35
	v_fmac_f32_e32 v21, v17, v17
	v_fmac_f32_e32 v26, v32, v32
	v_fmac_f32_e32 v21, v24, v24
	v_fmac_f32_e32 v26, v33, v33
	v_fmac_f32_e32 v21, v25, v25
	v_add_f32_e32 v26, v26, v21
	ds_bpermute_b32 v27, v183, v26
	v_cvt_pk_bf16_f32 v20, v16, v17
	v_lshl_add_u64 v[16:17], s[10:11], 0, v[94:95]
	v_cvt_pk_bf16_f32 v19, v22, v23
	v_lshl_add_u64 v[22:23], v[16:17], 0, v[162:163]
	s_waitcnt lgkmcnt(0)
	v_add_f32_e32 v16, v26, v27
	ds_bpermute_b32 v17, v184, v16
	v_add_co_u32_e32 v22, vcc, s59, v22
	v_cvt_pk_bf16_f32 v21, v24, v25
	s_nop 0
	v_addc_co_u32_e32 v23, vcc, 0, v23, vcc
	global_store_dwordx4 v[22:23], v[18:21], off offset:256 sc1
	s_and_saveexec_b64 s[26:27], s[2:3]
	s_cbranch_execz .LBB0_1191
	s_waitcnt lgkmcnt(0)
	v_add_f32_e32 v18, v16, v17
	v_lshl_add_u64 v[16:17], v[92:93], 2, s[14:15]
	global_atomic_add_f32 v[16:17], v18, off
.LBB0_1191:
	s_or_b64 exec, exec, s[26:27]
	s_waitcnt vmcnt(7)
	v_lshlrev_b32_e32 v16, 16, v68
	s_waitcnt lgkmcnt(0)
	v_and_b32_e32 v17, 0xffff0000, v68
	v_lshlrev_b32_e32 v18, 16, v69
	v_and_b32_e32 v19, 0xffff0000, v69
	v_lshlrev_b32_e32 v20, 16, v70
	v_and_b32_e32 v21, 0xffff0000, v70
	v_lshlrev_b32_e32 v22, 16, v71
	v_and_b32_e32 v23, 0xffff0000, v71
	s_waitcnt vmcnt(6)
	v_lshlrev_b32_e32 v24, 16, v64
	v_and_b32_e32 v25, 0xffff0000, v64
	v_pk_add_f32 v[14:15], v[14:15], v[18:19]
	v_pk_add_f32 v[12:13], v[12:13], v[16:17]
	v_pk_add_f32 v[16:17], v[10:11], v[22:23]
	v_pk_add_f32 v[18:19], v[8:9], v[20:21]
	v_lshl_add_u64 v[20:21], s[16:17], 0, v[90:91]
	v_lshlrev_b32_e32 v30, 16, v67
	v_and_b32_e32 v31, 0xffff0000, v67
	v_cvt_pk_bf16_f32 v8, v12, v13
	v_cvt_pk_bf16_f32 v9, v14, v15
	v_cvt_pk_bf16_f32 v10, v18, v19
	v_cvt_pk_bf16_f32 v11, v16, v17
	v_lshl_add_u64 v[20:21], v[20:21], 0, v[162:163]
	v_pk_add_f32 v[4:5], v[4:5], v[24:25]
	v_lshlrev_b32_e32 v26, 16, v65
	v_and_b32_e32 v27, 0xffff0000, v65
	global_store_dwordx4 v[20:21], v[8:11], off sc1
	v_pk_add_f32 v[6:7], v[6:7], v[26:27]
	v_lshlrev_b32_e32 v28, 16, v66
	v_mul_f32_e32 v10, v13, v13
	v_pk_add_f32 v[8:9], v[2:3], v[30:31]
	v_cvt_pk_bf16_f32 v2, v4, v5
	v_mul_f32_e32 v5, v5, v5
	v_fmac_f32_e32 v10, v12, v12
	v_fmac_f32_e32 v5, v4, v4
	v_and_b32_e32 v29, 0xffff0000, v66
	v_fmac_f32_e32 v10, v14, v14
	v_fmac_f32_e32 v5, v6, v6
	v_fmac_f32_e32 v10, v15, v15
	v_pk_add_f32 v[0:1], v[0:1], v[28:29]
	v_fmac_f32_e32 v5, v7, v7
	v_fmac_f32_e32 v10, v18, v18
	v_fmac_f32_e32 v5, v0, v0
	v_fmac_f32_e32 v10, v19, v19
	v_fmac_f32_e32 v5, v1, v1
	v_fmac_f32_e32 v10, v16, v16
	v_fmac_f32_e32 v5, v8, v8
	v_fmac_f32_e32 v10, v17, v17
	v_fmac_f32_e32 v5, v9, v9
	v_add_f32_e32 v10, v10, v5
	ds_bpermute_b32 v11, v183, v10
	v_cvt_pk_bf16_f32 v4, v0, v1
	v_lshl_add_u64 v[0:1], s[10:11], 0, v[90:91]
	v_cvt_pk_bf16_f32 v3, v6, v7
	v_lshl_add_u64 v[6:7], v[0:1], 0, v[162:163]
	s_waitcnt lgkmcnt(0)
	v_add_f32_e32 v0, v10, v11
	ds_bpermute_b32 v1, v184, v0
	v_add_co_u32_e32 v6, vcc, s59, v6
	v_cvt_pk_bf16_f32 v5, v8, v9
	s_nop 0
	v_addc_co_u32_e32 v7, vcc, 0, v7, vcc
	global_store_dwordx4 v[6:7], v[2:5], off offset:256 sc1
	s_and_saveexec_b64 s[26:27], s[2:3]
	s_cbranch_execz .LBB0_1168
	s_waitcnt lgkmcnt(0)
	v_add_f32_e32 v2, v0, v1
	v_lshl_add_u64 v[0:1], v[88:89], 2, s[14:15]
	global_atomic_add_f32 v[0:1], v2, off
	s_branch .LBB0_1168
